# speedup vs baseline: 1.0291x; 1.0046x over previous
; #define STAGE(P, BASE, br, kt) do { const char* _g = (const char*)((BASE) + (size_t)(br) * K + (size_t)(kt) * G_BK); \
;     _Pragma("unroll") for (int _i = 0; _i < 2; ++_i) { \
;       __builtin_amdgcn_global_load_lds((const unsigned*)(_g + (size_t)_i * 128 * K + sg_off), (unsigned*)((char*)(P) + wid * 1024 + _i * 8192), 16, 0, 0); } } while (0)
; #define LDA(dst, b, h) _Pragma("unroll") for (int m = 0; m < 4; ++m) _Pragma("unroll") for (int k = 0; k < 2; ++k) \
;     dst[m][k] = *reinterpret_cast<const bf16x8*>((const char*)shm + aoff + (((b) * 2 + (h)) * 16384 + m * 2048 + k * 1024))
; #define LDB(dst, b, h) _Pragma("unroll") for (int n = 0; n < 2; ++n) _Pragma("unroll") for (int k = 0; k < 2; ++k) \
;     dst[n][k] = *reinterpret_cast<const bf16x8*>((const char*)shm + boff + (((b) * 2 + (h)) * 16384 + n * 2048 + k * 1024))
; #define MMA(ai, bj, At, Bt_) do { __builtin_amdgcn_s_setprio(1); \
;     _Pragma("unroll") for (int m = 0; m < 4; ++m) _Pragma("unroll") for (int n = 0; n < 2; ++n) _Pragma("unroll") for (int k = 0; k < 2; ++k) \
;       acc[ai][bj][m][n] = mfma16(At[m][k], Bt_[n][k], acc[ai][bj][m][n]); \
;     __builtin_amdgcn_s_setprio(0); } while (0)
; #define WAIT_V(n) asm volatile("s_waitcnt vmcnt(" #n ")" ::: "memory")
; #define WAIT_L(n) asm volatile("s_waitcnt lgkmcnt(" #n ")" ::: "memory")
; #define BAR __builtin_amdgcn_s_barrier()
; #define SCHED __builtin_amdgcn_sched_barrier(0)
; template <class Epi>
; __device__ __forceinline__ void gemm_phase(const bfr* __restrict__ A, int lda, const bfr* __restrict__ Bt, int K,
;                                            int nM, int nN, const Epi& epi, bfr* shm, int wv, int nMfull, int ksplit) {
;     ...
;       LDB(B0, 0, 0); SCHED; LDA(At, 0, 0); STAGE(SA(1, 1), Ak, brow + G_HALF, t + 1);
;       WAIT_L(8); BAR; WAIT_L(0); MMA(0, 0, At, B0); BAR; SCHED;
;       LDB(B1, 0, 1); STAGE(SB(0, 0), Bk, bcol, t + 2);
;       BAR; WAIT_L(0); MMA(0, 1, At, B1); BAR;
;       LDA(At, 0, 1); STAGE(SA(0, 0), Ak, brow, t + 2);
;       BAR; WAIT_L(0); MMA(1, 0, At, B0); BAR; SCHED;
;       STAGE(SB(0, 1), Bk, bcol + G_HALF, t + 2);
;       WAIT_V(6); BAR; MMA(1, 1, At, B1); BAR;
.LBB0_195:
	ds_read_b128 v[142:145], v139
	ds_read_b128 v[146:149], v139 offset:1024
	ds_read_b128 v[150:153], v139 offset:2048
	ds_read_b128 v[154:157], v139 offset:3072
	ds_read_b128 v[158:161], v138
	ds_read_b128 v[162:165], v138 offset:1024
	ds_read_b128 v[166:169], v138 offset:2048
	ds_read_b128 v[170:173], v138 offset:3072
	ds_read_b128 v[174:177], v138 offset:4096
	ds_read_b128 v[178:181], v138 offset:5120
	ds_read_b128 v[182:185], v138 offset:6144
	ds_read_b128 v[186:189], v138 offset:7168
	ds_read_b128 v[190:193], v139 offset:16384
	ds_read_b128 v[194:197], v139 offset:17408
	ds_read_b128 v[198:201], v139 offset:18432
	ds_read_b128 v[202:205], v139 offset:19456
	v_lshl_add_u64 v[136:137], s[38:39], 0, v[134:135]
	v_lshl_add_u64 v[206:207], s[36:37], 0, v[134:135]
	s_mov_b32 m0, s54
	s_mov_b64 s[46:47], 0x40080
	v_lshl_add_u64 v[210:211], v[136:137], 0, s[46:47]
	global_load_lds_dwordx4 v[210:211], off
	s_mov_b32 m0, s55
	s_mov_b64 s[46:47], 0x60080
	v_lshl_add_u64 v[212:213], v[136:137], 0, s[46:47]
	global_load_lds_dwordx4 v[212:213], off
	s_waitcnt lgkmcnt(0)
	s_barrier
	s_setprio 1
	v_mfma_f32_16x16x32_bf16 v[124:127], v[158:161], v[142:145], v[124:127]
	v_mfma_f32_16x16x32_bf16 v[120:123], v[158:161], v[150:153], v[120:123]
	v_mfma_f32_16x16x32_bf16 v[116:119], v[166:169], v[142:145], v[116:119]
	v_mfma_f32_16x16x32_bf16 v[112:115], v[166:169], v[150:153], v[112:115]
	v_mfma_f32_16x16x32_bf16 v[108:111], v[174:177], v[142:145], v[108:111]
	v_mfma_f32_16x16x32_bf16 v[104:107], v[174:177], v[150:153], v[104:107]
	v_mfma_f32_16x16x32_bf16 v[100:103], v[182:185], v[142:145], v[100:103]
	v_mfma_f32_16x16x32_bf16 v[96:99], v[182:185], v[150:153], v[96:99]
	v_mfma_f32_16x16x32_bf16 v[124:127], v[162:165], v[146:149], v[124:127]
	v_mfma_f32_16x16x32_bf16 v[120:123], v[162:165], v[154:157], v[120:123]
	v_mfma_f32_16x16x32_bf16 v[116:119], v[170:173], v[146:149], v[116:119]
	v_mfma_f32_16x16x32_bf16 v[112:115], v[170:173], v[154:157], v[112:115]
	v_mfma_f32_16x16x32_bf16 v[108:111], v[178:181], v[146:149], v[108:111]
	v_mfma_f32_16x16x32_bf16 v[104:107], v[178:181], v[154:157], v[104:107]
	v_mfma_f32_16x16x32_bf16 v[100:103], v[186:189], v[146:149], v[100:103]
	v_mfma_f32_16x16x32_bf16 v[96:99], v[186:189], v[154:157], v[96:99]
	v_mfma_f32_16x16x32_bf16 v[92:95], v[158:161], v[190:193], v[92:95]
	v_mfma_f32_16x16x32_bf16 v[88:91], v[158:161], v[198:201], v[88:91]
	v_mfma_f32_16x16x32_bf16 v[84:87], v[166:169], v[190:193], v[84:87]
	v_mfma_f32_16x16x32_bf16 v[80:83], v[166:169], v[198:201], v[80:83]
	v_mfma_f32_16x16x32_bf16 v[76:79], v[174:177], v[190:193], v[76:79]
	v_mfma_f32_16x16x32_bf16 v[72:75], v[174:177], v[198:201], v[72:75]
	v_mfma_f32_16x16x32_bf16 v[68:71], v[182:185], v[190:193], v[68:71]
	v_mfma_f32_16x16x32_bf16 v[64:67], v[182:185], v[198:201], v[64:67]
	v_mfma_f32_16x16x32_bf16 v[92:95], v[162:165], v[194:197], v[92:95]
	v_mfma_f32_16x16x32_bf16 v[88:91], v[162:165], v[202:205], v[88:91]
	v_mfma_f32_16x16x32_bf16 v[84:87], v[170:173], v[194:197], v[84:87]
	v_mfma_f32_16x16x32_bf16 v[80:83], v[170:173], v[202:205], v[80:83]
	v_mfma_f32_16x16x32_bf16 v[76:79], v[178:181], v[194:197], v[76:79]
	v_mfma_f32_16x16x32_bf16 v[72:75], v[178:181], v[202:205], v[72:75]
	v_mfma_f32_16x16x32_bf16 v[68:71], v[186:189], v[194:197], v[68:71]
	v_mfma_f32_16x16x32_bf16 v[64:67], v[186:189], v[202:205], v[64:67]
	s_setprio 0
	s_barrier
	ds_read_b128 v[158:161], v138 offset:16384
	ds_read_b128 v[162:165], v138 offset:17408
	ds_read_b128 v[166:169], v138 offset:18432
	ds_read_b128 v[170:173], v138 offset:19456
	ds_read_b128 v[174:177], v138 offset:20480
	ds_read_b128 v[178:181], v138 offset:21504
	ds_read_b128 v[182:185], v138 offset:22528
	ds_read_b128 v[186:189], v138 offset:23552
	s_mov_b32 m0, s24
	v_lshl_add_u64 v[214:215], v[206:207], 0, s[10:11]
	global_load_lds_dwordx4 v[214:215], off
	s_mov_b32 m0, s25
	v_lshl_add_u64 v[210:211], v[206:207], 0, s[12:13]
	global_load_lds_dwordx4 v[210:211], off
	s_mov_b32 m0, s23
	v_lshl_add_u64 v[212:213], v[136:137], 0, s[10:11]
	global_load_lds_dwordx4 v[212:213], off
	s_mov_b32 m0, s26
	v_lshl_add_u64 v[214:215], v[136:137], 0, s[12:13]
	global_load_lds_dwordx4 v[214:215], off
	s_mov_b32 m0, s27
	v_lshl_add_u64 v[210:211], v[206:207], 0, s[14:15]
	global_load_lds_dwordx4 v[210:211], off
	s_mov_b32 m0, s28
	v_lshl_add_u64 v[212:213], v[206:207], 0, s[16:17]
	global_load_lds_dwordx4 v[212:213], off
	s_waitcnt vmcnt(6)
	s_waitcnt lgkmcnt(0)
	s_barrier
	s_setprio 1
	v_mfma_f32_16x16x32_bf16 v[60:63], v[158:161], v[142:145], v[60:63]
	v_mfma_f32_16x16x32_bf16 v[56:59], v[158:161], v[150:153], v[56:59]
	v_mfma_f32_16x16x32_bf16 v[52:55], v[166:169], v[142:145], v[52:55]
	v_mfma_f32_16x16x32_bf16 v[48:51], v[166:169], v[150:153], v[48:51]
	v_mfma_f32_16x16x32_bf16 v[44:47], v[174:177], v[142:145], v[44:47]
	v_mfma_f32_16x16x32_bf16 v[40:43], v[174:177], v[150:153], v[40:43]
	v_mfma_f32_16x16x32_bf16 v[36:39], v[182:185], v[142:145], v[36:39]
	v_mfma_f32_16x16x32_bf16 v[32:35], v[182:185], v[150:153], v[32:35]
	v_mfma_f32_16x16x32_bf16 v[60:63], v[162:165], v[146:149], v[60:63]
	v_mfma_f32_16x16x32_bf16 v[56:59], v[162:165], v[154:157], v[56:59]
	v_mfma_f32_16x16x32_bf16 v[52:55], v[170:173], v[146:149], v[52:55]
	v_mfma_f32_16x16x32_bf16 v[48:51], v[170:173], v[154:157], v[48:51]
	v_mfma_f32_16x16x32_bf16 v[44:47], v[178:181], v[146:149], v[44:47]
	v_mfma_f32_16x16x32_bf16 v[40:43], v[178:181], v[154:157], v[40:43]
	v_mfma_f32_16x16x32_bf16 v[36:39], v[186:189], v[146:149], v[36:39]
	v_mfma_f32_16x16x32_bf16 v[32:35], v[186:189], v[154:157], v[32:35]
	v_mfma_f32_16x16x32_bf16 v[28:31], v[158:161], v[190:193], v[28:31]
	v_mfma_f32_16x16x32_bf16 v[24:27], v[158:161], v[198:201], v[24:27]
	v_mfma_f32_16x16x32_bf16 v[20:23], v[166:169], v[190:193], v[20:23]
	v_mfma_f32_16x16x32_bf16 v[16:19], v[166:169], v[198:201], v[16:19]
	v_mfma_f32_16x16x32_bf16 v[12:15], v[174:177], v[190:193], v[12:15]
	v_mfma_f32_16x16x32_bf16 v[8:11], v[174:177], v[198:201], v[8:11]
	v_mfma_f32_16x16x32_bf16 v[4:7], v[182:185], v[190:193], v[4:7]
	v_mfma_f32_16x16x32_bf16 v[0:3], v[182:185], v[198:201], v[0:3]
	v_mfma_f32_16x16x32_bf16 v[28:31], v[162:165], v[194:197], v[28:31]
	v_mfma_f32_16x16x32_bf16 v[24:27], v[162:165], v[202:205], v[24:27]
	v_mfma_f32_16x16x32_bf16 v[20:23], v[170:173], v[194:197], v[20:23]
	v_mfma_f32_16x16x32_bf16 v[16:19], v[170:173], v[202:205], v[16:19]
	v_mfma_f32_16x16x32_bf16 v[12:15], v[178:181], v[194:197], v[12:15]
	v_mfma_f32_16x16x32_bf16 v[8:11], v[178:181], v[202:205], v[8:11]
	v_mfma_f32_16x16x32_bf16 v[4:7], v[186:189], v[194:197], v[4:7]
	v_mfma_f32_16x16x32_bf16 v[0:3], v[186:189], v[202:205], v[0:3]
	s_setprio 0
	s_barrier
; #define STAGE(P, BASE, br, kt) do { const char* _g = (const char*)((BASE) + (size_t)(br) * K + (size_t)(kt) * G_BK); \
;     _Pragma("unroll") for (int _i = 0; _i < 2; ++_i) { \
;       __builtin_amdgcn_global_load_lds((const unsigned*)(_g + (size_t)_i * 128 * K + sg_off), (unsigned*)((char*)(P) + wid * 1024 + _i * 8192), 16, 0, 0); } } while (0)
; #define LDA(dst, b, h) _Pragma("unroll") for (int m = 0; m < 4; ++m) _Pragma("unroll") for (int k = 0; k < 2; ++k) \
;     dst[m][k] = *reinterpret_cast<const bf16x8*>((const char*)shm + aoff + (((b) * 2 + (h)) * 16384 + m * 2048 + k * 1024))
; #define LDB(dst, b, h) _Pragma("unroll") for (int n = 0; n < 2; ++n) _Pragma("unroll") for (int k = 0; k < 2; ++k) \
;     dst[n][k] = *reinterpret_cast<const bf16x8*>((const char*)shm + boff + (((b) * 2 + (h)) * 16384 + n * 2048 + k * 1024))
; #define MMA(ai, bj, At, Bt_) do { __builtin_amdgcn_s_setprio(1); \
;     _Pragma("unroll") for (int m = 0; m < 4; ++m) _Pragma("unroll") for (int n = 0; n < 2; ++n) _Pragma("unroll") for (int k = 0; k < 2; ++k) \
;       acc[ai][bj][m][n] = mfma16(At[m][k], Bt_[n][k], acc[ai][bj][m][n]); \
;     __builtin_amdgcn_s_setprio(0); } while (0)
; #define WAIT_V(n) asm volatile("s_waitcnt vmcnt(" #n ")" ::: "memory")
; #define WAIT_L(n) asm volatile("s_waitcnt lgkmcnt(" #n ")" ::: "memory")
; #define BAR __builtin_amdgcn_s_barrier()
; #define SCHED __builtin_amdgcn_sched_barrier(0)
; template <class Epi>
; __device__ __forceinline__ void gemm_phase(const bfr* __restrict__ A, int lda, const bfr* __restrict__ Bt, int K,
;                                            int nM, int nN, const Epi& epi, bfr* shm, int wv, int nMfull, int ksplit) {
;     ...
;       LDB(B0, 1, 0); SCHED; LDA(At, 1, 0); STAGE(SA(0, 1), Ak, brow + G_HALF, t + 2);
;       WAIT_L(8); BAR; WAIT_L(0); MMA(0, 0, At, B0); BAR; SCHED;
;       LDB(B1, 1, 1); STAGE(SB(1, 0), Bk, bcol, t + 3);
;       BAR; WAIT_L(0); MMA(0, 1, At, B1); BAR;
;       LDA(At, 1, 1); STAGE(SA(1, 0), Ak, brow, t + 3);
;       BAR; WAIT_L(0); MMA(1, 0, At, B0); BAR; SCHED;
;       STAGE(SB(1, 1), Bk, bcol + G_HALF, t + 3);
;       WAIT_V(6); BAR; MMA(1, 1, At, B1); BAR;
;     }
	ds_read_b128 v[142:145], v139 offset:32768
	ds_read_b128 v[146:149], v139 offset:33792
	ds_read_b128 v[150:153], v139 offset:34816
	ds_read_b128 v[154:157], v139 offset:35840
	ds_read_b128 v[158:161], v138 offset:32768
	ds_read_b128 v[162:165], v138 offset:33792
	ds_read_b128 v[166:169], v138 offset:34816
	ds_read_b128 v[170:173], v138 offset:35840
	ds_read_b128 v[174:177], v138 offset:36864
	ds_read_b128 v[178:181], v138 offset:37888
	ds_read_b128 v[182:185], v138 offset:38912
	ds_read_b128 v[186:189], v138 offset:39936
	ds_read_b128 v[190:193], v139 offset:49152
	ds_read_b128 v[194:197], v139 offset:50176
	ds_read_b128 v[198:201], v139 offset:51200
	ds_read_b128 v[202:205], v139 offset:52224
	s_mov_b32 m0, s29
	v_lshl_add_u64 v[214:215], v[136:137], 0, s[14:15]
	global_load_lds_dwordx4 v[214:215], off
	s_mov_b32 m0, s33
	v_lshl_add_u64 v[210:211], v[136:137], 0, s[16:17]
	global_load_lds_dwordx4 v[210:211], off
	s_waitcnt lgkmcnt(0)
	s_barrier
	s_setprio 1
	v_mfma_f32_16x16x32_bf16 v[124:127], v[158:161], v[142:145], v[124:127]
	v_mfma_f32_16x16x32_bf16 v[120:123], v[158:161], v[150:153], v[120:123]
	v_mfma_f32_16x16x32_bf16 v[116:119], v[166:169], v[142:145], v[116:119]
	v_mfma_f32_16x16x32_bf16 v[112:115], v[166:169], v[150:153], v[112:115]
	v_mfma_f32_16x16x32_bf16 v[108:111], v[174:177], v[142:145], v[108:111]
	v_mfma_f32_16x16x32_bf16 v[104:107], v[174:177], v[150:153], v[104:107]
	v_mfma_f32_16x16x32_bf16 v[100:103], v[182:185], v[142:145], v[100:103]
	v_mfma_f32_16x16x32_bf16 v[96:99], v[182:185], v[150:153], v[96:99]
	v_mfma_f32_16x16x32_bf16 v[124:127], v[162:165], v[146:149], v[124:127]
	v_mfma_f32_16x16x32_bf16 v[120:123], v[162:165], v[154:157], v[120:123]
	v_mfma_f32_16x16x32_bf16 v[116:119], v[170:173], v[146:149], v[116:119]
	v_mfma_f32_16x16x32_bf16 v[112:115], v[170:173], v[154:157], v[112:115]
	v_mfma_f32_16x16x32_bf16 v[108:111], v[178:181], v[146:149], v[108:111]
	v_mfma_f32_16x16x32_bf16 v[104:107], v[178:181], v[154:157], v[104:107]
	v_mfma_f32_16x16x32_bf16 v[100:103], v[186:189], v[146:149], v[100:103]
	v_mfma_f32_16x16x32_bf16 v[96:99], v[186:189], v[154:157], v[96:99]
	v_mfma_f32_16x16x32_bf16 v[92:95], v[158:161], v[190:193], v[92:95]
	v_mfma_f32_16x16x32_bf16 v[88:91], v[158:161], v[198:201], v[88:91]
	v_mfma_f32_16x16x32_bf16 v[84:87], v[166:169], v[190:193], v[84:87]
	v_mfma_f32_16x16x32_bf16 v[80:83], v[166:169], v[198:201], v[80:83]
	v_mfma_f32_16x16x32_bf16 v[76:79], v[174:177], v[190:193], v[76:79]
	v_mfma_f32_16x16x32_bf16 v[72:75], v[174:177], v[198:201], v[72:75]
	v_mfma_f32_16x16x32_bf16 v[68:71], v[182:185], v[190:193], v[68:71]
	v_mfma_f32_16x16x32_bf16 v[64:67], v[182:185], v[198:201], v[64:67]
	v_mfma_f32_16x16x32_bf16 v[92:95], v[162:165], v[194:197], v[92:95]
	v_mfma_f32_16x16x32_bf16 v[88:91], v[162:165], v[202:205], v[88:91]
	v_mfma_f32_16x16x32_bf16 v[84:87], v[170:173], v[194:197], v[84:87]
	v_mfma_f32_16x16x32_bf16 v[80:83], v[170:173], v[202:205], v[80:83]
	v_mfma_f32_16x16x32_bf16 v[76:79], v[178:181], v[194:197], v[76:79]
	v_mfma_f32_16x16x32_bf16 v[72:75], v[178:181], v[202:205], v[72:75]
	v_mfma_f32_16x16x32_bf16 v[68:71], v[186:189], v[194:197], v[68:71]
	v_mfma_f32_16x16x32_bf16 v[64:67], v[186:189], v[202:205], v[64:67]
	s_setprio 0
	s_barrier
	ds_read_b128 v[158:161], v138 offset:49152
	ds_read_b128 v[162:165], v138 offset:50176
	ds_read_b128 v[166:169], v138 offset:51200
	ds_read_b128 v[170:173], v138 offset:52224
	ds_read_b128 v[174:177], v138 offset:53248
	ds_read_b128 v[178:181], v138 offset:54272
	ds_read_b128 v[182:185], v138 offset:55296
	ds_read_b128 v[186:189], v138 offset:56320
	s_mov_b32 m0, s48
	v_lshl_add_u64 v[212:213], v[206:207], 0, s[18:19]
	global_load_lds_dwordx4 v[212:213], off
	s_mov_b32 m0, s49
	v_lshl_add_u64 v[214:215], v[206:207], 0, s[20:21]
	global_load_lds_dwordx4 v[214:215], off
	s_mov_b32 m0, s50
	v_lshl_add_u64 v[210:211], v[136:137], 0, s[18:19]
	global_load_lds_dwordx4 v[210:211], off
	s_mov_b32 m0, s51
	v_lshl_add_u64 v[212:213], v[136:137], 0, s[20:21]
	global_load_lds_dwordx4 v[212:213], off
	s_mov_b32 m0, s52
	s_mov_b64 s[46:47], 0x40180
	v_lshl_add_u64 v[214:215], v[206:207], 0, s[46:47]
	global_load_lds_dwordx4 v[214:215], off
	s_mov_b32 m0, s53
	s_mov_b64 s[46:47], 0x60180
	v_lshl_add_u64 v[210:211], v[206:207], 0, s[46:47]
	global_load_lds_dwordx4 v[210:211], off
	s_waitcnt vmcnt(6)
	s_waitcnt lgkmcnt(0)
	s_barrier
	s_setprio 1
	v_mfma_f32_16x16x32_bf16 v[60:63], v[158:161], v[142:145], v[60:63]
	v_mfma_f32_16x16x32_bf16 v[56:59], v[158:161], v[150:153], v[56:59]
	v_mfma_f32_16x16x32_bf16 v[52:55], v[166:169], v[142:145], v[52:55]
	v_mfma_f32_16x16x32_bf16 v[48:51], v[166:169], v[150:153], v[48:51]
	v_mfma_f32_16x16x32_bf16 v[44:47], v[174:177], v[142:145], v[44:47]
	v_mfma_f32_16x16x32_bf16 v[40:43], v[174:177], v[150:153], v[40:43]
	v_mfma_f32_16x16x32_bf16 v[36:39], v[182:185], v[142:145], v[36:39]
	v_mfma_f32_16x16x32_bf16 v[32:35], v[182:185], v[150:153], v[32:35]
	v_mfma_f32_16x16x32_bf16 v[60:63], v[162:165], v[146:149], v[60:63]
	v_mfma_f32_16x16x32_bf16 v[56:59], v[162:165], v[154:157], v[56:59]
	v_mfma_f32_16x16x32_bf16 v[52:55], v[170:173], v[146:149], v[52:55]
	v_mfma_f32_16x16x32_bf16 v[48:51], v[170:173], v[154:157], v[48:51]
	v_mfma_f32_16x16x32_bf16 v[44:47], v[178:181], v[146:149], v[44:47]
	v_mfma_f32_16x16x32_bf16 v[40:43], v[178:181], v[154:157], v[40:43]
	v_mfma_f32_16x16x32_bf16 v[36:39], v[186:189], v[146:149], v[36:39]
	v_mfma_f32_16x16x32_bf16 v[32:35], v[186:189], v[154:157], v[32:35]
	v_mfma_f32_16x16x32_bf16 v[28:31], v[158:161], v[190:193], v[28:31]
	v_mfma_f32_16x16x32_bf16 v[24:27], v[158:161], v[198:201], v[24:27]
	v_mfma_f32_16x16x32_bf16 v[20:23], v[166:169], v[190:193], v[20:23]
	v_mfma_f32_16x16x32_bf16 v[16:19], v[166:169], v[198:201], v[16:19]
	v_mfma_f32_16x16x32_bf16 v[12:15], v[174:177], v[190:193], v[12:15]
	v_mfma_f32_16x16x32_bf16 v[8:11], v[174:177], v[198:201], v[8:11]
	v_mfma_f32_16x16x32_bf16 v[4:7], v[182:185], v[190:193], v[4:7]
	v_mfma_f32_16x16x32_bf16 v[0:3], v[182:185], v[198:201], v[0:3]
	v_mfma_f32_16x16x32_bf16 v[28:31], v[162:165], v[194:197], v[28:31]
	v_mfma_f32_16x16x32_bf16 v[24:27], v[162:165], v[202:205], v[24:27]
	v_mfma_f32_16x16x32_bf16 v[20:23], v[170:173], v[194:197], v[20:23]
	v_mfma_f32_16x16x32_bf16 v[16:19], v[170:173], v[202:205], v[16:19]
	v_mfma_f32_16x16x32_bf16 v[12:15], v[178:181], v[194:197], v[12:15]
	v_mfma_f32_16x16x32_bf16 v[8:11], v[178:181], v[202:205], v[8:11]
	v_mfma_f32_16x16x32_bf16 v[4:7], v[186:189], v[194:197], v[4:7]
	v_mfma_f32_16x16x32_bf16 v[0:3], v[186:189], v[202:205], v[0:3]
	s_setprio 0
	s_add_i32 s40, s40, 2
	s_add_u32 s36, s36, 0x100
	s_addc_u32 s37, s37, 0
	s_add_u32 s38, s38, 0x100
	s_addc_u32 s39, s39, 0
	s_cmp_ge_i32 s40, s31
	s_barrier
	s_cbranch_scc0 .LBB0_195

; #define STAGE(P, BASE, br, kt) do { const char* _g = (const char*)((BASE) + (size_t)(br) * K + (size_t)(kt) * G_BK); \
;     _Pragma("unroll") for (int _i = 0; _i < 2; ++_i) { \
;       __builtin_amdgcn_global_load_lds((const unsigned*)(_g + (size_t)_i * 128 * K + sg_off), (unsigned*)((char*)(P) + wid * 1024 + _i * 8192), 16, 0, 0); } } while (0)
; #define LDA(dst, b, h) _Pragma("unroll") for (int m = 0; m < 4; ++m) _Pragma("unroll") for (int k = 0; k < 2; ++k) \
;     dst[m][k] = *reinterpret_cast<const bf16x8*>((const char*)shm + aoff + (((b) * 2 + (h)) * 16384 + m * 2048 + k * 1024))
; #define LDB(dst, b, h) _Pragma("unroll") for (int n = 0; n < 2; ++n) _Pragma("unroll") for (int k = 0; k < 2; ++k) \
;     dst[n][k] = *reinterpret_cast<const bf16x8*>((const char*)shm + boff + (((b) * 2 + (h)) * 16384 + n * 2048 + k * 1024))
; #define MMA(ai, bj, At, Bt_) do { __builtin_amdgcn_s_setprio(1); \
;     _Pragma("unroll") for (int m = 0; m < 4; ++m) _Pragma("unroll") for (int n = 0; n < 2; ++n) _Pragma("unroll") for (int k = 0; k < 2; ++k) \
;       acc[ai][bj][m][n] = mfma16(At[m][k], Bt_[n][k], acc[ai][bj][m][n]); \
;     __builtin_amdgcn_s_setprio(0); } while (0)
; #define WAIT_V(n) asm volatile("s_waitcnt vmcnt(" #n ")" ::: "memory")
; #define WAIT_L(n) asm volatile("s_waitcnt lgkmcnt(" #n ")" ::: "memory")
; #define BAR __builtin_amdgcn_s_barrier()
; #define SCHED __builtin_amdgcn_sched_barrier(0)
; template <class Epi>
; __device__ __forceinline__ void gemm_phase(const bfr* __restrict__ A, int lda, const bfr* __restrict__ Bt, int K,
;                                            int nM, int nN, const Epi& epi, bfr* shm, int wv, int nMfull, int ksplit) {
;     ...
;       LDB(B0, 0, 0); SCHED; LDA(At, 0, 0); STAGE(SA(1, 1), Ak, brow + G_HALF, t + 1);
;       WAIT_L(8); BAR; WAIT_L(0); MMA(0, 0, At, B0); BAR; SCHED;
;       LDB(B1, 0, 1); STAGE(SB(0, 0), Bk, bcol, t + 2);
;       BAR; WAIT_L(0); MMA(0, 1, At, B1); BAR;
;       LDA(At, 0, 1); STAGE(SA(0, 0), Ak, brow, t + 2);
;       BAR; WAIT_L(0); MMA(1, 0, At, B0); BAR; SCHED;
;       STAGE(SB(0, 1), Bk, bcol + G_HALF, t + 2);
;       WAIT_V(6); BAR; MMA(1, 1, At, B1); BAR;
.LBB0_242:
	ds_read_b128 v[140:143], v178
	ds_read_b128 v[144:147], v178 offset:1024
	ds_read_b128 v[148:151], v178 offset:2048
	ds_read_b128 v[152:155], v178 offset:3072
	ds_read_b128 v[156:159], v129
	ds_read_b128 v[160:163], v129 offset:1024
	ds_read_b128 v[164:167], v129 offset:2048
	ds_read_b128 v[168:171], v129 offset:3072
	ds_read_b128 v[172:175], v129 offset:4096
	ds_read_b128 v[180:183], v129 offset:5120
	ds_read_b128 v[184:187], v129 offset:6144
	ds_read_b128 v[188:191], v129 offset:7168
	ds_read_b128 v[192:195], v178 offset:16384
	ds_read_b128 v[196:199], v178 offset:17408
	ds_read_b128 v[200:203], v178 offset:18432
	ds_read_b128 v[204:207], v178 offset:19456
	v_lshl_add_u64 v[176:177], s[44:45], 0, v[138:139]
	v_lshl_add_u64 v[208:209], s[38:39], 0, v[138:139]
	s_mov_b32 m0, s28
	v_lshl_add_u64 v[212:213], v[176:177], 0, s[16:17]
	global_load_lds_dwordx4 v[212:213], off
	s_mov_b32 m0, s29
	v_lshl_add_u64 v[214:215], v[176:177], 0, s[18:19]
	global_load_lds_dwordx4 v[214:215], off
	s_waitcnt lgkmcnt(0)
	s_barrier
	s_setprio 1
	v_mfma_f32_16x16x32_bf16 v[124:127], v[156:159], v[140:143], v[124:127]
	v_mfma_f32_16x16x32_bf16 v[120:123], v[156:159], v[148:151], v[120:123]
	v_mfma_f32_16x16x32_bf16 v[116:119], v[164:167], v[140:143], v[116:119]
	v_mfma_f32_16x16x32_bf16 v[112:115], v[164:167], v[148:151], v[112:115]
	v_mfma_f32_16x16x32_bf16 v[108:111], v[172:175], v[140:143], v[108:111]
	v_mfma_f32_16x16x32_bf16 v[104:107], v[172:175], v[148:151], v[104:107]
	v_mfma_f32_16x16x32_bf16 v[100:103], v[184:187], v[140:143], v[100:103]
	v_mfma_f32_16x16x32_bf16 v[96:99], v[184:187], v[148:151], v[96:99]
	v_mfma_f32_16x16x32_bf16 v[124:127], v[160:163], v[144:147], v[124:127]
	v_mfma_f32_16x16x32_bf16 v[120:123], v[160:163], v[152:155], v[120:123]
	v_mfma_f32_16x16x32_bf16 v[116:119], v[168:171], v[144:147], v[116:119]
	v_mfma_f32_16x16x32_bf16 v[112:115], v[168:171], v[152:155], v[112:115]
	v_mfma_f32_16x16x32_bf16 v[108:111], v[180:183], v[144:147], v[108:111]
	v_mfma_f32_16x16x32_bf16 v[104:107], v[180:183], v[152:155], v[104:107]
	v_mfma_f32_16x16x32_bf16 v[100:103], v[188:191], v[144:147], v[100:103]
	v_mfma_f32_16x16x32_bf16 v[96:99], v[188:191], v[152:155], v[96:99]
	v_mfma_f32_16x16x32_bf16 v[92:95], v[156:159], v[192:195], v[92:95]
	v_mfma_f32_16x16x32_bf16 v[88:91], v[156:159], v[200:203], v[88:91]
	v_mfma_f32_16x16x32_bf16 v[84:87], v[164:167], v[192:195], v[84:87]
	v_mfma_f32_16x16x32_bf16 v[80:83], v[164:167], v[200:203], v[80:83]
	v_mfma_f32_16x16x32_bf16 v[76:79], v[172:175], v[192:195], v[76:79]
	v_mfma_f32_16x16x32_bf16 v[72:75], v[172:175], v[200:203], v[72:75]
	v_mfma_f32_16x16x32_bf16 v[68:71], v[184:187], v[192:195], v[68:71]
	v_mfma_f32_16x16x32_bf16 v[64:67], v[184:187], v[200:203], v[64:67]
	v_mfma_f32_16x16x32_bf16 v[92:95], v[160:163], v[196:199], v[92:95]
	v_mfma_f32_16x16x32_bf16 v[88:91], v[160:163], v[204:207], v[88:91]
	v_mfma_f32_16x16x32_bf16 v[84:87], v[168:171], v[196:199], v[84:87]
	v_mfma_f32_16x16x32_bf16 v[80:83], v[168:171], v[204:207], v[80:83]
	v_mfma_f32_16x16x32_bf16 v[76:79], v[180:183], v[196:199], v[76:79]
	v_mfma_f32_16x16x32_bf16 v[72:75], v[180:183], v[204:207], v[72:75]
	v_mfma_f32_16x16x32_bf16 v[68:71], v[188:191], v[196:199], v[68:71]
	v_mfma_f32_16x16x32_bf16 v[64:67], v[188:191], v[204:207], v[64:67]
	s_setprio 0
	s_barrier
	ds_read_b128 v[156:159], v129 offset:16384
	ds_read_b128 v[160:163], v129 offset:17408
	ds_read_b128 v[164:167], v129 offset:18432
	ds_read_b128 v[168:171], v129 offset:19456
	ds_read_b128 v[172:175], v129 offset:20480
	ds_read_b128 v[180:183], v129 offset:21504
	ds_read_b128 v[184:187], v129 offset:22528
	ds_read_b128 v[188:191], v129 offset:23552
	s_mov_b32 m0, s33
	v_lshl_add_u64 v[216:217], v[208:209], 0, s[20:21]
	global_load_lds_dwordx4 v[216:217], off
	s_mov_b32 m0, s92
	v_lshl_add_u64 v[212:213], v[208:209], 0, s[30:31]
	global_load_lds_dwordx4 v[212:213], off
	s_mov_b32 m0, s26
	v_lshl_add_u64 v[214:215], v[176:177], 0, s[20:21]
	global_load_lds_dwordx4 v[214:215], off
	s_mov_b32 m0, s93
	v_lshl_add_u64 v[216:217], v[176:177], 0, s[30:31]
	global_load_lds_dwordx4 v[216:217], off
	s_mov_b32 m0, s10
	v_lshl_add_u64 v[212:213], v[208:209], 0, s[40:41]
	global_load_lds_dwordx4 v[212:213], off
	s_mov_b32 m0, s11
	v_lshl_add_u64 v[214:215], v[208:209], 0, s[42:43]
	global_load_lds_dwordx4 v[214:215], off
	s_waitcnt vmcnt(6)
	s_waitcnt lgkmcnt(0)
	s_barrier
	s_setprio 1
	v_mfma_f32_16x16x32_bf16 v[60:63], v[156:159], v[140:143], v[60:63]
	v_mfma_f32_16x16x32_bf16 v[56:59], v[156:159], v[148:151], v[56:59]
	v_mfma_f32_16x16x32_bf16 v[52:55], v[164:167], v[140:143], v[52:55]
	v_mfma_f32_16x16x32_bf16 v[48:51], v[164:167], v[148:151], v[48:51]
	v_mfma_f32_16x16x32_bf16 v[44:47], v[172:175], v[140:143], v[44:47]
	v_mfma_f32_16x16x32_bf16 v[40:43], v[172:175], v[148:151], v[40:43]
	v_mfma_f32_16x16x32_bf16 v[36:39], v[184:187], v[140:143], v[36:39]
	v_mfma_f32_16x16x32_bf16 v[32:35], v[184:187], v[148:151], v[32:35]
	v_mfma_f32_16x16x32_bf16 v[60:63], v[160:163], v[144:147], v[60:63]
	v_mfma_f32_16x16x32_bf16 v[56:59], v[160:163], v[152:155], v[56:59]
	v_mfma_f32_16x16x32_bf16 v[52:55], v[168:171], v[144:147], v[52:55]
	v_mfma_f32_16x16x32_bf16 v[48:51], v[168:171], v[152:155], v[48:51]
	v_mfma_f32_16x16x32_bf16 v[44:47], v[180:183], v[144:147], v[44:47]
	v_mfma_f32_16x16x32_bf16 v[40:43], v[180:183], v[152:155], v[40:43]
	v_mfma_f32_16x16x32_bf16 v[36:39], v[188:191], v[144:147], v[36:39]
	v_mfma_f32_16x16x32_bf16 v[32:35], v[188:191], v[152:155], v[32:35]
	v_mfma_f32_16x16x32_bf16 v[28:31], v[156:159], v[192:195], v[28:31]
	v_mfma_f32_16x16x32_bf16 v[24:27], v[156:159], v[200:203], v[24:27]
	v_mfma_f32_16x16x32_bf16 v[20:23], v[164:167], v[192:195], v[20:23]
	v_mfma_f32_16x16x32_bf16 v[16:19], v[164:167], v[200:203], v[16:19]
	v_mfma_f32_16x16x32_bf16 v[12:15], v[172:175], v[192:195], v[12:15]
	v_mfma_f32_16x16x32_bf16 v[8:11], v[172:175], v[200:203], v[8:11]
	v_mfma_f32_16x16x32_bf16 v[4:7], v[184:187], v[192:195], v[4:7]
	v_mfma_f32_16x16x32_bf16 v[0:3], v[184:187], v[200:203], v[0:3]
	v_mfma_f32_16x16x32_bf16 v[28:31], v[160:163], v[196:199], v[28:31]
	v_mfma_f32_16x16x32_bf16 v[24:27], v[160:163], v[204:207], v[24:27]
	v_mfma_f32_16x16x32_bf16 v[20:23], v[168:171], v[196:199], v[20:23]
	v_mfma_f32_16x16x32_bf16 v[16:19], v[168:171], v[204:207], v[16:19]
	v_mfma_f32_16x16x32_bf16 v[12:15], v[180:183], v[196:199], v[12:15]
	v_mfma_f32_16x16x32_bf16 v[8:11], v[180:183], v[204:207], v[8:11]
	v_mfma_f32_16x16x32_bf16 v[4:7], v[188:191], v[196:199], v[4:7]
	v_mfma_f32_16x16x32_bf16 v[0:3], v[188:191], v[204:207], v[0:3]
	s_setprio 0
	s_barrier
; #define STAGE(P, BASE, br, kt) do { const char* _g = (const char*)((BASE) + (size_t)(br) * K + (size_t)(kt) * G_BK); \
;     _Pragma("unroll") for (int _i = 0; _i < 2; ++_i) { \
;       __builtin_amdgcn_global_load_lds((const unsigned*)(_g + (size_t)_i * 128 * K + sg_off), (unsigned*)((char*)(P) + wid * 1024 + _i * 8192), 16, 0, 0); } } while (0)
; #define LDA(dst, b, h) _Pragma("unroll") for (int m = 0; m < 4; ++m) _Pragma("unroll") for (int k = 0; k < 2; ++k) \
;     dst[m][k] = *reinterpret_cast<const bf16x8*>((const char*)shm + aoff + (((b) * 2 + (h)) * 16384 + m * 2048 + k * 1024))
; #define LDB(dst, b, h) _Pragma("unroll") for (int n = 0; n < 2; ++n) _Pragma("unroll") for (int k = 0; k < 2; ++k) \
;     dst[n][k] = *reinterpret_cast<const bf16x8*>((const char*)shm + boff + (((b) * 2 + (h)) * 16384 + n * 2048 + k * 1024))
; #define MMA(ai, bj, At, Bt_) do { __builtin_amdgcn_s_setprio(1); \
;     _Pragma("unroll") for (int m = 0; m < 4; ++m) _Pragma("unroll") for (int n = 0; n < 2; ++n) _Pragma("unroll") for (int k = 0; k < 2; ++k) \
;       acc[ai][bj][m][n] = mfma16(At[m][k], Bt_[n][k], acc[ai][bj][m][n]); \
;     __builtin_amdgcn_s_setprio(0); } while (0)
; #define WAIT_V(n) asm volatile("s_waitcnt vmcnt(" #n ")" ::: "memory")
; #define WAIT_L(n) asm volatile("s_waitcnt lgkmcnt(" #n ")" ::: "memory")
; #define BAR __builtin_amdgcn_s_barrier()
; #define SCHED __builtin_amdgcn_sched_barrier(0)
; template <class Epi>
; __device__ __forceinline__ void gemm_phase(const bfr* __restrict__ A, int lda, const bfr* __restrict__ Bt, int K,
;                                            int nM, int nN, const Epi& epi, bfr* shm, int wv, int nMfull, int ksplit) {
;     ...
;       LDB(B0, 1, 0); SCHED; LDA(At, 1, 0); STAGE(SA(0, 1), Ak, brow + G_HALF, t + 2);
;       WAIT_L(8); BAR; WAIT_L(0); MMA(0, 0, At, B0); BAR; SCHED;
;       LDB(B1, 1, 1); STAGE(SB(1, 0), Bk, bcol, t + 3);
;       BAR; WAIT_L(0); MMA(0, 1, At, B1); BAR;
;       LDA(At, 1, 1); STAGE(SA(1, 0), Ak, brow, t + 3);
;       BAR; WAIT_L(0); MMA(1, 0, At, B0); BAR; SCHED;
;       STAGE(SB(1, 1), Bk, bcol + G_HALF, t + 3);
;       WAIT_V(6); BAR; MMA(1, 1, At, B1); BAR;
;     }
	ds_read_b128 v[140:143], v178 offset:32768
	ds_read_b128 v[144:147], v178 offset:33792
	ds_read_b128 v[148:151], v178 offset:34816
	ds_read_b128 v[152:155], v178 offset:35840
	ds_read_b128 v[156:159], v129 offset:32768
	ds_read_b128 v[160:163], v129 offset:33792
	ds_read_b128 v[164:167], v129 offset:34816
	ds_read_b128 v[168:171], v129 offset:35840
	ds_read_b128 v[172:175], v129 offset:36864
	ds_read_b128 v[180:183], v129 offset:37888
	ds_read_b128 v[184:187], v129 offset:38912
	ds_read_b128 v[188:191], v129 offset:39936
	ds_read_b128 v[192:195], v178 offset:49152
	ds_read_b128 v[196:199], v178 offset:50176
	ds_read_b128 v[200:203], v178 offset:51200
	ds_read_b128 v[204:207], v178 offset:52224
	s_mov_b32 m0, s94
	v_lshl_add_u64 v[216:217], v[176:177], 0, s[40:41]
	global_load_lds_dwordx4 v[216:217], off
	s_mov_b32 m0, s95
	v_lshl_add_u64 v[212:213], v[176:177], 0, s[42:43]
	global_load_lds_dwordx4 v[212:213], off
	s_waitcnt lgkmcnt(0)
	s_barrier
	s_setprio 1
	v_mfma_f32_16x16x32_bf16 v[124:127], v[156:159], v[140:143], v[124:127]
	v_mfma_f32_16x16x32_bf16 v[120:123], v[156:159], v[148:151], v[120:123]
	v_mfma_f32_16x16x32_bf16 v[116:119], v[164:167], v[140:143], v[116:119]
	v_mfma_f32_16x16x32_bf16 v[112:115], v[164:167], v[148:151], v[112:115]
	v_mfma_f32_16x16x32_bf16 v[108:111], v[172:175], v[140:143], v[108:111]
	v_mfma_f32_16x16x32_bf16 v[104:107], v[172:175], v[148:151], v[104:107]
	v_mfma_f32_16x16x32_bf16 v[100:103], v[184:187], v[140:143], v[100:103]
	v_mfma_f32_16x16x32_bf16 v[96:99], v[184:187], v[148:151], v[96:99]
	v_mfma_f32_16x16x32_bf16 v[124:127], v[160:163], v[144:147], v[124:127]
	v_mfma_f32_16x16x32_bf16 v[120:123], v[160:163], v[152:155], v[120:123]
	v_mfma_f32_16x16x32_bf16 v[116:119], v[168:171], v[144:147], v[116:119]
	v_mfma_f32_16x16x32_bf16 v[112:115], v[168:171], v[152:155], v[112:115]
	v_mfma_f32_16x16x32_bf16 v[108:111], v[180:183], v[144:147], v[108:111]
	v_mfma_f32_16x16x32_bf16 v[104:107], v[180:183], v[152:155], v[104:107]
	v_mfma_f32_16x16x32_bf16 v[100:103], v[188:191], v[144:147], v[100:103]
	v_mfma_f32_16x16x32_bf16 v[96:99], v[188:191], v[152:155], v[96:99]
	v_mfma_f32_16x16x32_bf16 v[92:95], v[156:159], v[192:195], v[92:95]
	v_mfma_f32_16x16x32_bf16 v[88:91], v[156:159], v[200:203], v[88:91]
	v_mfma_f32_16x16x32_bf16 v[84:87], v[164:167], v[192:195], v[84:87]
	v_mfma_f32_16x16x32_bf16 v[80:83], v[164:167], v[200:203], v[80:83]
	v_mfma_f32_16x16x32_bf16 v[76:79], v[172:175], v[192:195], v[76:79]
	v_mfma_f32_16x16x32_bf16 v[72:75], v[172:175], v[200:203], v[72:75]
	v_mfma_f32_16x16x32_bf16 v[68:71], v[184:187], v[192:195], v[68:71]
	v_mfma_f32_16x16x32_bf16 v[64:67], v[184:187], v[200:203], v[64:67]
	v_mfma_f32_16x16x32_bf16 v[92:95], v[160:163], v[196:199], v[92:95]
	v_mfma_f32_16x16x32_bf16 v[88:91], v[160:163], v[204:207], v[88:91]
	v_mfma_f32_16x16x32_bf16 v[84:87], v[168:171], v[196:199], v[84:87]
	v_mfma_f32_16x16x32_bf16 v[80:83], v[168:171], v[204:207], v[80:83]
	v_mfma_f32_16x16x32_bf16 v[76:79], v[180:183], v[196:199], v[76:79]
	v_mfma_f32_16x16x32_bf16 v[72:75], v[180:183], v[204:207], v[72:75]
	v_mfma_f32_16x16x32_bf16 v[68:71], v[188:191], v[196:199], v[68:71]
	v_mfma_f32_16x16x32_bf16 v[64:67], v[188:191], v[204:207], v[64:67]
	s_setprio 0
	s_barrier
	ds_read_b128 v[156:159], v129 offset:49152
	ds_read_b128 v[160:163], v129 offset:50176
	ds_read_b128 v[164:167], v129 offset:51200
	ds_read_b128 v[168:171], v129 offset:52224
	ds_read_b128 v[172:175], v129 offset:53248
	ds_read_b128 v[180:183], v129 offset:54272
	ds_read_b128 v[184:187], v129 offset:55296
	ds_read_b128 v[188:191], v129 offset:56320
	s_mov_b32 m0, s8
	v_lshl_add_u64 v[214:215], v[208:209], 0, s[46:47]
	global_load_lds_dwordx4 v[214:215], off
	s_mov_b32 m0, s9
	v_lshl_add_u64 v[216:217], v[208:209], 0, s[48:49]
	global_load_lds_dwordx4 v[216:217], off
	s_mov_b32 m0, s50
	v_lshl_add_u64 v[212:213], v[176:177], 0, s[46:47]
	global_load_lds_dwordx4 v[212:213], off
	s_mov_b32 m0, s51
	v_lshl_add_u64 v[214:215], v[176:177], 0, s[48:49]
	global_load_lds_dwordx4 v[214:215], off
	s_mov_b32 m0, s24
	s_mov_b64 s[54:55], 0xb0180
	v_lshl_add_u64 v[216:217], v[208:209], 0, s[54:55]
	global_load_lds_dwordx4 v[216:217], off
	s_mov_b32 m0, s25
	s_mov_b64 s[54:55], 0x108180
	v_lshl_add_u64 v[212:213], v[208:209], 0, s[54:55]
	global_load_lds_dwordx4 v[212:213], off
	s_waitcnt vmcnt(6)
	s_waitcnt lgkmcnt(0)
	s_barrier
	s_setprio 1
	v_mfma_f32_16x16x32_bf16 v[60:63], v[156:159], v[140:143], v[60:63]
	v_mfma_f32_16x16x32_bf16 v[56:59], v[156:159], v[148:151], v[56:59]
	v_mfma_f32_16x16x32_bf16 v[52:55], v[164:167], v[140:143], v[52:55]
	v_mfma_f32_16x16x32_bf16 v[48:51], v[164:167], v[148:151], v[48:51]
	v_mfma_f32_16x16x32_bf16 v[44:47], v[172:175], v[140:143], v[44:47]
	v_mfma_f32_16x16x32_bf16 v[40:43], v[172:175], v[148:151], v[40:43]
	v_mfma_f32_16x16x32_bf16 v[36:39], v[184:187], v[140:143], v[36:39]
	v_mfma_f32_16x16x32_bf16 v[32:35], v[184:187], v[148:151], v[32:35]
	v_mfma_f32_16x16x32_bf16 v[60:63], v[160:163], v[144:147], v[60:63]
	v_mfma_f32_16x16x32_bf16 v[56:59], v[160:163], v[152:155], v[56:59]
	v_mfma_f32_16x16x32_bf16 v[52:55], v[168:171], v[144:147], v[52:55]
	v_mfma_f32_16x16x32_bf16 v[48:51], v[168:171], v[152:155], v[48:51]
	v_mfma_f32_16x16x32_bf16 v[44:47], v[180:183], v[144:147], v[44:47]
	v_mfma_f32_16x16x32_bf16 v[40:43], v[180:183], v[152:155], v[40:43]
	v_mfma_f32_16x16x32_bf16 v[36:39], v[188:191], v[144:147], v[36:39]
	v_mfma_f32_16x16x32_bf16 v[32:35], v[188:191], v[152:155], v[32:35]
	v_mfma_f32_16x16x32_bf16 v[28:31], v[156:159], v[192:195], v[28:31]
	v_mfma_f32_16x16x32_bf16 v[24:27], v[156:159], v[200:203], v[24:27]
	v_mfma_f32_16x16x32_bf16 v[20:23], v[164:167], v[192:195], v[20:23]
	v_mfma_f32_16x16x32_bf16 v[16:19], v[164:167], v[200:203], v[16:19]
	v_mfma_f32_16x16x32_bf16 v[12:15], v[172:175], v[192:195], v[12:15]
	v_mfma_f32_16x16x32_bf16 v[8:11], v[172:175], v[200:203], v[8:11]
	v_mfma_f32_16x16x32_bf16 v[4:7], v[184:187], v[192:195], v[4:7]
	v_mfma_f32_16x16x32_bf16 v[0:3], v[184:187], v[200:203], v[0:3]
	v_mfma_f32_16x16x32_bf16 v[28:31], v[160:163], v[196:199], v[28:31]
	v_mfma_f32_16x16x32_bf16 v[24:27], v[160:163], v[204:207], v[24:27]
	v_mfma_f32_16x16x32_bf16 v[20:23], v[168:171], v[196:199], v[20:23]
	v_mfma_f32_16x16x32_bf16 v[16:19], v[168:171], v[204:207], v[16:19]
	v_mfma_f32_16x16x32_bf16 v[12:15], v[180:183], v[196:199], v[12:15]
	v_mfma_f32_16x16x32_bf16 v[8:11], v[180:183], v[204:207], v[8:11]
	v_mfma_f32_16x16x32_bf16 v[4:7], v[188:191], v[196:199], v[4:7]
	v_mfma_f32_16x16x32_bf16 v[0:3], v[188:191], v[204:207], v[0:3]
	s_setprio 0
	s_add_i32 s27, s27, 2
	s_add_u32 s38, s38, 0x100
	s_addc_u32 s39, s39, 0
	s_add_u32 s44, s44, 0x100
	s_addc_u32 s45, s45, 0
	s_cmp_ge_i32 s27, s6
	s_barrier
	s_cbranch_scc0 .LBB0_242

; #define STAGE(P, BASE, br, kt) do { const char* _g = (const char*)((BASE) + (size_t)(br) * K + (size_t)(kt) * G_BK); \
;     _Pragma("unroll") for (int _i = 0; _i < 2; ++_i) { \
;       __builtin_amdgcn_global_load_lds((const unsigned*)(_g + (size_t)_i * 128 * K + sg_off), (unsigned*)((char*)(P) + wid * 1024 + _i * 8192), 16, 0, 0); } } while (0)
; #define LDA(dst, b, h) _Pragma("unroll") for (int m = 0; m < 4; ++m) _Pragma("unroll") for (int k = 0; k < 2; ++k) \
;     dst[m][k] = *reinterpret_cast<const bf16x8*>((const char*)shm + aoff + (((b) * 2 + (h)) * 16384 + m * 2048 + k * 1024))
; #define LDB(dst, b, h) _Pragma("unroll") for (int n = 0; n < 2; ++n) _Pragma("unroll") for (int k = 0; k < 2; ++k) \
;     dst[n][k] = *reinterpret_cast<const bf16x8*>((const char*)shm + boff + (((b) * 2 + (h)) * 16384 + n * 2048 + k * 1024))
; #define MMA(ai, bj, At, Bt_) do { __builtin_amdgcn_s_setprio(1); \
;     _Pragma("unroll") for (int m = 0; m < 4; ++m) _Pragma("unroll") for (int n = 0; n < 2; ++n) _Pragma("unroll") for (int k = 0; k < 2; ++k) \
;       acc[ai][bj][m][n] = mfma16(At[m][k], Bt_[n][k], acc[ai][bj][m][n]); \
;     __builtin_amdgcn_s_setprio(0); } while (0)
; #define WAIT_V(n) asm volatile("s_waitcnt vmcnt(" #n ")" ::: "memory")
; #define WAIT_L(n) asm volatile("s_waitcnt lgkmcnt(" #n ")" ::: "memory")
; #define BAR __builtin_amdgcn_s_barrier()
; #define SCHED __builtin_amdgcn_sched_barrier(0)
; template <class Epi>
; __device__ __forceinline__ void gemm_phase(const bfr* __restrict__ A, int lda, const bfr* __restrict__ Bt, int K,
;                                            int nM, int nN, const Epi& epi, bfr* shm, int wv, int nMfull, int ksplit) {
;     ...
;       LDB(B0, 0, 0); SCHED; LDA(At, 0, 0); STAGE(SA(1, 1), Ak, brow + G_HALF, t + 1);
;       WAIT_L(8); BAR; WAIT_L(0); MMA(0, 0, At, B0); BAR; SCHED;
;       LDB(B1, 0, 1); STAGE(SB(0, 0), Bk, bcol, t + 2);
;       BAR; WAIT_L(0); MMA(0, 1, At, B1); BAR;
;       LDA(At, 0, 1); STAGE(SA(0, 0), Ak, brow, t + 2);
;       BAR; WAIT_L(0); MMA(1, 0, At, B0); BAR; SCHED;
;       STAGE(SB(0, 1), Bk, bcol + G_HALF, t + 2);
;       WAIT_V(6); BAR; MMA(1, 1, At, B1); BAR;
.LBB0_396:
	ds_read_b128 v[128:131], v181
	ds_read_b128 v[136:139], v181 offset:1024
	ds_read_b128 v[142:145], v181 offset:2048
	ds_read_b128 v[146:149], v181 offset:3072
	ds_read_b128 v[150:153], v179
	ds_read_b128 v[154:157], v179 offset:1024
	ds_read_b128 v[158:161], v179 offset:2048
	ds_read_b128 v[162:165], v179 offset:3072
	ds_read_b128 v[166:169], v179 offset:4096
	ds_read_b128 v[182:185], v179 offset:5120
	ds_read_b128 v[186:189], v179 offset:6144
	ds_read_b128 v[190:193], v179 offset:7168
	ds_read_b128 v[194:197], v181 offset:16384
	ds_read_b128 v[198:201], v181 offset:17408
	ds_read_b128 v[202:205], v181 offset:18432
	ds_read_b128 v[206:209], v181 offset:19456
	v_lshl_add_u64 v[132:133], s[4:5], 0, v[140:141]
	v_lshl_add_u64 v[170:171], s[2:3], 0, v[140:141]
	s_mov_b32 m0, s58
	s_mov_b64 s[12:13], 0x40080
	v_lshl_add_u64 v[210:211], v[132:133], 0, s[12:13]
	global_load_lds_dwordx4 v[210:211], off
	s_mov_b32 m0, s59
	s_mov_b64 s[12:13], 0x60080
	v_lshl_add_u64 v[212:213], v[132:133], 0, s[12:13]
	global_load_lds_dwordx4 v[212:213], off
	s_waitcnt lgkmcnt(0)
	s_barrier
	s_setprio 1
	v_mfma_f32_16x16x32_bf16 v[124:127], v[150:153], v[128:131], v[124:127]
	v_mfma_f32_16x16x32_bf16 v[120:123], v[150:153], v[142:145], v[120:123]
	v_mfma_f32_16x16x32_bf16 v[116:119], v[158:161], v[128:131], v[116:119]
	v_mfma_f32_16x16x32_bf16 v[112:115], v[158:161], v[142:145], v[112:115]
	v_mfma_f32_16x16x32_bf16 v[108:111], v[166:169], v[128:131], v[108:111]
	v_mfma_f32_16x16x32_bf16 v[104:107], v[166:169], v[142:145], v[104:107]
	v_mfma_f32_16x16x32_bf16 v[100:103], v[186:189], v[128:131], v[100:103]
	v_mfma_f32_16x16x32_bf16 v[96:99], v[186:189], v[142:145], v[96:99]
	v_mfma_f32_16x16x32_bf16 v[124:127], v[154:157], v[136:139], v[124:127]
	v_mfma_f32_16x16x32_bf16 v[120:123], v[154:157], v[146:149], v[120:123]
	v_mfma_f32_16x16x32_bf16 v[116:119], v[162:165], v[136:139], v[116:119]
	v_mfma_f32_16x16x32_bf16 v[112:115], v[162:165], v[146:149], v[112:115]
	v_mfma_f32_16x16x32_bf16 v[108:111], v[182:185], v[136:139], v[108:111]
	v_mfma_f32_16x16x32_bf16 v[104:107], v[182:185], v[146:149], v[104:107]
	v_mfma_f32_16x16x32_bf16 v[100:103], v[190:193], v[136:139], v[100:103]
	v_mfma_f32_16x16x32_bf16 v[96:99], v[190:193], v[146:149], v[96:99]
	v_mfma_f32_16x16x32_bf16 v[92:95], v[150:153], v[194:197], v[92:95]
	v_mfma_f32_16x16x32_bf16 v[88:91], v[150:153], v[202:205], v[88:91]
	v_mfma_f32_16x16x32_bf16 v[84:87], v[158:161], v[194:197], v[84:87]
	v_mfma_f32_16x16x32_bf16 v[80:83], v[158:161], v[202:205], v[80:83]
	v_mfma_f32_16x16x32_bf16 v[76:79], v[166:169], v[194:197], v[76:79]
	v_mfma_f32_16x16x32_bf16 v[72:75], v[166:169], v[202:205], v[72:75]
	v_mfma_f32_16x16x32_bf16 v[68:71], v[186:189], v[194:197], v[68:71]
	v_mfma_f32_16x16x32_bf16 v[64:67], v[186:189], v[202:205], v[64:67]
	v_mfma_f32_16x16x32_bf16 v[92:95], v[154:157], v[198:201], v[92:95]
	v_mfma_f32_16x16x32_bf16 v[88:91], v[154:157], v[206:209], v[88:91]
	v_mfma_f32_16x16x32_bf16 v[84:87], v[162:165], v[198:201], v[84:87]
	v_mfma_f32_16x16x32_bf16 v[80:83], v[162:165], v[206:209], v[80:83]
	v_mfma_f32_16x16x32_bf16 v[76:79], v[182:185], v[198:201], v[76:79]
	v_mfma_f32_16x16x32_bf16 v[72:75], v[182:185], v[206:209], v[72:75]
	v_mfma_f32_16x16x32_bf16 v[68:71], v[190:193], v[198:201], v[68:71]
	v_mfma_f32_16x16x32_bf16 v[64:67], v[190:193], v[206:209], v[64:67]
	s_setprio 0
	s_barrier
	ds_read_b128 v[150:153], v179 offset:16384
	ds_read_b128 v[154:157], v179 offset:17408
	ds_read_b128 v[158:161], v179 offset:18432
	ds_read_b128 v[162:165], v179 offset:19456
	ds_read_b128 v[166:169], v179 offset:20480
	ds_read_b128 v[182:185], v179 offset:21504
	ds_read_b128 v[186:189], v179 offset:22528
	ds_read_b128 v[190:193], v179 offset:23552
	s_mov_b32 m0, s97
	v_lshl_add_u64 v[214:215], v[170:171], 0, s[14:15]
	global_load_lds_dwordx4 v[214:215], off
	s_mov_b32 m0, s51
	v_lshl_add_u64 v[210:211], v[170:171], 0, s[16:17]
	global_load_lds_dwordx4 v[210:211], off
	s_mov_b32 m0, s56
	v_lshl_add_u64 v[212:213], v[132:133], 0, s[14:15]
	global_load_lds_dwordx4 v[212:213], off
	s_mov_b32 m0, s57
	v_lshl_add_u64 v[214:215], v[132:133], 0, s[16:17]
	global_load_lds_dwordx4 v[214:215], off
	s_mov_b32 m0, s33
	v_lshl_add_u64 v[210:211], v[170:171], 0, s[18:19]
	global_load_lds_dwordx4 v[210:211], off
	s_mov_b32 m0, s22
	v_lshl_add_u64 v[212:213], v[170:171], 0, s[20:21]
	global_load_lds_dwordx4 v[212:213], off
	s_waitcnt vmcnt(6)
	s_waitcnt lgkmcnt(0)
	s_barrier
	s_setprio 1
	v_mfma_f32_16x16x32_bf16 v[60:63], v[150:153], v[128:131], v[60:63]
	v_mfma_f32_16x16x32_bf16 v[56:59], v[150:153], v[142:145], v[56:59]
	v_mfma_f32_16x16x32_bf16 v[52:55], v[158:161], v[128:131], v[52:55]
	v_mfma_f32_16x16x32_bf16 v[48:51], v[158:161], v[142:145], v[48:51]
	v_mfma_f32_16x16x32_bf16 v[44:47], v[166:169], v[128:131], v[44:47]
	v_mfma_f32_16x16x32_bf16 v[40:43], v[166:169], v[142:145], v[40:43]
	v_mfma_f32_16x16x32_bf16 v[36:39], v[186:189], v[128:131], v[36:39]
	v_mfma_f32_16x16x32_bf16 v[32:35], v[186:189], v[142:145], v[32:35]
	v_mfma_f32_16x16x32_bf16 v[60:63], v[154:157], v[136:139], v[60:63]
	v_mfma_f32_16x16x32_bf16 v[56:59], v[154:157], v[146:149], v[56:59]
	v_mfma_f32_16x16x32_bf16 v[52:55], v[162:165], v[136:139], v[52:55]
	v_mfma_f32_16x16x32_bf16 v[48:51], v[162:165], v[146:149], v[48:51]
	v_mfma_f32_16x16x32_bf16 v[44:47], v[182:185], v[136:139], v[44:47]
	v_mfma_f32_16x16x32_bf16 v[40:43], v[182:185], v[146:149], v[40:43]
	v_mfma_f32_16x16x32_bf16 v[36:39], v[190:193], v[136:139], v[36:39]
	v_mfma_f32_16x16x32_bf16 v[32:35], v[190:193], v[146:149], v[32:35]
	v_mfma_f32_16x16x32_bf16 v[28:31], v[150:153], v[194:197], v[28:31]
	v_mfma_f32_16x16x32_bf16 v[24:27], v[150:153], v[202:205], v[24:27]
	v_mfma_f32_16x16x32_bf16 v[20:23], v[158:161], v[194:197], v[20:23]
	v_mfma_f32_16x16x32_bf16 v[16:19], v[158:161], v[202:205], v[16:19]
	v_mfma_f32_16x16x32_bf16 v[12:15], v[166:169], v[194:197], v[12:15]
	v_mfma_f32_16x16x32_bf16 v[8:11], v[166:169], v[202:205], v[8:11]
	v_mfma_f32_16x16x32_bf16 v[4:7], v[186:189], v[194:197], v[4:7]
	v_mfma_f32_16x16x32_bf16 v[0:3], v[186:189], v[202:205], v[0:3]
	v_mfma_f32_16x16x32_bf16 v[28:31], v[154:157], v[198:201], v[28:31]
	v_mfma_f32_16x16x32_bf16 v[24:27], v[154:157], v[206:209], v[24:27]
	v_mfma_f32_16x16x32_bf16 v[20:23], v[162:165], v[198:201], v[20:23]
	v_mfma_f32_16x16x32_bf16 v[16:19], v[162:165], v[206:209], v[16:19]
	v_mfma_f32_16x16x32_bf16 v[12:15], v[182:185], v[198:201], v[12:15]
	v_mfma_f32_16x16x32_bf16 v[8:11], v[182:185], v[206:209], v[8:11]
	v_mfma_f32_16x16x32_bf16 v[4:7], v[190:193], v[198:201], v[4:7]
	v_mfma_f32_16x16x32_bf16 v[0:3], v[190:193], v[206:209], v[0:3]
	s_setprio 0
	s_barrier
; #define STAGE(P, BASE, br, kt) do { const char* _g = (const char*)((BASE) + (size_t)(br) * K + (size_t)(kt) * G_BK); \
;     _Pragma("unroll") for (int _i = 0; _i < 2; ++_i) { \
;       __builtin_amdgcn_global_load_lds((const unsigned*)(_g + (size_t)_i * 128 * K + sg_off), (unsigned*)((char*)(P) + wid * 1024 + _i * 8192), 16, 0, 0); } } while (0)
; #define LDA(dst, b, h) _Pragma("unroll") for (int m = 0; m < 4; ++m) _Pragma("unroll") for (int k = 0; k < 2; ++k) \
;     dst[m][k] = *reinterpret_cast<const bf16x8*>((const char*)shm + aoff + (((b) * 2 + (h)) * 16384 + m * 2048 + k * 1024))
; #define LDB(dst, b, h) _Pragma("unroll") for (int n = 0; n < 2; ++n) _Pragma("unroll") for (int k = 0; k < 2; ++k) \
;     dst[n][k] = *reinterpret_cast<const bf16x8*>((const char*)shm + boff + (((b) * 2 + (h)) * 16384 + n * 2048 + k * 1024))
; #define MMA(ai, bj, At, Bt_) do { __builtin_amdgcn_s_setprio(1); \
;     _Pragma("unroll") for (int m = 0; m < 4; ++m) _Pragma("unroll") for (int n = 0; n < 2; ++n) _Pragma("unroll") for (int k = 0; k < 2; ++k) \
;       acc[ai][bj][m][n] = mfma16(At[m][k], Bt_[n][k], acc[ai][bj][m][n]); \
;     __builtin_amdgcn_s_setprio(0); } while (0)
; #define WAIT_V(n) asm volatile("s_waitcnt vmcnt(" #n ")" ::: "memory")
; #define WAIT_L(n) asm volatile("s_waitcnt lgkmcnt(" #n ")" ::: "memory")
; #define BAR __builtin_amdgcn_s_barrier()
; #define SCHED __builtin_amdgcn_sched_barrier(0)
; template <class Epi>
; __device__ __forceinline__ void gemm_phase(const bfr* __restrict__ A, int lda, const bfr* __restrict__ Bt, int K,
;                                            int nM, int nN, const Epi& epi, bfr* shm, int wv, int nMfull, int ksplit) {
;     ...
;       LDB(B0, 1, 0); SCHED; LDA(At, 1, 0); STAGE(SA(0, 1), Ak, brow + G_HALF, t + 2);
;       WAIT_L(8); BAR; WAIT_L(0); MMA(0, 0, At, B0); BAR; SCHED;
;       LDB(B1, 1, 1); STAGE(SB(1, 0), Bk, bcol, t + 3);
;       BAR; WAIT_L(0); MMA(0, 1, At, B1); BAR;
;       LDA(At, 1, 1); STAGE(SA(1, 0), Ak, brow, t + 3);
;       BAR; WAIT_L(0); MMA(1, 0, At, B0); BAR; SCHED;
;       STAGE(SB(1, 1), Bk, bcol + G_HALF, t + 3);
;       WAIT_V(6); BAR; MMA(1, 1, At, B1); BAR;
;     }
	ds_read_b128 v[128:131], v181 offset:32768
	ds_read_b128 v[136:139], v181 offset:33792
	ds_read_b128 v[142:145], v181 offset:34816
	ds_read_b128 v[146:149], v181 offset:35840
	ds_read_b128 v[150:153], v179 offset:32768
	ds_read_b128 v[154:157], v179 offset:33792
	ds_read_b128 v[158:161], v179 offset:34816
	ds_read_b128 v[162:165], v179 offset:35840
	ds_read_b128 v[166:169], v179 offset:36864
	ds_read_b128 v[182:185], v179 offset:37888
	ds_read_b128 v[186:189], v179 offset:38912
	ds_read_b128 v[190:193], v179 offset:39936
	ds_read_b128 v[194:197], v181 offset:49152
	ds_read_b128 v[198:201], v181 offset:50176
	ds_read_b128 v[202:205], v181 offset:51200
	ds_read_b128 v[206:209], v181 offset:52224
	s_mov_b32 m0, s23
	v_lshl_add_u64 v[214:215], v[132:133], 0, s[18:19]
	global_load_lds_dwordx4 v[214:215], off
	s_mov_b32 m0, s24
	v_lshl_add_u64 v[210:211], v[132:133], 0, s[20:21]
	global_load_lds_dwordx4 v[210:211], off
	s_waitcnt lgkmcnt(0)
	s_barrier
	s_setprio 1
	v_mfma_f32_16x16x32_bf16 v[124:127], v[150:153], v[128:131], v[124:127]
	v_mfma_f32_16x16x32_bf16 v[120:123], v[150:153], v[142:145], v[120:123]
	v_mfma_f32_16x16x32_bf16 v[116:119], v[158:161], v[128:131], v[116:119]
	v_mfma_f32_16x16x32_bf16 v[112:115], v[158:161], v[142:145], v[112:115]
	v_mfma_f32_16x16x32_bf16 v[108:111], v[166:169], v[128:131], v[108:111]
	v_mfma_f32_16x16x32_bf16 v[104:107], v[166:169], v[142:145], v[104:107]
	v_mfma_f32_16x16x32_bf16 v[100:103], v[186:189], v[128:131], v[100:103]
	v_mfma_f32_16x16x32_bf16 v[96:99], v[186:189], v[142:145], v[96:99]
	v_mfma_f32_16x16x32_bf16 v[124:127], v[154:157], v[136:139], v[124:127]
	v_mfma_f32_16x16x32_bf16 v[120:123], v[154:157], v[146:149], v[120:123]
	v_mfma_f32_16x16x32_bf16 v[116:119], v[162:165], v[136:139], v[116:119]
	v_mfma_f32_16x16x32_bf16 v[112:115], v[162:165], v[146:149], v[112:115]
	v_mfma_f32_16x16x32_bf16 v[108:111], v[182:185], v[136:139], v[108:111]
	v_mfma_f32_16x16x32_bf16 v[104:107], v[182:185], v[146:149], v[104:107]
	v_mfma_f32_16x16x32_bf16 v[100:103], v[190:193], v[136:139], v[100:103]
	v_mfma_f32_16x16x32_bf16 v[96:99], v[190:193], v[146:149], v[96:99]
	v_mfma_f32_16x16x32_bf16 v[92:95], v[150:153], v[194:197], v[92:95]
	v_mfma_f32_16x16x32_bf16 v[88:91], v[150:153], v[202:205], v[88:91]
	v_mfma_f32_16x16x32_bf16 v[84:87], v[158:161], v[194:197], v[84:87]
	v_mfma_f32_16x16x32_bf16 v[80:83], v[158:161], v[202:205], v[80:83]
	v_mfma_f32_16x16x32_bf16 v[76:79], v[166:169], v[194:197], v[76:79]
	v_mfma_f32_16x16x32_bf16 v[72:75], v[166:169], v[202:205], v[72:75]
	v_mfma_f32_16x16x32_bf16 v[68:71], v[186:189], v[194:197], v[68:71]
	v_mfma_f32_16x16x32_bf16 v[64:67], v[186:189], v[202:205], v[64:67]
	v_mfma_f32_16x16x32_bf16 v[92:95], v[154:157], v[198:201], v[92:95]
	v_mfma_f32_16x16x32_bf16 v[88:91], v[154:157], v[206:209], v[88:91]
	v_mfma_f32_16x16x32_bf16 v[84:87], v[162:165], v[198:201], v[84:87]
	v_mfma_f32_16x16x32_bf16 v[80:83], v[162:165], v[206:209], v[80:83]
	v_mfma_f32_16x16x32_bf16 v[76:79], v[182:185], v[198:201], v[76:79]
	v_mfma_f32_16x16x32_bf16 v[72:75], v[182:185], v[206:209], v[72:75]
	v_mfma_f32_16x16x32_bf16 v[68:71], v[190:193], v[198:201], v[68:71]
	v_mfma_f32_16x16x32_bf16 v[64:67], v[190:193], v[206:209], v[64:67]
	s_setprio 0
	s_barrier
	ds_read_b128 v[150:153], v179 offset:49152
	ds_read_b128 v[154:157], v179 offset:50176
	ds_read_b128 v[158:161], v179 offset:51200
	ds_read_b128 v[162:165], v179 offset:52224
	ds_read_b128 v[166:169], v179 offset:53248
	ds_read_b128 v[182:185], v179 offset:54272
	ds_read_b128 v[186:189], v179 offset:55296
	ds_read_b128 v[190:193], v179 offset:56320
	s_mov_b32 m0, s25
	v_lshl_add_u64 v[212:213], v[170:171], 0, s[30:31]
	global_load_lds_dwordx4 v[212:213], off
	s_mov_b32 m0, s26
	v_lshl_add_u64 v[214:215], v[170:171], 0, s[40:41]
	global_load_lds_dwordx4 v[214:215], off
	s_mov_b32 m0, s27
	v_lshl_add_u64 v[210:211], v[132:133], 0, s[30:31]
	global_load_lds_dwordx4 v[210:211], off
	s_mov_b32 m0, s28
	v_lshl_add_u64 v[212:213], v[132:133], 0, s[40:41]
	global_load_lds_dwordx4 v[212:213], off
	s_mov_b32 m0, s29
	s_mov_b64 s[12:13], 0x40180
	v_lshl_add_u64 v[214:215], v[170:171], 0, s[12:13]
	global_load_lds_dwordx4 v[214:215], off
	s_mov_b32 m0, s9
	s_mov_b64 s[12:13], 0x60180
	v_lshl_add_u64 v[210:211], v[170:171], 0, s[12:13]
	global_load_lds_dwordx4 v[210:211], off
	s_waitcnt vmcnt(6)
	s_waitcnt lgkmcnt(0)
	s_barrier
	s_setprio 1
	v_mfma_f32_16x16x32_bf16 v[60:63], v[150:153], v[128:131], v[60:63]
	v_mfma_f32_16x16x32_bf16 v[56:59], v[150:153], v[142:145], v[56:59]
	v_mfma_f32_16x16x32_bf16 v[52:55], v[158:161], v[128:131], v[52:55]
	v_mfma_f32_16x16x32_bf16 v[48:51], v[158:161], v[142:145], v[48:51]
	v_mfma_f32_16x16x32_bf16 v[44:47], v[166:169], v[128:131], v[44:47]
	v_mfma_f32_16x16x32_bf16 v[40:43], v[166:169], v[142:145], v[40:43]
	v_mfma_f32_16x16x32_bf16 v[36:39], v[186:189], v[128:131], v[36:39]
	v_mfma_f32_16x16x32_bf16 v[32:35], v[186:189], v[142:145], v[32:35]
	v_mfma_f32_16x16x32_bf16 v[60:63], v[154:157], v[136:139], v[60:63]
	v_mfma_f32_16x16x32_bf16 v[56:59], v[154:157], v[146:149], v[56:59]
	v_mfma_f32_16x16x32_bf16 v[52:55], v[162:165], v[136:139], v[52:55]
	v_mfma_f32_16x16x32_bf16 v[48:51], v[162:165], v[146:149], v[48:51]
	v_mfma_f32_16x16x32_bf16 v[44:47], v[182:185], v[136:139], v[44:47]
	v_mfma_f32_16x16x32_bf16 v[40:43], v[182:185], v[146:149], v[40:43]
	v_mfma_f32_16x16x32_bf16 v[36:39], v[190:193], v[136:139], v[36:39]
	v_mfma_f32_16x16x32_bf16 v[32:35], v[190:193], v[146:149], v[32:35]
	v_mfma_f32_16x16x32_bf16 v[28:31], v[150:153], v[194:197], v[28:31]
	v_mfma_f32_16x16x32_bf16 v[24:27], v[150:153], v[202:205], v[24:27]
	v_mfma_f32_16x16x32_bf16 v[20:23], v[158:161], v[194:197], v[20:23]
	v_mfma_f32_16x16x32_bf16 v[16:19], v[158:161], v[202:205], v[16:19]
	v_mfma_f32_16x16x32_bf16 v[12:15], v[166:169], v[194:197], v[12:15]
	v_mfma_f32_16x16x32_bf16 v[8:11], v[166:169], v[202:205], v[8:11]
	v_mfma_f32_16x16x32_bf16 v[4:7], v[186:189], v[194:197], v[4:7]
	v_mfma_f32_16x16x32_bf16 v[0:3], v[186:189], v[202:205], v[0:3]
	v_mfma_f32_16x16x32_bf16 v[28:31], v[154:157], v[198:201], v[28:31]
	v_mfma_f32_16x16x32_bf16 v[24:27], v[154:157], v[206:209], v[24:27]
	v_mfma_f32_16x16x32_bf16 v[20:23], v[162:165], v[198:201], v[20:23]
	v_mfma_f32_16x16x32_bf16 v[16:19], v[162:165], v[206:209], v[16:19]
	v_mfma_f32_16x16x32_bf16 v[12:15], v[182:185], v[198:201], v[12:15]
	v_mfma_f32_16x16x32_bf16 v[8:11], v[182:185], v[206:209], v[8:11]
	v_mfma_f32_16x16x32_bf16 v[4:7], v[190:193], v[198:201], v[4:7]
	v_mfma_f32_16x16x32_bf16 v[0:3], v[190:193], v[206:209], v[0:3]
	s_setprio 0
	s_add_i32 s6, s6, 2
	s_add_u32 s2, s2, 0x100
	s_addc_u32 s3, s3, 0
	s_add_u32 s4, s4, 0x100
	s_addc_u32 s5, s5, 0
	s_cmp_ge_i32 s6, s1
	s_barrier
	s_cbranch_scc0 .LBB0_396
	v_readlane_b32 s60, v255, 41

; #define STAGE(P, BASE, br, kt) do { const char* _g = (const char*)((BASE) + (size_t)(br) * K + (size_t)(kt) * G_BK); \
;     _Pragma("unroll") for (int _i = 0; _i < 2; ++_i) { \
;       __builtin_amdgcn_global_load_lds((const unsigned*)(_g + (size_t)_i * 128 * K + sg_off), (unsigned*)((char*)(P) + wid * 1024 + _i * 8192), 16, 0, 0); } } while (0)
; #define LDA(dst, b, h) _Pragma("unroll") for (int m = 0; m < 4; ++m) _Pragma("unroll") for (int k = 0; k < 2; ++k) \
;     dst[m][k] = *reinterpret_cast<const bf16x8*>((const char*)shm + aoff + (((b) * 2 + (h)) * 16384 + m * 2048 + k * 1024))
; #define LDB(dst, b, h) _Pragma("unroll") for (int n = 0; n < 2; ++n) _Pragma("unroll") for (int k = 0; k < 2; ++k) \
;     dst[n][k] = *reinterpret_cast<const bf16x8*>((const char*)shm + boff + (((b) * 2 + (h)) * 16384 + n * 2048 + k * 1024))
; #define MMA(ai, bj, At, Bt_) do { __builtin_amdgcn_s_setprio(1); \
;     _Pragma("unroll") for (int m = 0; m < 4; ++m) _Pragma("unroll") for (int n = 0; n < 2; ++n) _Pragma("unroll") for (int k = 0; k < 2; ++k) \
;       acc[ai][bj][m][n] = mfma16(At[m][k], Bt_[n][k], acc[ai][bj][m][n]); \
;     __builtin_amdgcn_s_setprio(0); } while (0)
; #define WAIT_V(n) asm volatile("s_waitcnt vmcnt(" #n ")" ::: "memory")
; #define WAIT_L(n) asm volatile("s_waitcnt lgkmcnt(" #n ")" ::: "memory")
; #define BAR __builtin_amdgcn_s_barrier()
; #define SCHED __builtin_amdgcn_sched_barrier(0)
; template <class Epi>
; __device__ __forceinline__ void gemm_phase(const bfr* __restrict__ A, int lda, const bfr* __restrict__ Bt, int K,
;                                            int nM, int nN, const Epi& epi, bfr* shm, int wv, int nMfull, int ksplit) {
;     ...
;       LDB(B0, 0, 0); SCHED; LDA(At, 0, 0); STAGE(SA(1, 1), Ak, brow + G_HALF, t + 1);
;       WAIT_L(8); BAR; WAIT_L(0); MMA(0, 0, At, B0); BAR; SCHED;
;       LDB(B1, 0, 1); STAGE(SB(0, 0), Bk, bcol, t + 2);
;       BAR; WAIT_L(0); MMA(0, 1, At, B1); BAR;
;       LDA(At, 0, 1); STAGE(SA(0, 0), Ak, brow, t + 2);
;       BAR; WAIT_L(0); MMA(1, 0, At, B0); BAR; SCHED;
;       STAGE(SB(0, 1), Bk, bcol + G_HALF, t + 2);
;       WAIT_V(6); BAR; MMA(1, 1, At, B1); BAR;
.LBB0_523:
	ds_read_b128 v[138:141], v179
	ds_read_b128 v[142:145], v179 offset:1024
	ds_read_b128 v[146:149], v179 offset:2048
	ds_read_b128 v[150:153], v179 offset:3072
	ds_read_b128 v[154:157], v178
	ds_read_b128 v[158:161], v178 offset:1024
	ds_read_b128 v[162:165], v178 offset:2048
	ds_read_b128 v[166:169], v178 offset:3072
	ds_read_b128 v[170:173], v178 offset:4096
	ds_read_b128 v[174:177], v178 offset:5120
	ds_read_b128 v[184:187], v178 offset:6144
	ds_read_b128 v[188:191], v178 offset:7168
	ds_read_b128 v[192:195], v179 offset:16384
	ds_read_b128 v[196:199], v179 offset:17408
	ds_read_b128 v[200:203], v179 offset:18432
	ds_read_b128 v[204:207], v179 offset:19456
	v_lshl_add_u64 v[208:209], s[44:45], 0, v[136:137]
	v_lshl_add_u64 v[210:211], s[42:43], 0, v[136:137]
	s_mov_b32 m0, s92
	s_mov_b64 s[52:53], 0x40080
	v_lshl_add_u64 v[214:215], v[208:209], 0, s[52:53]
	global_load_lds_dwordx4 v[214:215], off
	s_mov_b32 m0, s93
	s_mov_b64 s[52:53], 0x60080
	v_lshl_add_u64 v[216:217], v[208:209], 0, s[52:53]
	global_load_lds_dwordx4 v[216:217], off
	s_waitcnt lgkmcnt(0)
	s_barrier
	s_setprio 1
	v_mfma_f32_16x16x32_bf16 v[124:127], v[154:157], v[138:141], v[124:127]
	v_mfma_f32_16x16x32_bf16 v[120:123], v[154:157], v[146:149], v[120:123]
	v_mfma_f32_16x16x32_bf16 v[116:119], v[162:165], v[138:141], v[116:119]
	v_mfma_f32_16x16x32_bf16 v[112:115], v[162:165], v[146:149], v[112:115]
	v_mfma_f32_16x16x32_bf16 v[108:111], v[170:173], v[138:141], v[108:111]
	v_mfma_f32_16x16x32_bf16 v[104:107], v[170:173], v[146:149], v[104:107]
	v_mfma_f32_16x16x32_bf16 v[100:103], v[184:187], v[138:141], v[100:103]
	v_mfma_f32_16x16x32_bf16 v[96:99], v[184:187], v[146:149], v[96:99]
	v_mfma_f32_16x16x32_bf16 v[124:127], v[158:161], v[142:145], v[124:127]
	v_mfma_f32_16x16x32_bf16 v[120:123], v[158:161], v[150:153], v[120:123]
	v_mfma_f32_16x16x32_bf16 v[116:119], v[166:169], v[142:145], v[116:119]
	v_mfma_f32_16x16x32_bf16 v[112:115], v[166:169], v[150:153], v[112:115]
	v_mfma_f32_16x16x32_bf16 v[108:111], v[174:177], v[142:145], v[108:111]
	v_mfma_f32_16x16x32_bf16 v[104:107], v[174:177], v[150:153], v[104:107]
	v_mfma_f32_16x16x32_bf16 v[100:103], v[188:191], v[142:145], v[100:103]
	v_mfma_f32_16x16x32_bf16 v[96:99], v[188:191], v[150:153], v[96:99]
	v_mfma_f32_16x16x32_bf16 v[92:95], v[154:157], v[192:195], v[92:95]
	v_mfma_f32_16x16x32_bf16 v[88:91], v[154:157], v[200:203], v[88:91]
	v_mfma_f32_16x16x32_bf16 v[84:87], v[162:165], v[192:195], v[84:87]
	v_mfma_f32_16x16x32_bf16 v[80:83], v[162:165], v[200:203], v[80:83]
	v_mfma_f32_16x16x32_bf16 v[76:79], v[170:173], v[192:195], v[76:79]
	v_mfma_f32_16x16x32_bf16 v[72:75], v[170:173], v[200:203], v[72:75]
	v_mfma_f32_16x16x32_bf16 v[68:71], v[184:187], v[192:195], v[68:71]
	v_mfma_f32_16x16x32_bf16 v[64:67], v[184:187], v[200:203], v[64:67]
	v_mfma_f32_16x16x32_bf16 v[92:95], v[158:161], v[196:199], v[92:95]
	v_mfma_f32_16x16x32_bf16 v[88:91], v[158:161], v[204:207], v[88:91]
	v_mfma_f32_16x16x32_bf16 v[84:87], v[166:169], v[196:199], v[84:87]
	v_mfma_f32_16x16x32_bf16 v[80:83], v[166:169], v[204:207], v[80:83]
	v_mfma_f32_16x16x32_bf16 v[76:79], v[174:177], v[196:199], v[76:79]
	v_mfma_f32_16x16x32_bf16 v[72:75], v[174:177], v[204:207], v[72:75]
	v_mfma_f32_16x16x32_bf16 v[68:71], v[188:191], v[196:199], v[68:71]
	v_mfma_f32_16x16x32_bf16 v[64:67], v[188:191], v[204:207], v[64:67]
	s_setprio 0
	s_barrier
	ds_read_b128 v[154:157], v178 offset:16384
	ds_read_b128 v[158:161], v178 offset:17408
	ds_read_b128 v[162:165], v178 offset:18432
	ds_read_b128 v[166:169], v178 offset:19456
	ds_read_b128 v[170:173], v178 offset:20480
	ds_read_b128 v[174:177], v178 offset:21504
	ds_read_b128 v[184:187], v178 offset:22528
	ds_read_b128 v[188:191], v178 offset:23552
	s_mov_b32 m0, s94
	v_lshl_add_u64 v[218:219], v[210:211], 0, s[16:17]
	global_load_lds_dwordx4 v[218:219], off
	s_mov_b32 m0, s95
	v_lshl_add_u64 v[214:215], v[210:211], 0, s[18:19]
	global_load_lds_dwordx4 v[214:215], off
	s_mov_b32 m0, s91
	v_lshl_add_u64 v[216:217], v[208:209], 0, s[16:17]
	global_load_lds_dwordx4 v[216:217], off
	s_mov_b32 m0, s96
	v_lshl_add_u64 v[218:219], v[208:209], 0, s[18:19]
	global_load_lds_dwordx4 v[218:219], off
	s_mov_b32 m0, s97
	v_lshl_add_u64 v[214:215], v[210:211], 0, s[20:21]
	global_load_lds_dwordx4 v[214:215], off
	s_mov_b32 m0, s34
	v_lshl_add_u64 v[216:217], v[210:211], 0, s[22:23]
	global_load_lds_dwordx4 v[216:217], off
	s_waitcnt vmcnt(6)
	s_waitcnt lgkmcnt(0)
	s_barrier
	s_setprio 1
	v_mfma_f32_16x16x32_bf16 v[60:63], v[154:157], v[138:141], v[60:63]
	v_mfma_f32_16x16x32_bf16 v[56:59], v[154:157], v[146:149], v[56:59]
	v_mfma_f32_16x16x32_bf16 v[52:55], v[162:165], v[138:141], v[52:55]
	v_mfma_f32_16x16x32_bf16 v[48:51], v[162:165], v[146:149], v[48:51]
	v_mfma_f32_16x16x32_bf16 v[44:47], v[170:173], v[138:141], v[44:47]
	v_mfma_f32_16x16x32_bf16 v[40:43], v[170:173], v[146:149], v[40:43]
	v_mfma_f32_16x16x32_bf16 v[36:39], v[184:187], v[138:141], v[36:39]
	v_mfma_f32_16x16x32_bf16 v[32:35], v[184:187], v[146:149], v[32:35]
	v_mfma_f32_16x16x32_bf16 v[60:63], v[158:161], v[142:145], v[60:63]
	v_mfma_f32_16x16x32_bf16 v[56:59], v[158:161], v[150:153], v[56:59]
	v_mfma_f32_16x16x32_bf16 v[52:55], v[166:169], v[142:145], v[52:55]
	v_mfma_f32_16x16x32_bf16 v[48:51], v[166:169], v[150:153], v[48:51]
	v_mfma_f32_16x16x32_bf16 v[44:47], v[174:177], v[142:145], v[44:47]
	v_mfma_f32_16x16x32_bf16 v[40:43], v[174:177], v[150:153], v[40:43]
	v_mfma_f32_16x16x32_bf16 v[36:39], v[188:191], v[142:145], v[36:39]
	v_mfma_f32_16x16x32_bf16 v[32:35], v[188:191], v[150:153], v[32:35]
	v_mfma_f32_16x16x32_bf16 v[28:31], v[154:157], v[192:195], v[28:31]
	v_mfma_f32_16x16x32_bf16 v[24:27], v[154:157], v[200:203], v[24:27]
	v_mfma_f32_16x16x32_bf16 v[20:23], v[162:165], v[192:195], v[20:23]
	v_mfma_f32_16x16x32_bf16 v[16:19], v[162:165], v[200:203], v[16:19]
	v_mfma_f32_16x16x32_bf16 v[12:15], v[170:173], v[192:195], v[12:15]
	v_mfma_f32_16x16x32_bf16 v[8:11], v[170:173], v[200:203], v[8:11]
	v_mfma_f32_16x16x32_bf16 v[4:7], v[184:187], v[192:195], v[4:7]
	v_mfma_f32_16x16x32_bf16 v[0:3], v[184:187], v[200:203], v[0:3]
	v_mfma_f32_16x16x32_bf16 v[28:31], v[158:161], v[196:199], v[28:31]
	v_mfma_f32_16x16x32_bf16 v[24:27], v[158:161], v[204:207], v[24:27]
	v_mfma_f32_16x16x32_bf16 v[20:23], v[166:169], v[196:199], v[20:23]
	v_mfma_f32_16x16x32_bf16 v[16:19], v[166:169], v[204:207], v[16:19]
	v_mfma_f32_16x16x32_bf16 v[12:15], v[174:177], v[196:199], v[12:15]
	v_mfma_f32_16x16x32_bf16 v[8:11], v[174:177], v[204:207], v[8:11]
	v_mfma_f32_16x16x32_bf16 v[4:7], v[188:191], v[196:199], v[4:7]
	v_mfma_f32_16x16x32_bf16 v[0:3], v[188:191], v[204:207], v[0:3]
	s_setprio 0
	s_barrier
; #define STAGE(P, BASE, br, kt) do { const char* _g = (const char*)((BASE) + (size_t)(br) * K + (size_t)(kt) * G_BK); \
;     _Pragma("unroll") for (int _i = 0; _i < 2; ++_i) { \
;       __builtin_amdgcn_global_load_lds((const unsigned*)(_g + (size_t)_i * 128 * K + sg_off), (unsigned*)((char*)(P) + wid * 1024 + _i * 8192), 16, 0, 0); } } while (0)
; #define LDA(dst, b, h) _Pragma("unroll") for (int m = 0; m < 4; ++m) _Pragma("unroll") for (int k = 0; k < 2; ++k) \
;     dst[m][k] = *reinterpret_cast<const bf16x8*>((const char*)shm + aoff + (((b) * 2 + (h)) * 16384 + m * 2048 + k * 1024))
; #define LDB(dst, b, h) _Pragma("unroll") for (int n = 0; n < 2; ++n) _Pragma("unroll") for (int k = 0; k < 2; ++k) \
;     dst[n][k] = *reinterpret_cast<const bf16x8*>((const char*)shm + boff + (((b) * 2 + (h)) * 16384 + n * 2048 + k * 1024))
; #define MMA(ai, bj, At, Bt_) do { __builtin_amdgcn_s_setprio(1); \
;     _Pragma("unroll") for (int m = 0; m < 4; ++m) _Pragma("unroll") for (int n = 0; n < 2; ++n) _Pragma("unroll") for (int k = 0; k < 2; ++k) \
;       acc[ai][bj][m][n] = mfma16(At[m][k], Bt_[n][k], acc[ai][bj][m][n]); \
;     __builtin_amdgcn_s_setprio(0); } while (0)
; #define WAIT_V(n) asm volatile("s_waitcnt vmcnt(" #n ")" ::: "memory")
; #define WAIT_L(n) asm volatile("s_waitcnt lgkmcnt(" #n ")" ::: "memory")
; #define BAR __builtin_amdgcn_s_barrier()
; #define SCHED __builtin_amdgcn_sched_barrier(0)
; template <class Epi>
; __device__ __forceinline__ void gemm_phase(const bfr* __restrict__ A, int lda, const bfr* __restrict__ Bt, int K,
;                                            int nM, int nN, const Epi& epi, bfr* shm, int wv, int nMfull, int ksplit) {
;     ...
;       LDB(B0, 1, 0); SCHED; LDA(At, 1, 0); STAGE(SA(0, 1), Ak, brow + G_HALF, t + 2);
;       WAIT_L(8); BAR; WAIT_L(0); MMA(0, 0, At, B0); BAR; SCHED;
;       LDB(B1, 1, 1); STAGE(SB(1, 0), Bk, bcol, t + 3);
;       BAR; WAIT_L(0); MMA(0, 1, At, B1); BAR;
;       LDA(At, 1, 1); STAGE(SA(1, 0), Ak, brow, t + 3);
;       BAR; WAIT_L(0); MMA(1, 0, At, B0); BAR; SCHED;
;       STAGE(SB(1, 1), Bk, bcol + G_HALF, t + 3);
;       WAIT_V(6); BAR; MMA(1, 1, At, B1); BAR;
;     }
	ds_read_b128 v[138:141], v179 offset:32768
	ds_read_b128 v[142:145], v179 offset:33792
	ds_read_b128 v[146:149], v179 offset:34816
	ds_read_b128 v[150:153], v179 offset:35840
	ds_read_b128 v[154:157], v178 offset:32768
	ds_read_b128 v[158:161], v178 offset:33792
	ds_read_b128 v[162:165], v178 offset:34816
	ds_read_b128 v[166:169], v178 offset:35840
	ds_read_b128 v[170:173], v178 offset:36864
	ds_read_b128 v[174:177], v178 offset:37888
	ds_read_b128 v[184:187], v178 offset:38912
	ds_read_b128 v[188:191], v178 offset:39936
	ds_read_b128 v[192:195], v179 offset:49152
	ds_read_b128 v[196:199], v179 offset:50176
	ds_read_b128 v[200:203], v179 offset:51200
	ds_read_b128 v[204:207], v179 offset:52224
	s_mov_b32 m0, s35
	v_lshl_add_u64 v[218:219], v[208:209], 0, s[20:21]
	global_load_lds_dwordx4 v[218:219], off
	s_mov_b32 m0, s36
	v_lshl_add_u64 v[214:215], v[208:209], 0, s[22:23]
	global_load_lds_dwordx4 v[214:215], off
	s_waitcnt lgkmcnt(0)
	s_barrier
	s_setprio 1
	v_mfma_f32_16x16x32_bf16 v[124:127], v[154:157], v[138:141], v[124:127]
	v_mfma_f32_16x16x32_bf16 v[120:123], v[154:157], v[146:149], v[120:123]
	v_mfma_f32_16x16x32_bf16 v[116:119], v[162:165], v[138:141], v[116:119]
	v_mfma_f32_16x16x32_bf16 v[112:115], v[162:165], v[146:149], v[112:115]
	v_mfma_f32_16x16x32_bf16 v[108:111], v[170:173], v[138:141], v[108:111]
	v_mfma_f32_16x16x32_bf16 v[104:107], v[170:173], v[146:149], v[104:107]
	v_mfma_f32_16x16x32_bf16 v[100:103], v[184:187], v[138:141], v[100:103]
	v_mfma_f32_16x16x32_bf16 v[96:99], v[184:187], v[146:149], v[96:99]
	v_mfma_f32_16x16x32_bf16 v[124:127], v[158:161], v[142:145], v[124:127]
	v_mfma_f32_16x16x32_bf16 v[120:123], v[158:161], v[150:153], v[120:123]
	v_mfma_f32_16x16x32_bf16 v[116:119], v[166:169], v[142:145], v[116:119]
	v_mfma_f32_16x16x32_bf16 v[112:115], v[166:169], v[150:153], v[112:115]
	v_mfma_f32_16x16x32_bf16 v[108:111], v[174:177], v[142:145], v[108:111]
	v_mfma_f32_16x16x32_bf16 v[104:107], v[174:177], v[150:153], v[104:107]
	v_mfma_f32_16x16x32_bf16 v[100:103], v[188:191], v[142:145], v[100:103]
	v_mfma_f32_16x16x32_bf16 v[96:99], v[188:191], v[150:153], v[96:99]
	v_mfma_f32_16x16x32_bf16 v[92:95], v[154:157], v[192:195], v[92:95]
	v_mfma_f32_16x16x32_bf16 v[88:91], v[154:157], v[200:203], v[88:91]
	v_mfma_f32_16x16x32_bf16 v[84:87], v[162:165], v[192:195], v[84:87]
	v_mfma_f32_16x16x32_bf16 v[80:83], v[162:165], v[200:203], v[80:83]
	v_mfma_f32_16x16x32_bf16 v[76:79], v[170:173], v[192:195], v[76:79]
	v_mfma_f32_16x16x32_bf16 v[72:75], v[170:173], v[200:203], v[72:75]
	v_mfma_f32_16x16x32_bf16 v[68:71], v[184:187], v[192:195], v[68:71]
	v_mfma_f32_16x16x32_bf16 v[64:67], v[184:187], v[200:203], v[64:67]
	v_mfma_f32_16x16x32_bf16 v[92:95], v[158:161], v[196:199], v[92:95]
	v_mfma_f32_16x16x32_bf16 v[88:91], v[158:161], v[204:207], v[88:91]
	v_mfma_f32_16x16x32_bf16 v[84:87], v[166:169], v[196:199], v[84:87]
	v_mfma_f32_16x16x32_bf16 v[80:83], v[166:169], v[204:207], v[80:83]
	v_mfma_f32_16x16x32_bf16 v[76:79], v[174:177], v[196:199], v[76:79]
	v_mfma_f32_16x16x32_bf16 v[72:75], v[174:177], v[204:207], v[72:75]
	v_mfma_f32_16x16x32_bf16 v[68:71], v[188:191], v[196:199], v[68:71]
	v_mfma_f32_16x16x32_bf16 v[64:67], v[188:191], v[204:207], v[64:67]
	s_setprio 0
	s_barrier
	ds_read_b128 v[154:157], v178 offset:49152
	ds_read_b128 v[158:161], v178 offset:50176
	ds_read_b128 v[162:165], v178 offset:51200
	ds_read_b128 v[166:169], v178 offset:52224
	ds_read_b128 v[170:173], v178 offset:53248
	ds_read_b128 v[174:177], v178 offset:54272
	ds_read_b128 v[184:187], v178 offset:55296
	ds_read_b128 v[188:191], v178 offset:56320
	s_mov_b32 m0, s37
	v_lshl_add_u64 v[216:217], v[210:211], 0, s[24:25]
	global_load_lds_dwordx4 v[216:217], off
	s_mov_b32 m0, s12
	v_lshl_add_u64 v[218:219], v[210:211], 0, s[26:27]
	global_load_lds_dwordx4 v[218:219], off
	s_mov_b32 m0, s13
	v_lshl_add_u64 v[214:215], v[208:209], 0, s[24:25]
	global_load_lds_dwordx4 v[214:215], off
	s_mov_b32 m0, s28
	v_lshl_add_u64 v[216:217], v[208:209], 0, s[26:27]
	global_load_lds_dwordx4 v[216:217], off
	s_mov_b32 m0, s29
	s_mov_b64 s[52:53], 0x40180
	v_lshl_add_u64 v[218:219], v[210:211], 0, s[52:53]
	global_load_lds_dwordx4 v[218:219], off
	s_mov_b32 m0, s30
	s_mov_b64 s[52:53], 0x60180
	v_lshl_add_u64 v[214:215], v[210:211], 0, s[52:53]
	global_load_lds_dwordx4 v[214:215], off
	s_waitcnt vmcnt(6)
	s_waitcnt lgkmcnt(0)
	s_barrier
	s_setprio 1
	v_mfma_f32_16x16x32_bf16 v[60:63], v[154:157], v[138:141], v[60:63]
	v_mfma_f32_16x16x32_bf16 v[56:59], v[154:157], v[146:149], v[56:59]
	v_mfma_f32_16x16x32_bf16 v[52:55], v[162:165], v[138:141], v[52:55]
	v_mfma_f32_16x16x32_bf16 v[48:51], v[162:165], v[146:149], v[48:51]
	v_mfma_f32_16x16x32_bf16 v[44:47], v[170:173], v[138:141], v[44:47]
	v_mfma_f32_16x16x32_bf16 v[40:43], v[170:173], v[146:149], v[40:43]
	v_mfma_f32_16x16x32_bf16 v[36:39], v[184:187], v[138:141], v[36:39]
	v_mfma_f32_16x16x32_bf16 v[32:35], v[184:187], v[146:149], v[32:35]
	v_mfma_f32_16x16x32_bf16 v[60:63], v[158:161], v[142:145], v[60:63]
	v_mfma_f32_16x16x32_bf16 v[56:59], v[158:161], v[150:153], v[56:59]
	v_mfma_f32_16x16x32_bf16 v[52:55], v[166:169], v[142:145], v[52:55]
	v_mfma_f32_16x16x32_bf16 v[48:51], v[166:169], v[150:153], v[48:51]
	v_mfma_f32_16x16x32_bf16 v[44:47], v[174:177], v[142:145], v[44:47]
	v_mfma_f32_16x16x32_bf16 v[40:43], v[174:177], v[150:153], v[40:43]
	v_mfma_f32_16x16x32_bf16 v[36:39], v[188:191], v[142:145], v[36:39]
	v_mfma_f32_16x16x32_bf16 v[32:35], v[188:191], v[150:153], v[32:35]
	v_mfma_f32_16x16x32_bf16 v[28:31], v[154:157], v[192:195], v[28:31]
	v_mfma_f32_16x16x32_bf16 v[24:27], v[154:157], v[200:203], v[24:27]
	v_mfma_f32_16x16x32_bf16 v[20:23], v[162:165], v[192:195], v[20:23]
	v_mfma_f32_16x16x32_bf16 v[16:19], v[162:165], v[200:203], v[16:19]
	v_mfma_f32_16x16x32_bf16 v[12:15], v[170:173], v[192:195], v[12:15]
	v_mfma_f32_16x16x32_bf16 v[8:11], v[170:173], v[200:203], v[8:11]
	v_mfma_f32_16x16x32_bf16 v[4:7], v[184:187], v[192:195], v[4:7]
	v_mfma_f32_16x16x32_bf16 v[0:3], v[184:187], v[200:203], v[0:3]
	v_mfma_f32_16x16x32_bf16 v[28:31], v[158:161], v[196:199], v[28:31]
	v_mfma_f32_16x16x32_bf16 v[24:27], v[158:161], v[204:207], v[24:27]
	v_mfma_f32_16x16x32_bf16 v[20:23], v[166:169], v[196:199], v[20:23]
	v_mfma_f32_16x16x32_bf16 v[16:19], v[166:169], v[204:207], v[16:19]
	v_mfma_f32_16x16x32_bf16 v[12:15], v[174:177], v[196:199], v[12:15]
	v_mfma_f32_16x16x32_bf16 v[8:11], v[174:177], v[204:207], v[8:11]
	v_mfma_f32_16x16x32_bf16 v[4:7], v[188:191], v[196:199], v[4:7]
	v_mfma_f32_16x16x32_bf16 v[0:3], v[188:191], v[204:207], v[0:3]
	s_setprio 0
	s_add_i32 s41, s41, 2
	s_add_u32 s42, s42, 0x100
	s_addc_u32 s43, s43, 0
	s_add_u32 s44, s44, 0x100
	s_addc_u32 s45, s45, 0
	s_cmp_ge_i32 s41, s46
	s_barrier
	s_cbranch_scc0 .LBB0_523

; #define STAGE(P, BASE, br, kt) do { const char* _g = (const char*)((BASE) + (size_t)(br) * K + (size_t)(kt) * G_BK); \
;     _Pragma("unroll") for (int _i = 0; _i < 2; ++_i) { \
;       __builtin_amdgcn_global_load_lds((const unsigned*)(_g + (size_t)_i * 128 * K + sg_off), (unsigned*)((char*)(P) + wid * 1024 + _i * 8192), 16, 0, 0); } } while (0)
; #define LDA(dst, b, h) _Pragma("unroll") for (int m = 0; m < 4; ++m) _Pragma("unroll") for (int k = 0; k < 2; ++k) \
;     dst[m][k] = *reinterpret_cast<const bf16x8*>((const char*)shm + aoff + (((b) * 2 + (h)) * 16384 + m * 2048 + k * 1024))
; #define LDB(dst, b, h) _Pragma("unroll") for (int n = 0; n < 2; ++n) _Pragma("unroll") for (int k = 0; k < 2; ++k) \
;     dst[n][k] = *reinterpret_cast<const bf16x8*>((const char*)shm + boff + (((b) * 2 + (h)) * 16384 + n * 2048 + k * 1024))
; #define MMA(ai, bj, At, Bt_) do { __builtin_amdgcn_s_setprio(1); \
;     _Pragma("unroll") for (int m = 0; m < 4; ++m) _Pragma("unroll") for (int n = 0; n < 2; ++n) _Pragma("unroll") for (int k = 0; k < 2; ++k) \
;       acc[ai][bj][m][n] = mfma16(At[m][k], Bt_[n][k], acc[ai][bj][m][n]); \
;     __builtin_amdgcn_s_setprio(0); } while (0)
; #define WAIT_V(n) asm volatile("s_waitcnt vmcnt(" #n ")" ::: "memory")
; #define WAIT_L(n) asm volatile("s_waitcnt lgkmcnt(" #n ")" ::: "memory")
; #define BAR __builtin_amdgcn_s_barrier()
; #define SCHED __builtin_amdgcn_sched_barrier(0)
; template <class Epi>
; __device__ __forceinline__ void gemm_phase(const bfr* __restrict__ A, int lda, const bfr* __restrict__ Bt, int K,
;                                            int nM, int nN, const Epi& epi, bfr* shm, int wv, int nMfull, int ksplit) {
;     ...
;       LDB(B0, 0, 0); SCHED; LDA(At, 0, 0); STAGE(SA(1, 1), Ak, brow + G_HALF, t + 1);
;       WAIT_L(8); BAR; WAIT_L(0); MMA(0, 0, At, B0); BAR; SCHED;
;       LDB(B1, 0, 1); STAGE(SB(0, 0), Bk, bcol, t + 2);
;       BAR; WAIT_L(0); MMA(0, 1, At, B1); BAR;
;       LDA(At, 0, 1); STAGE(SA(0, 0), Ak, brow, t + 2);
;       BAR; WAIT_L(0); MMA(1, 0, At, B0); BAR; SCHED;
;       STAGE(SB(0, 1), Bk, bcol + G_HALF, t + 2);
;       WAIT_V(6); BAR; MMA(1, 1, At, B1); BAR;
.LBB0_673:
	ds_read_b128 v[138:141], v169
	ds_read_b128 v[142:145], v169 offset:1024
	ds_read_b128 v[146:149], v169 offset:2048
	ds_read_b128 v[150:153], v169 offset:3072
	ds_read_b128 v[154:157], v129
	ds_read_b128 v[158:161], v129 offset:1024
	ds_read_b128 v[162:165], v129 offset:2048
	ds_read_b128 v[172:175], v129 offset:3072
	ds_read_b128 v[180:183], v129 offset:4096
	ds_read_b128 v[184:187], v129 offset:5120
	ds_read_b128 v[188:191], v129 offset:6144
	ds_read_b128 v[192:195], v129 offset:7168
	ds_read_b128 v[196:199], v169 offset:16384
	ds_read_b128 v[200:203], v169 offset:17408
	ds_read_b128 v[204:207], v169 offset:18432
	ds_read_b128 v[208:211], v169 offset:19456
	v_lshl_add_u64 v[166:167], s[24:25], 0, v[136:137]
	v_lshl_add_u64 v[176:177], s[6:7], 0, v[136:137]
	s_mov_b32 m0, s52
	s_mov_b64 s[26:27], 0x40080
	v_lshl_add_u64 v[214:215], v[166:167], 0, s[26:27]
	global_load_lds_dwordx4 v[214:215], off
	s_mov_b32 m0, s53
	s_mov_b64 s[26:27], 0x60080
	v_lshl_add_u64 v[216:217], v[166:167], 0, s[26:27]
	global_load_lds_dwordx4 v[216:217], off
	s_waitcnt lgkmcnt(0)
	s_barrier
	s_setprio 1
	v_mfma_f32_16x16x32_bf16 v[124:127], v[154:157], v[138:141], v[124:127]
	v_mfma_f32_16x16x32_bf16 v[120:123], v[154:157], v[146:149], v[120:123]
	v_mfma_f32_16x16x32_bf16 v[116:119], v[162:165], v[138:141], v[116:119]
	v_mfma_f32_16x16x32_bf16 v[112:115], v[162:165], v[146:149], v[112:115]
	v_mfma_f32_16x16x32_bf16 v[108:111], v[180:183], v[138:141], v[108:111]
	v_mfma_f32_16x16x32_bf16 v[104:107], v[180:183], v[146:149], v[104:107]
	v_mfma_f32_16x16x32_bf16 v[100:103], v[188:191], v[138:141], v[100:103]
	v_mfma_f32_16x16x32_bf16 v[96:99], v[188:191], v[146:149], v[96:99]
	v_mfma_f32_16x16x32_bf16 v[124:127], v[158:161], v[142:145], v[124:127]
	v_mfma_f32_16x16x32_bf16 v[120:123], v[158:161], v[150:153], v[120:123]
	v_mfma_f32_16x16x32_bf16 v[116:119], v[172:175], v[142:145], v[116:119]
	v_mfma_f32_16x16x32_bf16 v[112:115], v[172:175], v[150:153], v[112:115]
	v_mfma_f32_16x16x32_bf16 v[108:111], v[184:187], v[142:145], v[108:111]
	v_mfma_f32_16x16x32_bf16 v[104:107], v[184:187], v[150:153], v[104:107]
	v_mfma_f32_16x16x32_bf16 v[100:103], v[192:195], v[142:145], v[100:103]
	v_mfma_f32_16x16x32_bf16 v[96:99], v[192:195], v[150:153], v[96:99]
	v_mfma_f32_16x16x32_bf16 v[92:95], v[154:157], v[196:199], v[92:95]
	v_mfma_f32_16x16x32_bf16 v[88:91], v[154:157], v[204:207], v[88:91]
	v_mfma_f32_16x16x32_bf16 v[84:87], v[162:165], v[196:199], v[84:87]
	v_mfma_f32_16x16x32_bf16 v[80:83], v[162:165], v[204:207], v[80:83]
	v_mfma_f32_16x16x32_bf16 v[76:79], v[180:183], v[196:199], v[76:79]
	v_mfma_f32_16x16x32_bf16 v[72:75], v[180:183], v[204:207], v[72:75]
	v_mfma_f32_16x16x32_bf16 v[68:71], v[188:191], v[196:199], v[68:71]
	v_mfma_f32_16x16x32_bf16 v[64:67], v[188:191], v[204:207], v[64:67]
	v_mfma_f32_16x16x32_bf16 v[92:95], v[158:161], v[200:203], v[92:95]
	v_mfma_f32_16x16x32_bf16 v[88:91], v[158:161], v[208:211], v[88:91]
	v_mfma_f32_16x16x32_bf16 v[84:87], v[172:175], v[200:203], v[84:87]
	v_mfma_f32_16x16x32_bf16 v[80:83], v[172:175], v[208:211], v[80:83]
	v_mfma_f32_16x16x32_bf16 v[76:79], v[184:187], v[200:203], v[76:79]
	v_mfma_f32_16x16x32_bf16 v[72:75], v[184:187], v[208:211], v[72:75]
	v_mfma_f32_16x16x32_bf16 v[68:71], v[192:195], v[200:203], v[68:71]
	v_mfma_f32_16x16x32_bf16 v[64:67], v[192:195], v[208:211], v[64:67]
	s_setprio 0
	s_barrier
	ds_read_b128 v[154:157], v129 offset:16384
	ds_read_b128 v[158:161], v129 offset:17408
	ds_read_b128 v[162:165], v129 offset:18432
	ds_read_b128 v[172:175], v129 offset:19456
	ds_read_b128 v[180:183], v129 offset:20480
	ds_read_b128 v[184:187], v129 offset:21504
	ds_read_b128 v[188:191], v129 offset:22528
	ds_read_b128 v[192:195], v129 offset:23552
	s_mov_b32 m0, s39
	s_mov_b64 s[26:27], 0xb00100
	v_lshl_add_u64 v[218:219], v[176:177], 0, s[26:27]
	global_load_lds_dwordx4 v[218:219], off
	s_mov_b32 m0, s40
	s_mov_b64 s[26:27], 0xb20100
	v_lshl_add_u64 v[214:215], v[176:177], 0, s[26:27]
	global_load_lds_dwordx4 v[214:215], off
	s_mov_b32 m0, s38
	s_mov_b64 s[26:27], 0x100
	v_lshl_add_u64 v[216:217], v[166:167], 0, s[26:27]
	global_load_lds_dwordx4 v[216:217], off
	s_mov_b32 m0, s41
	s_mov_b64 s[26:27], 0x20100
	v_lshl_add_u64 v[218:219], v[166:167], 0, s[26:27]
	global_load_lds_dwordx4 v[218:219], off
	s_mov_b32 m0, s42
	s_mov_b64 s[26:27], 0xb40100
	v_lshl_add_u64 v[214:215], v[176:177], 0, s[26:27]
	global_load_lds_dwordx4 v[214:215], off
	s_mov_b32 m0, s43
	s_mov_b64 s[26:27], 0xb60100
	v_lshl_add_u64 v[216:217], v[176:177], 0, s[26:27]
	global_load_lds_dwordx4 v[216:217], off
	s_waitcnt vmcnt(6)
	s_waitcnt lgkmcnt(0)
	s_barrier
; #define STAGE(P, BASE, br, kt) do { const char* _g = (const char*)((BASE) + (size_t)(br) * K + (size_t)(kt) * G_BK); \
;     _Pragma("unroll") for (int _i = 0; _i < 2; ++_i) { \
;       __builtin_amdgcn_global_load_lds((const unsigned*)(_g + (size_t)_i * 128 * K + sg_off), (unsigned*)((char*)(P) + wid * 1024 + _i * 8192), 16, 0, 0); } } while (0)
; #define LDA(dst, b, h) _Pragma("unroll") for (int m = 0; m < 4; ++m) _Pragma("unroll") for (int k = 0; k < 2; ++k) \
;     dst[m][k] = *reinterpret_cast<const bf16x8*>((const char*)shm + aoff + (((b) * 2 + (h)) * 16384 + m * 2048 + k * 1024))
; #define LDB(dst, b, h) _Pragma("unroll") for (int n = 0; n < 2; ++n) _Pragma("unroll") for (int k = 0; k < 2; ++k) \
;     dst[n][k] = *reinterpret_cast<const bf16x8*>((const char*)shm + boff + (((b) * 2 + (h)) * 16384 + n * 2048 + k * 1024))
; #define MMA(ai, bj, At, Bt_) do { __builtin_amdgcn_s_setprio(1); \
;     _Pragma("unroll") for (int m = 0; m < 4; ++m) _Pragma("unroll") for (int n = 0; n < 2; ++n) _Pragma("unroll") for (int k = 0; k < 2; ++k) \
;       acc[ai][bj][m][n] = mfma16(At[m][k], Bt_[n][k], acc[ai][bj][m][n]); \
;     __builtin_amdgcn_s_setprio(0); } while (0)
; #define WAIT_V(n) asm volatile("s_waitcnt vmcnt(" #n ")" ::: "memory")
; #define WAIT_L(n) asm volatile("s_waitcnt lgkmcnt(" #n ")" ::: "memory")
; #define BAR __builtin_amdgcn_s_barrier()
; #define SCHED __builtin_amdgcn_sched_barrier(0)
; template <class Epi>
; __device__ __forceinline__ void gemm_phase(const bfr* __restrict__ A, int lda, const bfr* __restrict__ Bt, int K,
;                                            int nM, int nN, const Epi& epi, bfr* shm, int wv, int nMfull, int ksplit) {
;     ...
;       BAR; WAIT_L(0); MMA(0, 1, At, B1); BAR;
;       LDA(At, 0, 1); STAGE(SA(0, 0), Ak, brow, t + 2);
;       BAR; WAIT_L(0); MMA(1, 0, At, B0); BAR; SCHED;
;       STAGE(SB(0, 1), Bk, bcol + G_HALF, t + 2);
;       WAIT_V(6); BAR; MMA(1, 1, At, B1); BAR;
;       LDB(B0, 1, 0); SCHED; LDA(At, 1, 0); STAGE(SA(0, 1), Ak, brow + G_HALF, t + 2);
;       WAIT_L(8); BAR; WAIT_L(0); MMA(0, 0, At, B0); BAR; SCHED;
;       LDB(B1, 1, 1); STAGE(SB(1, 0), Bk, bcol, t + 3);
;       BAR; WAIT_L(0); MMA(0, 1, At, B1); BAR;
;       LDA(At, 1, 1); STAGE(SA(1, 0), Ak, brow, t + 3);
;       BAR; WAIT_L(0); MMA(1, 0, At, B0); BAR; SCHED;
	s_setprio 1
	v_mfma_f32_16x16x32_bf16 v[60:63], v[154:157], v[138:141], v[60:63]
	v_mfma_f32_16x16x32_bf16 v[56:59], v[154:157], v[146:149], v[56:59]
	v_mfma_f32_16x16x32_bf16 v[52:55], v[162:165], v[138:141], v[52:55]
	v_mfma_f32_16x16x32_bf16 v[48:51], v[162:165], v[146:149], v[48:51]
	v_mfma_f32_16x16x32_bf16 v[44:47], v[180:183], v[138:141], v[44:47]
	v_mfma_f32_16x16x32_bf16 v[40:43], v[180:183], v[146:149], v[40:43]
	v_mfma_f32_16x16x32_bf16 v[36:39], v[188:191], v[138:141], v[36:39]
	v_mfma_f32_16x16x32_bf16 v[32:35], v[188:191], v[146:149], v[32:35]
	v_mfma_f32_16x16x32_bf16 v[60:63], v[158:161], v[142:145], v[60:63]
	v_mfma_f32_16x16x32_bf16 v[56:59], v[158:161], v[150:153], v[56:59]
	v_mfma_f32_16x16x32_bf16 v[52:55], v[172:175], v[142:145], v[52:55]
	v_mfma_f32_16x16x32_bf16 v[48:51], v[172:175], v[150:153], v[48:51]
	v_mfma_f32_16x16x32_bf16 v[44:47], v[184:187], v[142:145], v[44:47]
	v_mfma_f32_16x16x32_bf16 v[40:43], v[184:187], v[150:153], v[40:43]
	v_mfma_f32_16x16x32_bf16 v[36:39], v[192:195], v[142:145], v[36:39]
	v_mfma_f32_16x16x32_bf16 v[32:35], v[192:195], v[150:153], v[32:35]
	v_mfma_f32_16x16x32_bf16 v[28:31], v[154:157], v[196:199], v[28:31]
	v_mfma_f32_16x16x32_bf16 v[24:27], v[154:157], v[204:207], v[24:27]
	v_mfma_f32_16x16x32_bf16 v[20:23], v[162:165], v[196:199], v[20:23]
	v_mfma_f32_16x16x32_bf16 v[16:19], v[162:165], v[204:207], v[16:19]
	v_mfma_f32_16x16x32_bf16 v[12:15], v[180:183], v[196:199], v[12:15]
	v_mfma_f32_16x16x32_bf16 v[8:11], v[180:183], v[204:207], v[8:11]
	v_mfma_f32_16x16x32_bf16 v[4:7], v[188:191], v[196:199], v[4:7]
	v_mfma_f32_16x16x32_bf16 v[0:3], v[188:191], v[204:207], v[0:3]
	v_mfma_f32_16x16x32_bf16 v[28:31], v[158:161], v[200:203], v[28:31]
	v_mfma_f32_16x16x32_bf16 v[24:27], v[158:161], v[208:211], v[24:27]
	v_mfma_f32_16x16x32_bf16 v[20:23], v[172:175], v[200:203], v[20:23]
	v_mfma_f32_16x16x32_bf16 v[16:19], v[172:175], v[208:211], v[16:19]
	v_mfma_f32_16x16x32_bf16 v[12:15], v[184:187], v[200:203], v[12:15]
	v_mfma_f32_16x16x32_bf16 v[8:11], v[184:187], v[208:211], v[8:11]
	v_mfma_f32_16x16x32_bf16 v[4:7], v[192:195], v[200:203], v[4:7]
	v_mfma_f32_16x16x32_bf16 v[0:3], v[192:195], v[208:211], v[0:3]
	s_setprio 0
	s_barrier
	ds_read_b128 v[138:141], v169 offset:32768
	ds_read_b128 v[142:145], v169 offset:33792
	ds_read_b128 v[146:149], v169 offset:34816
	ds_read_b128 v[150:153], v169 offset:35840
	ds_read_b128 v[154:157], v129 offset:32768
	ds_read_b128 v[158:161], v129 offset:33792
	ds_read_b128 v[162:165], v129 offset:34816
	ds_read_b128 v[172:175], v129 offset:35840
	ds_read_b128 v[180:183], v129 offset:36864
	ds_read_b128 v[184:187], v129 offset:37888
	ds_read_b128 v[188:191], v129 offset:38912
	ds_read_b128 v[192:195], v129 offset:39936
	ds_read_b128 v[196:199], v169 offset:49152
	ds_read_b128 v[200:203], v169 offset:50176
	ds_read_b128 v[204:207], v169 offset:51200
	ds_read_b128 v[208:211], v169 offset:52224
	s_mov_b32 m0, s44
	s_mov_b64 s[26:27], 0x40100
	v_lshl_add_u64 v[218:219], v[166:167], 0, s[26:27]
	global_load_lds_dwordx4 v[218:219], off
	s_mov_b32 m0, s45
	s_mov_b64 s[26:27], 0x60100
	v_lshl_add_u64 v[214:215], v[166:167], 0, s[26:27]
	global_load_lds_dwordx4 v[214:215], off
	s_waitcnt lgkmcnt(0)
	s_barrier
	s_setprio 1
	v_mfma_f32_16x16x32_bf16 v[124:127], v[154:157], v[138:141], v[124:127]
	v_mfma_f32_16x16x32_bf16 v[120:123], v[154:157], v[146:149], v[120:123]
	v_mfma_f32_16x16x32_bf16 v[116:119], v[162:165], v[138:141], v[116:119]
	v_mfma_f32_16x16x32_bf16 v[112:115], v[162:165], v[146:149], v[112:115]
	v_mfma_f32_16x16x32_bf16 v[108:111], v[180:183], v[138:141], v[108:111]
	v_mfma_f32_16x16x32_bf16 v[104:107], v[180:183], v[146:149], v[104:107]
	v_mfma_f32_16x16x32_bf16 v[100:103], v[188:191], v[138:141], v[100:103]
	v_mfma_f32_16x16x32_bf16 v[96:99], v[188:191], v[146:149], v[96:99]
	v_mfma_f32_16x16x32_bf16 v[124:127], v[158:161], v[142:145], v[124:127]
	v_mfma_f32_16x16x32_bf16 v[120:123], v[158:161], v[150:153], v[120:123]
	v_mfma_f32_16x16x32_bf16 v[116:119], v[172:175], v[142:145], v[116:119]
	v_mfma_f32_16x16x32_bf16 v[112:115], v[172:175], v[150:153], v[112:115]
	v_mfma_f32_16x16x32_bf16 v[108:111], v[184:187], v[142:145], v[108:111]
	v_mfma_f32_16x16x32_bf16 v[104:107], v[184:187], v[150:153], v[104:107]
	v_mfma_f32_16x16x32_bf16 v[100:103], v[192:195], v[142:145], v[100:103]
	v_mfma_f32_16x16x32_bf16 v[96:99], v[192:195], v[150:153], v[96:99]
	v_mfma_f32_16x16x32_bf16 v[92:95], v[154:157], v[196:199], v[92:95]
	v_mfma_f32_16x16x32_bf16 v[88:91], v[154:157], v[204:207], v[88:91]
	v_mfma_f32_16x16x32_bf16 v[84:87], v[162:165], v[196:199], v[84:87]
	v_mfma_f32_16x16x32_bf16 v[80:83], v[162:165], v[204:207], v[80:83]
	v_mfma_f32_16x16x32_bf16 v[76:79], v[180:183], v[196:199], v[76:79]
	v_mfma_f32_16x16x32_bf16 v[72:75], v[180:183], v[204:207], v[72:75]
	v_mfma_f32_16x16x32_bf16 v[68:71], v[188:191], v[196:199], v[68:71]
	v_mfma_f32_16x16x32_bf16 v[64:67], v[188:191], v[204:207], v[64:67]
	v_mfma_f32_16x16x32_bf16 v[92:95], v[158:161], v[200:203], v[92:95]
	v_mfma_f32_16x16x32_bf16 v[88:91], v[158:161], v[208:211], v[88:91]
	v_mfma_f32_16x16x32_bf16 v[84:87], v[172:175], v[200:203], v[84:87]
	v_mfma_f32_16x16x32_bf16 v[80:83], v[172:175], v[208:211], v[80:83]
	v_mfma_f32_16x16x32_bf16 v[76:79], v[184:187], v[200:203], v[76:79]
	v_mfma_f32_16x16x32_bf16 v[72:75], v[184:187], v[208:211], v[72:75]
	v_mfma_f32_16x16x32_bf16 v[68:71], v[192:195], v[200:203], v[68:71]
	v_mfma_f32_16x16x32_bf16 v[64:67], v[192:195], v[208:211], v[64:67]
	s_setprio 0
	s_barrier
; #define STAGE(P, BASE, br, kt) do { const char* _g = (const char*)((BASE) + (size_t)(br) * K + (size_t)(kt) * G_BK); \
;     _Pragma("unroll") for (int _i = 0; _i < 2; ++_i) { \
;       __builtin_amdgcn_global_load_lds((const unsigned*)(_g + (size_t)_i * 128 * K + sg_off), (unsigned*)((char*)(P) + wid * 1024 + _i * 8192), 16, 0, 0); } } while (0)
; #define LDA(dst, b, h) _Pragma("unroll") for (int m = 0; m < 4; ++m) _Pragma("unroll") for (int k = 0; k < 2; ++k) \
;     dst[m][k] = *reinterpret_cast<const bf16x8*>((const char*)shm + aoff + (((b) * 2 + (h)) * 16384 + m * 2048 + k * 1024))
; #define MMA(ai, bj, At, Bt_) do { __builtin_amdgcn_s_setprio(1); \
;     _Pragma("unroll") for (int m = 0; m < 4; ++m) _Pragma("unroll") for (int n = 0; n < 2; ++n) _Pragma("unroll") for (int k = 0; k < 2; ++k) \
;       acc[ai][bj][m][n] = mfma16(At[m][k], Bt_[n][k], acc[ai][bj][m][n]); \
;     __builtin_amdgcn_s_setprio(0); } while (0)
; #define WAIT_V(n) asm volatile("s_waitcnt vmcnt(" #n ")" ::: "memory")
; #define WAIT_L(n) asm volatile("s_waitcnt lgkmcnt(" #n ")" ::: "memory")
; #define BAR __builtin_amdgcn_s_barrier()
; #define SCHED __builtin_amdgcn_sched_barrier(0)
; template <class Epi>
; __device__ __forceinline__ void gemm_phase(const bfr* __restrict__ A, int lda, const bfr* __restrict__ Bt, int K,
;                                            int nM, int nN, const Epi& epi, bfr* shm, int wv, int nMfull, int ksplit) {
;     ...
;       LDA(At, 1, 1); STAGE(SA(1, 0), Ak, brow, t + 3);
;       BAR; WAIT_L(0); MMA(1, 0, At, B0); BAR; SCHED;
;       STAGE(SB(1, 1), Bk, bcol + G_HALF, t + 3);
;       WAIT_V(6); BAR; MMA(1, 1, At, B1); BAR;
;     }
	ds_read_b128 v[154:157], v129 offset:49152
	ds_read_b128 v[158:161], v129 offset:50176
	ds_read_b128 v[162:165], v129 offset:51200
	ds_read_b128 v[172:175], v129 offset:52224
	ds_read_b128 v[180:183], v129 offset:53248
	ds_read_b128 v[184:187], v129 offset:54272
	ds_read_b128 v[188:191], v129 offset:55296
	ds_read_b128 v[192:195], v129 offset:56320
	s_mov_b32 m0, s46
	s_mov_b64 s[26:27], 0xb00180
	v_lshl_add_u64 v[216:217], v[176:177], 0, s[26:27]
	global_load_lds_dwordx4 v[216:217], off
	s_mov_b32 m0, s47
	s_mov_b64 s[26:27], 0xb20180
	v_lshl_add_u64 v[218:219], v[176:177], 0, s[26:27]
	global_load_lds_dwordx4 v[218:219], off
	s_mov_b32 m0, s48
	s_mov_b64 s[26:27], 0x180
	v_lshl_add_u64 v[214:215], v[166:167], 0, s[26:27]
	global_load_lds_dwordx4 v[214:215], off
	s_mov_b32 m0, s49
	s_mov_b64 s[26:27], 0x20180
	v_lshl_add_u64 v[216:217], v[166:167], 0, s[26:27]
	global_load_lds_dwordx4 v[216:217], off
	s_mov_b32 m0, s50
	s_mov_b64 s[26:27], 0xb40180
	v_lshl_add_u64 v[218:219], v[176:177], 0, s[26:27]
	global_load_lds_dwordx4 v[218:219], off
	s_mov_b32 m0, s51
	s_mov_b64 s[26:27], 0xb60180
	v_lshl_add_u64 v[214:215], v[176:177], 0, s[26:27]
	global_load_lds_dwordx4 v[214:215], off
	s_waitcnt vmcnt(6)
	s_waitcnt lgkmcnt(0)
	s_barrier
	s_setprio 1
	v_mfma_f32_16x16x32_bf16 v[60:63], v[154:157], v[138:141], v[60:63]
	v_mfma_f32_16x16x32_bf16 v[56:59], v[154:157], v[146:149], v[56:59]
	v_mfma_f32_16x16x32_bf16 v[52:55], v[162:165], v[138:141], v[52:55]
	v_mfma_f32_16x16x32_bf16 v[48:51], v[162:165], v[146:149], v[48:51]
	v_mfma_f32_16x16x32_bf16 v[44:47], v[180:183], v[138:141], v[44:47]
	v_mfma_f32_16x16x32_bf16 v[40:43], v[180:183], v[146:149], v[40:43]
	v_mfma_f32_16x16x32_bf16 v[36:39], v[188:191], v[138:141], v[36:39]
	v_mfma_f32_16x16x32_bf16 v[32:35], v[188:191], v[146:149], v[32:35]
	v_mfma_f32_16x16x32_bf16 v[60:63], v[158:161], v[142:145], v[60:63]
	v_mfma_f32_16x16x32_bf16 v[56:59], v[158:161], v[150:153], v[56:59]
	v_mfma_f32_16x16x32_bf16 v[52:55], v[172:175], v[142:145], v[52:55]
	v_mfma_f32_16x16x32_bf16 v[48:51], v[172:175], v[150:153], v[48:51]
	v_mfma_f32_16x16x32_bf16 v[44:47], v[184:187], v[142:145], v[44:47]
	v_mfma_f32_16x16x32_bf16 v[40:43], v[184:187], v[150:153], v[40:43]
	v_mfma_f32_16x16x32_bf16 v[36:39], v[192:195], v[142:145], v[36:39]
	v_mfma_f32_16x16x32_bf16 v[32:35], v[192:195], v[150:153], v[32:35]
	v_mfma_f32_16x16x32_bf16 v[28:31], v[154:157], v[196:199], v[28:31]
	v_mfma_f32_16x16x32_bf16 v[24:27], v[154:157], v[204:207], v[24:27]
	v_mfma_f32_16x16x32_bf16 v[20:23], v[162:165], v[196:199], v[20:23]
	v_mfma_f32_16x16x32_bf16 v[16:19], v[162:165], v[204:207], v[16:19]
	v_mfma_f32_16x16x32_bf16 v[12:15], v[180:183], v[196:199], v[12:15]
	v_mfma_f32_16x16x32_bf16 v[8:11], v[180:183], v[204:207], v[8:11]
	v_mfma_f32_16x16x32_bf16 v[4:7], v[188:191], v[196:199], v[4:7]
	v_mfma_f32_16x16x32_bf16 v[0:3], v[188:191], v[204:207], v[0:3]
	v_mfma_f32_16x16x32_bf16 v[28:31], v[158:161], v[200:203], v[28:31]
	v_mfma_f32_16x16x32_bf16 v[24:27], v[158:161], v[208:211], v[24:27]
	v_mfma_f32_16x16x32_bf16 v[20:23], v[172:175], v[200:203], v[20:23]
	v_mfma_f32_16x16x32_bf16 v[16:19], v[172:175], v[208:211], v[16:19]
	v_mfma_f32_16x16x32_bf16 v[12:15], v[184:187], v[200:203], v[12:15]
	v_mfma_f32_16x16x32_bf16 v[8:11], v[184:187], v[208:211], v[8:11]
	v_mfma_f32_16x16x32_bf16 v[4:7], v[192:195], v[200:203], v[4:7]
	v_mfma_f32_16x16x32_bf16 v[0:3], v[192:195], v[208:211], v[0:3]
	s_setprio 0
	s_add_i32 s3, s3, 2
	s_add_u32 s6, s6, 0x100
	s_addc_u32 s7, s7, 0
	s_add_u32 s24, s24, 0x100
	s_addc_u32 s25, s25, 0
	s_cmp_ge_i32 s3, s2
	s_barrier
	s_cbranch_scc0 .LBB0_673

; #define STAGE(P, BASE, br, kt) do { const char* _g = (const char*)((BASE) + (size_t)(br) * K + (size_t)(kt) * G_BK); \
;     _Pragma("unroll") for (int _i = 0; _i < 2; ++_i) { \
;       __builtin_amdgcn_global_load_lds((const unsigned*)(_g + (size_t)_i * 128 * K + sg_off), (unsigned*)((char*)(P) + wid * 1024 + _i * 8192), 16, 0, 0); } } while (0)
; #define LDA(dst, b, h) _Pragma("unroll") for (int m = 0; m < 4; ++m) _Pragma("unroll") for (int k = 0; k < 2; ++k) \
;     dst[m][k] = *reinterpret_cast<const bf16x8*>((const char*)shm + aoff + (((b) * 2 + (h)) * 16384 + m * 2048 + k * 1024))
; #define LDB(dst, b, h) _Pragma("unroll") for (int n = 0; n < 2; ++n) _Pragma("unroll") for (int k = 0; k < 2; ++k) \
;     dst[n][k] = *reinterpret_cast<const bf16x8*>((const char*)shm + boff + (((b) * 2 + (h)) * 16384 + n * 2048 + k * 1024))
; #define MMA(ai, bj, At, Bt_) do { __builtin_amdgcn_s_setprio(1); \
;     _Pragma("unroll") for (int m = 0; m < 4; ++m) _Pragma("unroll") for (int n = 0; n < 2; ++n) _Pragma("unroll") for (int k = 0; k < 2; ++k) \
;       acc[ai][bj][m][n] = mfma16(At[m][k], Bt_[n][k], acc[ai][bj][m][n]); \
;     __builtin_amdgcn_s_setprio(0); } while (0)
; #define WAIT_V(n) asm volatile("s_waitcnt vmcnt(" #n ")" ::: "memory")
; #define WAIT_L(n) asm volatile("s_waitcnt lgkmcnt(" #n ")" ::: "memory")
; #define BAR __builtin_amdgcn_s_barrier()
; #define SCHED __builtin_amdgcn_sched_barrier(0)
; template <class Epi>
; __device__ __forceinline__ void gemm_phase(const bfr* __restrict__ A, int lda, const bfr* __restrict__ Bt, int K,
;                                            int nM, int nN, const Epi& epi, bfr* shm, int wv, int nMfull, int ksplit) {
;     ...
;       LDB(B0, 0, 0); SCHED; LDA(At, 0, 0); STAGE(SA(1, 1), Ak, brow + G_HALF, t + 1);
;       WAIT_L(8); BAR; WAIT_L(0); MMA(0, 0, At, B0); BAR; SCHED;
;       LDB(B1, 0, 1); STAGE(SB(0, 0), Bk, bcol, t + 2);
;       BAR; WAIT_L(0); MMA(0, 1, At, B1); BAR;
;       LDA(At, 0, 1); STAGE(SA(0, 0), Ak, brow, t + 2);
;       BAR; WAIT_L(0); MMA(1, 0, At, B0); BAR; SCHED;
;       STAGE(SB(0, 1), Bk, bcol + G_HALF, t + 2);
;       WAIT_V(6); BAR; MMA(1, 1, At, B1); BAR;
.LBB0_729:
	ds_read_b128 v[138:141], v179
	ds_read_b128 v[142:145], v179 offset:1024
	ds_read_b128 v[146:149], v179 offset:2048
	ds_read_b128 v[150:153], v179 offset:3072
	ds_read_b128 v[154:157], v178
	ds_read_b128 v[158:161], v178 offset:1024
	ds_read_b128 v[162:165], v178 offset:2048
	ds_read_b128 v[166:169], v178 offset:3072
	ds_read_b128 v[170:173], v178 offset:4096
	ds_read_b128 v[174:177], v178 offset:5120
	ds_read_b128 v[184:187], v178 offset:6144
	ds_read_b128 v[188:191], v178 offset:7168
	ds_read_b128 v[192:195], v179 offset:16384
	ds_read_b128 v[196:199], v179 offset:17408
	ds_read_b128 v[200:203], v179 offset:18432
	ds_read_b128 v[204:207], v179 offset:19456
	v_lshl_add_u64 v[208:209], s[34:35], 0, v[136:137]
	v_lshl_add_u64 v[210:211], s[38:39], 0, v[136:137]
	s_mov_b32 m0, s52
	v_lshl_add_u64 v[214:215], v[208:209], 0, s[16:17]
	global_load_lds_dwordx4 v[214:215], off
	s_mov_b32 m0, s53
	v_lshl_add_u64 v[216:217], v[208:209], 0, s[18:19]
	global_load_lds_dwordx4 v[216:217], off
	s_waitcnt lgkmcnt(0)
	s_barrier
	s_setprio 1
	v_mfma_f32_16x16x32_bf16 v[124:127], v[154:157], v[138:141], v[124:127]
	v_mfma_f32_16x16x32_bf16 v[120:123], v[154:157], v[146:149], v[120:123]
	v_mfma_f32_16x16x32_bf16 v[116:119], v[162:165], v[138:141], v[116:119]
	v_mfma_f32_16x16x32_bf16 v[112:115], v[162:165], v[146:149], v[112:115]
	v_mfma_f32_16x16x32_bf16 v[108:111], v[170:173], v[138:141], v[108:111]
	v_mfma_f32_16x16x32_bf16 v[104:107], v[170:173], v[146:149], v[104:107]
	v_mfma_f32_16x16x32_bf16 v[100:103], v[184:187], v[138:141], v[100:103]
	v_mfma_f32_16x16x32_bf16 v[96:99], v[184:187], v[146:149], v[96:99]
	v_mfma_f32_16x16x32_bf16 v[124:127], v[158:161], v[142:145], v[124:127]
	v_mfma_f32_16x16x32_bf16 v[120:123], v[158:161], v[150:153], v[120:123]
	v_mfma_f32_16x16x32_bf16 v[116:119], v[166:169], v[142:145], v[116:119]
	v_mfma_f32_16x16x32_bf16 v[112:115], v[166:169], v[150:153], v[112:115]
	v_mfma_f32_16x16x32_bf16 v[108:111], v[174:177], v[142:145], v[108:111]
	v_mfma_f32_16x16x32_bf16 v[104:107], v[174:177], v[150:153], v[104:107]
	v_mfma_f32_16x16x32_bf16 v[100:103], v[188:191], v[142:145], v[100:103]
	v_mfma_f32_16x16x32_bf16 v[96:99], v[188:191], v[150:153], v[96:99]
	v_mfma_f32_16x16x32_bf16 v[92:95], v[154:157], v[192:195], v[92:95]
	v_mfma_f32_16x16x32_bf16 v[88:91], v[154:157], v[200:203], v[88:91]
	v_mfma_f32_16x16x32_bf16 v[84:87], v[162:165], v[192:195], v[84:87]
	v_mfma_f32_16x16x32_bf16 v[80:83], v[162:165], v[200:203], v[80:83]
	v_mfma_f32_16x16x32_bf16 v[76:79], v[170:173], v[192:195], v[76:79]
	v_mfma_f32_16x16x32_bf16 v[72:75], v[170:173], v[200:203], v[72:75]
	v_mfma_f32_16x16x32_bf16 v[68:71], v[184:187], v[192:195], v[68:71]
	v_mfma_f32_16x16x32_bf16 v[64:67], v[184:187], v[200:203], v[64:67]
	v_mfma_f32_16x16x32_bf16 v[92:95], v[158:161], v[196:199], v[92:95]
	v_mfma_f32_16x16x32_bf16 v[88:91], v[158:161], v[204:207], v[88:91]
	v_mfma_f32_16x16x32_bf16 v[84:87], v[166:169], v[196:199], v[84:87]
	v_mfma_f32_16x16x32_bf16 v[80:83], v[166:169], v[204:207], v[80:83]
	v_mfma_f32_16x16x32_bf16 v[76:79], v[174:177], v[196:199], v[76:79]
	v_mfma_f32_16x16x32_bf16 v[72:75], v[174:177], v[204:207], v[72:75]
	v_mfma_f32_16x16x32_bf16 v[68:71], v[188:191], v[196:199], v[68:71]
	v_mfma_f32_16x16x32_bf16 v[64:67], v[188:191], v[204:207], v[64:67]
	s_setprio 0
	s_barrier
	ds_read_b128 v[154:157], v178 offset:16384
	ds_read_b128 v[158:161], v178 offset:17408
	ds_read_b128 v[162:165], v178 offset:18432
	ds_read_b128 v[166:169], v178 offset:19456
	ds_read_b128 v[170:173], v178 offset:20480
	ds_read_b128 v[174:177], v178 offset:21504
	ds_read_b128 v[184:187], v178 offset:22528
	ds_read_b128 v[188:191], v178 offset:23552
	s_mov_b32 m0, s54
	s_mov_b64 s[40:41], 0x580100
	v_lshl_add_u64 v[218:219], v[210:211], 0, s[40:41]
	global_load_lds_dwordx4 v[218:219], off
	s_mov_b32 m0, s55
	s_mov_b64 s[40:41], 0x5d8100
	v_lshl_add_u64 v[214:215], v[210:211], 0, s[40:41]
	global_load_lds_dwordx4 v[214:215], off
	s_mov_b32 m0, s51
	s_mov_b64 s[40:41], 0x100
	v_lshl_add_u64 v[216:217], v[208:209], 0, s[40:41]
	global_load_lds_dwordx4 v[216:217], off
	s_mov_b32 m0, s56
	s_mov_b64 s[40:41], 0x58100
	v_lshl_add_u64 v[218:219], v[208:209], 0, s[40:41]
	global_load_lds_dwordx4 v[218:219], off
	s_mov_b32 m0, s57
	s_mov_b64 s[40:41], 0x630100
	v_lshl_add_u64 v[214:215], v[210:211], 0, s[40:41]
	global_load_lds_dwordx4 v[214:215], off
	s_mov_b32 m0, s58
	s_mov_b64 s[40:41], 0x688100
	v_lshl_add_u64 v[216:217], v[210:211], 0, s[40:41]
	global_load_lds_dwordx4 v[216:217], off
	s_waitcnt vmcnt(6)
	s_waitcnt lgkmcnt(0)
	s_barrier
; #define STAGE(P, BASE, br, kt) do { const char* _g = (const char*)((BASE) + (size_t)(br) * K + (size_t)(kt) * G_BK); \
;     _Pragma("unroll") for (int _i = 0; _i < 2; ++_i) { \
;       __builtin_amdgcn_global_load_lds((const unsigned*)(_g + (size_t)_i * 128 * K + sg_off), (unsigned*)((char*)(P) + wid * 1024 + _i * 8192), 16, 0, 0); } } while (0)
; #define LDA(dst, b, h) _Pragma("unroll") for (int m = 0; m < 4; ++m) _Pragma("unroll") for (int k = 0; k < 2; ++k) \
;     dst[m][k] = *reinterpret_cast<const bf16x8*>((const char*)shm + aoff + (((b) * 2 + (h)) * 16384 + m * 2048 + k * 1024))
; #define LDB(dst, b, h) _Pragma("unroll") for (int n = 0; n < 2; ++n) _Pragma("unroll") for (int k = 0; k < 2; ++k) \
;     dst[n][k] = *reinterpret_cast<const bf16x8*>((const char*)shm + boff + (((b) * 2 + (h)) * 16384 + n * 2048 + k * 1024))
; #define MMA(ai, bj, At, Bt_) do { __builtin_amdgcn_s_setprio(1); \
;     _Pragma("unroll") for (int m = 0; m < 4; ++m) _Pragma("unroll") for (int n = 0; n < 2; ++n) _Pragma("unroll") for (int k = 0; k < 2; ++k) \
;       acc[ai][bj][m][n] = mfma16(At[m][k], Bt_[n][k], acc[ai][bj][m][n]); \
;     __builtin_amdgcn_s_setprio(0); } while (0)
; #define WAIT_V(n) asm volatile("s_waitcnt vmcnt(" #n ")" ::: "memory")
; #define WAIT_L(n) asm volatile("s_waitcnt lgkmcnt(" #n ")" ::: "memory")
; #define BAR __builtin_amdgcn_s_barrier()
; #define SCHED __builtin_amdgcn_sched_barrier(0)
; template <class Epi>
; __device__ __forceinline__ void gemm_phase(const bfr* __restrict__ A, int lda, const bfr* __restrict__ Bt, int K,
;                                            int nM, int nN, const Epi& epi, bfr* shm, int wv, int nMfull, int ksplit) {
;     ...
;       BAR; WAIT_L(0); MMA(0, 1, At, B1); BAR;
;       LDA(At, 0, 1); STAGE(SA(0, 0), Ak, brow, t + 2);
;       BAR; WAIT_L(0); MMA(1, 0, At, B0); BAR; SCHED;
;       STAGE(SB(0, 1), Bk, bcol + G_HALF, t + 2);
;       WAIT_V(6); BAR; MMA(1, 1, At, B1); BAR;
;       LDB(B0, 1, 0); SCHED; LDA(At, 1, 0); STAGE(SA(0, 1), Ak, brow + G_HALF, t + 2);
;       WAIT_L(8); BAR; WAIT_L(0); MMA(0, 0, At, B0); BAR; SCHED;
;       LDB(B1, 1, 1); STAGE(SB(1, 0), Bk, bcol, t + 3);
;       BAR; WAIT_L(0); MMA(0, 1, At, B1); BAR;
;       LDA(At, 1, 1); STAGE(SA(1, 0), Ak, brow, t + 3);
;       BAR; WAIT_L(0); MMA(1, 0, At, B0); BAR; SCHED;
	s_setprio 1
	v_mfma_f32_16x16x32_bf16 v[60:63], v[154:157], v[138:141], v[60:63]
	v_mfma_f32_16x16x32_bf16 v[56:59], v[154:157], v[146:149], v[56:59]
	v_mfma_f32_16x16x32_bf16 v[52:55], v[162:165], v[138:141], v[52:55]
	v_mfma_f32_16x16x32_bf16 v[48:51], v[162:165], v[146:149], v[48:51]
	v_mfma_f32_16x16x32_bf16 v[44:47], v[170:173], v[138:141], v[44:47]
	v_mfma_f32_16x16x32_bf16 v[40:43], v[170:173], v[146:149], v[40:43]
	v_mfma_f32_16x16x32_bf16 v[36:39], v[184:187], v[138:141], v[36:39]
	v_mfma_f32_16x16x32_bf16 v[32:35], v[184:187], v[146:149], v[32:35]
	v_mfma_f32_16x16x32_bf16 v[60:63], v[158:161], v[142:145], v[60:63]
	v_mfma_f32_16x16x32_bf16 v[56:59], v[158:161], v[150:153], v[56:59]
	v_mfma_f32_16x16x32_bf16 v[52:55], v[166:169], v[142:145], v[52:55]
	v_mfma_f32_16x16x32_bf16 v[48:51], v[166:169], v[150:153], v[48:51]
	v_mfma_f32_16x16x32_bf16 v[44:47], v[174:177], v[142:145], v[44:47]
	v_mfma_f32_16x16x32_bf16 v[40:43], v[174:177], v[150:153], v[40:43]
	v_mfma_f32_16x16x32_bf16 v[36:39], v[188:191], v[142:145], v[36:39]
	v_mfma_f32_16x16x32_bf16 v[32:35], v[188:191], v[150:153], v[32:35]
	v_mfma_f32_16x16x32_bf16 v[28:31], v[154:157], v[192:195], v[28:31]
	v_mfma_f32_16x16x32_bf16 v[24:27], v[154:157], v[200:203], v[24:27]
	v_mfma_f32_16x16x32_bf16 v[20:23], v[162:165], v[192:195], v[20:23]
	v_mfma_f32_16x16x32_bf16 v[16:19], v[162:165], v[200:203], v[16:19]
	v_mfma_f32_16x16x32_bf16 v[12:15], v[170:173], v[192:195], v[12:15]
	v_mfma_f32_16x16x32_bf16 v[8:11], v[170:173], v[200:203], v[8:11]
	v_mfma_f32_16x16x32_bf16 v[4:7], v[184:187], v[192:195], v[4:7]
	v_mfma_f32_16x16x32_bf16 v[0:3], v[184:187], v[200:203], v[0:3]
	v_mfma_f32_16x16x32_bf16 v[28:31], v[158:161], v[196:199], v[28:31]
	v_mfma_f32_16x16x32_bf16 v[24:27], v[158:161], v[204:207], v[24:27]
	v_mfma_f32_16x16x32_bf16 v[20:23], v[166:169], v[196:199], v[20:23]
	v_mfma_f32_16x16x32_bf16 v[16:19], v[166:169], v[204:207], v[16:19]
	v_mfma_f32_16x16x32_bf16 v[12:15], v[174:177], v[196:199], v[12:15]
	v_mfma_f32_16x16x32_bf16 v[8:11], v[174:177], v[204:207], v[8:11]
	v_mfma_f32_16x16x32_bf16 v[4:7], v[188:191], v[196:199], v[4:7]
	v_mfma_f32_16x16x32_bf16 v[0:3], v[188:191], v[204:207], v[0:3]
	s_setprio 0
	s_barrier
	ds_read_b128 v[138:141], v179 offset:32768
	ds_read_b128 v[142:145], v179 offset:33792
	ds_read_b128 v[146:149], v179 offset:34816
	ds_read_b128 v[150:153], v179 offset:35840
	ds_read_b128 v[154:157], v178 offset:32768
	ds_read_b128 v[158:161], v178 offset:33792
	ds_read_b128 v[162:165], v178 offset:34816
	ds_read_b128 v[166:169], v178 offset:35840
	ds_read_b128 v[170:173], v178 offset:36864
	ds_read_b128 v[174:177], v178 offset:37888
	ds_read_b128 v[184:187], v178 offset:38912
	ds_read_b128 v[188:191], v178 offset:39936
	ds_read_b128 v[192:195], v179 offset:49152
	ds_read_b128 v[196:199], v179 offset:50176
	ds_read_b128 v[200:203], v179 offset:51200
	ds_read_b128 v[204:207], v179 offset:52224
	s_mov_b32 m0, s59
	s_mov_b64 s[40:41], 0xb0100
	v_lshl_add_u64 v[218:219], v[208:209], 0, s[40:41]
	global_load_lds_dwordx4 v[218:219], off
	s_mov_b32 m0, s82
	s_mov_b64 s[40:41], 0x108100
	v_lshl_add_u64 v[214:215], v[208:209], 0, s[40:41]
	global_load_lds_dwordx4 v[214:215], off
	s_waitcnt lgkmcnt(0)
	s_barrier
	s_setprio 1
	v_mfma_f32_16x16x32_bf16 v[124:127], v[154:157], v[138:141], v[124:127]
	v_mfma_f32_16x16x32_bf16 v[120:123], v[154:157], v[146:149], v[120:123]
	v_mfma_f32_16x16x32_bf16 v[116:119], v[162:165], v[138:141], v[116:119]
	v_mfma_f32_16x16x32_bf16 v[112:115], v[162:165], v[146:149], v[112:115]
	v_mfma_f32_16x16x32_bf16 v[108:111], v[170:173], v[138:141], v[108:111]
	v_mfma_f32_16x16x32_bf16 v[104:107], v[170:173], v[146:149], v[104:107]
	v_mfma_f32_16x16x32_bf16 v[100:103], v[184:187], v[138:141], v[100:103]
	v_mfma_f32_16x16x32_bf16 v[96:99], v[184:187], v[146:149], v[96:99]
	v_mfma_f32_16x16x32_bf16 v[124:127], v[158:161], v[142:145], v[124:127]
	v_mfma_f32_16x16x32_bf16 v[120:123], v[158:161], v[150:153], v[120:123]
	v_mfma_f32_16x16x32_bf16 v[116:119], v[166:169], v[142:145], v[116:119]
	v_mfma_f32_16x16x32_bf16 v[112:115], v[166:169], v[150:153], v[112:115]
	v_mfma_f32_16x16x32_bf16 v[108:111], v[174:177], v[142:145], v[108:111]
	v_mfma_f32_16x16x32_bf16 v[104:107], v[174:177], v[150:153], v[104:107]
	v_mfma_f32_16x16x32_bf16 v[100:103], v[188:191], v[142:145], v[100:103]
	v_mfma_f32_16x16x32_bf16 v[96:99], v[188:191], v[150:153], v[96:99]
	v_mfma_f32_16x16x32_bf16 v[92:95], v[154:157], v[192:195], v[92:95]
	v_mfma_f32_16x16x32_bf16 v[88:91], v[154:157], v[200:203], v[88:91]
	v_mfma_f32_16x16x32_bf16 v[84:87], v[162:165], v[192:195], v[84:87]
	v_mfma_f32_16x16x32_bf16 v[80:83], v[162:165], v[200:203], v[80:83]
	v_mfma_f32_16x16x32_bf16 v[76:79], v[170:173], v[192:195], v[76:79]
	v_mfma_f32_16x16x32_bf16 v[72:75], v[170:173], v[200:203], v[72:75]
	v_mfma_f32_16x16x32_bf16 v[68:71], v[184:187], v[192:195], v[68:71]
	v_mfma_f32_16x16x32_bf16 v[64:67], v[184:187], v[200:203], v[64:67]
	v_mfma_f32_16x16x32_bf16 v[92:95], v[158:161], v[196:199], v[92:95]
	v_mfma_f32_16x16x32_bf16 v[88:91], v[158:161], v[204:207], v[88:91]
	v_mfma_f32_16x16x32_bf16 v[84:87], v[166:169], v[196:199], v[84:87]
	v_mfma_f32_16x16x32_bf16 v[80:83], v[166:169], v[204:207], v[80:83]
	v_mfma_f32_16x16x32_bf16 v[76:79], v[174:177], v[196:199], v[76:79]
	v_mfma_f32_16x16x32_bf16 v[72:75], v[174:177], v[204:207], v[72:75]
	v_mfma_f32_16x16x32_bf16 v[68:71], v[188:191], v[196:199], v[68:71]
	v_mfma_f32_16x16x32_bf16 v[64:67], v[188:191], v[204:207], v[64:67]
	s_setprio 0
	s_barrier
; #define STAGE(P, BASE, br, kt) do { const char* _g = (const char*)((BASE) + (size_t)(br) * K + (size_t)(kt) * G_BK); \
;     _Pragma("unroll") for (int _i = 0; _i < 2; ++_i) { \
;       __builtin_amdgcn_global_load_lds((const unsigned*)(_g + (size_t)_i * 128 * K + sg_off), (unsigned*)((char*)(P) + wid * 1024 + _i * 8192), 16, 0, 0); } } while (0)
; #define LDA(dst, b, h) _Pragma("unroll") for (int m = 0; m < 4; ++m) _Pragma("unroll") for (int k = 0; k < 2; ++k) \
;     dst[m][k] = *reinterpret_cast<const bf16x8*>((const char*)shm + aoff + (((b) * 2 + (h)) * 16384 + m * 2048 + k * 1024))
; #define MMA(ai, bj, At, Bt_) do { __builtin_amdgcn_s_setprio(1); \
;     _Pragma("unroll") for (int m = 0; m < 4; ++m) _Pragma("unroll") for (int n = 0; n < 2; ++n) _Pragma("unroll") for (int k = 0; k < 2; ++k) \
;       acc[ai][bj][m][n] = mfma16(At[m][k], Bt_[n][k], acc[ai][bj][m][n]); \
;     __builtin_amdgcn_s_setprio(0); } while (0)
; #define WAIT_V(n) asm volatile("s_waitcnt vmcnt(" #n ")" ::: "memory")
; #define WAIT_L(n) asm volatile("s_waitcnt lgkmcnt(" #n ")" ::: "memory")
; #define BAR __builtin_amdgcn_s_barrier()
; #define SCHED __builtin_amdgcn_sched_barrier(0)
; template <class Epi>
; __device__ __forceinline__ void gemm_phase(const bfr* __restrict__ A, int lda, const bfr* __restrict__ Bt, int K,
;                                            int nM, int nN, const Epi& epi, bfr* shm, int wv, int nMfull, int ksplit) {
;     ...
;       LDA(At, 1, 1); STAGE(SA(1, 0), Ak, brow, t + 3);
;       BAR; WAIT_L(0); MMA(1, 0, At, B0); BAR; SCHED;
;       STAGE(SB(1, 1), Bk, bcol + G_HALF, t + 3);
;       WAIT_V(6); BAR; MMA(1, 1, At, B1); BAR;
;     }
	ds_read_b128 v[154:157], v178 offset:49152
	ds_read_b128 v[158:161], v178 offset:50176
	ds_read_b128 v[162:165], v178 offset:51200
	ds_read_b128 v[166:169], v178 offset:52224
	ds_read_b128 v[170:173], v178 offset:53248
	ds_read_b128 v[174:177], v178 offset:54272
	ds_read_b128 v[184:187], v178 offset:55296
	ds_read_b128 v[188:191], v178 offset:56320
	s_mov_b32 m0, s83
	s_mov_b64 s[40:41], 0x580180
	v_lshl_add_u64 v[216:217], v[210:211], 0, s[40:41]
	global_load_lds_dwordx4 v[216:217], off
	s_mov_b32 m0, s84
	s_mov_b64 s[40:41], 0x5d8180
	v_lshl_add_u64 v[218:219], v[210:211], 0, s[40:41]
	global_load_lds_dwordx4 v[218:219], off
	s_mov_b32 m0, s85
	s_mov_b64 s[40:41], 0x180
	v_lshl_add_u64 v[214:215], v[208:209], 0, s[40:41]
	global_load_lds_dwordx4 v[214:215], off
	s_mov_b32 m0, s90
	s_mov_b64 s[40:41], 0x58180
	v_lshl_add_u64 v[216:217], v[208:209], 0, s[40:41]
	global_load_lds_dwordx4 v[216:217], off
	s_mov_b32 m0, s91
	s_mov_b64 s[40:41], 0x630180
	v_lshl_add_u64 v[218:219], v[210:211], 0, s[40:41]
	global_load_lds_dwordx4 v[218:219], off
	s_mov_b32 m0, s92
	s_mov_b64 s[40:41], 0x688180
	v_lshl_add_u64 v[214:215], v[210:211], 0, s[40:41]
	global_load_lds_dwordx4 v[214:215], off
	s_waitcnt vmcnt(6)
	s_waitcnt lgkmcnt(0)
	s_barrier
	s_setprio 1
	v_mfma_f32_16x16x32_bf16 v[60:63], v[154:157], v[138:141], v[60:63]
	v_mfma_f32_16x16x32_bf16 v[56:59], v[154:157], v[146:149], v[56:59]
	v_mfma_f32_16x16x32_bf16 v[52:55], v[162:165], v[138:141], v[52:55]
	v_mfma_f32_16x16x32_bf16 v[48:51], v[162:165], v[146:149], v[48:51]
	v_mfma_f32_16x16x32_bf16 v[44:47], v[170:173], v[138:141], v[44:47]
	v_mfma_f32_16x16x32_bf16 v[40:43], v[170:173], v[146:149], v[40:43]
	v_mfma_f32_16x16x32_bf16 v[36:39], v[184:187], v[138:141], v[36:39]
	v_mfma_f32_16x16x32_bf16 v[32:35], v[184:187], v[146:149], v[32:35]
	v_mfma_f32_16x16x32_bf16 v[60:63], v[158:161], v[142:145], v[60:63]
	v_mfma_f32_16x16x32_bf16 v[56:59], v[158:161], v[150:153], v[56:59]
	v_mfma_f32_16x16x32_bf16 v[52:55], v[166:169], v[142:145], v[52:55]
	v_mfma_f32_16x16x32_bf16 v[48:51], v[166:169], v[150:153], v[48:51]
	v_mfma_f32_16x16x32_bf16 v[44:47], v[174:177], v[142:145], v[44:47]
	v_mfma_f32_16x16x32_bf16 v[40:43], v[174:177], v[150:153], v[40:43]
	v_mfma_f32_16x16x32_bf16 v[36:39], v[188:191], v[142:145], v[36:39]
	v_mfma_f32_16x16x32_bf16 v[32:35], v[188:191], v[150:153], v[32:35]
	v_mfma_f32_16x16x32_bf16 v[28:31], v[154:157], v[192:195], v[28:31]
	v_mfma_f32_16x16x32_bf16 v[24:27], v[154:157], v[200:203], v[24:27]
	v_mfma_f32_16x16x32_bf16 v[20:23], v[162:165], v[192:195], v[20:23]
	v_mfma_f32_16x16x32_bf16 v[16:19], v[162:165], v[200:203], v[16:19]
	v_mfma_f32_16x16x32_bf16 v[12:15], v[170:173], v[192:195], v[12:15]
	v_mfma_f32_16x16x32_bf16 v[8:11], v[170:173], v[200:203], v[8:11]
	v_mfma_f32_16x16x32_bf16 v[4:7], v[184:187], v[192:195], v[4:7]
	v_mfma_f32_16x16x32_bf16 v[0:3], v[184:187], v[200:203], v[0:3]
	v_mfma_f32_16x16x32_bf16 v[28:31], v[158:161], v[196:199], v[28:31]
	v_mfma_f32_16x16x32_bf16 v[24:27], v[158:161], v[204:207], v[24:27]
	v_mfma_f32_16x16x32_bf16 v[20:23], v[166:169], v[196:199], v[20:23]
	v_mfma_f32_16x16x32_bf16 v[16:19], v[166:169], v[204:207], v[16:19]
	v_mfma_f32_16x16x32_bf16 v[12:15], v[174:177], v[196:199], v[12:15]
	v_mfma_f32_16x16x32_bf16 v[8:11], v[174:177], v[204:207], v[8:11]
	v_mfma_f32_16x16x32_bf16 v[4:7], v[188:191], v[196:199], v[4:7]
	v_mfma_f32_16x16x32_bf16 v[0:3], v[188:191], v[204:207], v[0:3]
	s_setprio 0
	s_add_i32 s37, s37, 2
	s_add_u32 s38, s38, 0x100
	s_addc_u32 s39, s39, 0
	s_add_u32 s34, s34, 0x100
	s_addc_u32 s35, s35, 0
	s_cmp_ge_i32 s37, s2
	s_barrier
	s_cbranch_scc0 .LBB0_729

; #define STAGE(P, BASE, br, kt) do { const char* _g = (const char*)((BASE) + (size_t)(br) * K + (size_t)(kt) * G_BK); \
;     _Pragma("unroll") for (int _i = 0; _i < 2; ++_i) { \
;       __builtin_amdgcn_global_load_lds((const unsigned*)(_g + (size_t)_i * 128 * K + sg_off), (unsigned*)((char*)(P) + wid * 1024 + _i * 8192), 16, 0, 0); } } while (0)
; #define LDA(dst, b, h) _Pragma("unroll") for (int m = 0; m < 4; ++m) _Pragma("unroll") for (int k = 0; k < 2; ++k) \
;     dst[m][k] = *reinterpret_cast<const bf16x8*>((const char*)shm + aoff + (((b) * 2 + (h)) * 16384 + m * 2048 + k * 1024))
; #define LDB(dst, b, h) _Pragma("unroll") for (int n = 0; n < 2; ++n) _Pragma("unroll") for (int k = 0; k < 2; ++k) \
;     dst[n][k] = *reinterpret_cast<const bf16x8*>((const char*)shm + boff + (((b) * 2 + (h)) * 16384 + n * 2048 + k * 1024))
; #define MMA(ai, bj, At, Bt_) do { __builtin_amdgcn_s_setprio(1); \
;     _Pragma("unroll") for (int m = 0; m < 4; ++m) _Pragma("unroll") for (int n = 0; n < 2; ++n) _Pragma("unroll") for (int k = 0; k < 2; ++k) \
;       acc[ai][bj][m][n] = mfma16(At[m][k], Bt_[n][k], acc[ai][bj][m][n]); \
;     __builtin_amdgcn_s_setprio(0); } while (0)
; #define WAIT_V(n) asm volatile("s_waitcnt vmcnt(" #n ")" ::: "memory")
; #define WAIT_L(n) asm volatile("s_waitcnt lgkmcnt(" #n ")" ::: "memory")
; #define BAR __builtin_amdgcn_s_barrier()
; #define SCHED __builtin_amdgcn_sched_barrier(0)
; template <class Epi>
; __device__ __forceinline__ void gemm_phase(const bfr* __restrict__ A, int lda, const bfr* __restrict__ Bt, int K,
;                                            int nM, int nN, const Epi& epi, bfr* shm, int wv, int nMfull, int ksplit) {
;     ...
;       LDB(B0, 0, 0); SCHED; LDA(At, 0, 0); STAGE(SA(1, 1), Ak, brow + G_HALF, t + 1);
;       WAIT_L(8); BAR; WAIT_L(0); MMA(0, 0, At, B0); BAR; SCHED;
;       LDB(B1, 0, 1); STAGE(SB(0, 0), Bk, bcol, t + 2);
;       BAR; WAIT_L(0); MMA(0, 1, At, B1); BAR;
;       LDA(At, 0, 1); STAGE(SA(0, 0), Ak, brow, t + 2);
;       BAR; WAIT_L(0); MMA(1, 0, At, B0); BAR; SCHED;
;       STAGE(SB(0, 1), Bk, bcol + G_HALF, t + 2);
;       WAIT_V(6); BAR; MMA(1, 1, At, B1); BAR;
.LBB0_879:
	ds_read_b128 v[138:141], v169
	ds_read_b128 v[142:145], v169 offset:1024
	ds_read_b128 v[146:149], v169 offset:2048
	ds_read_b128 v[150:153], v169 offset:3072
	ds_read_b128 v[154:157], v129
	ds_read_b128 v[158:161], v129 offset:1024
	ds_read_b128 v[162:165], v129 offset:2048
	ds_read_b128 v[172:175], v129 offset:3072
	ds_read_b128 v[180:183], v129 offset:4096
	ds_read_b128 v[184:187], v129 offset:5120
	ds_read_b128 v[188:191], v129 offset:6144
	ds_read_b128 v[192:195], v129 offset:7168
	ds_read_b128 v[196:199], v169 offset:16384
	ds_read_b128 v[200:203], v169 offset:17408
	ds_read_b128 v[204:207], v169 offset:18432
	ds_read_b128 v[208:211], v169 offset:19456
	v_lshl_add_u64 v[166:167], s[22:23], 0, v[136:137]
	v_lshl_add_u64 v[176:177], s[4:5], 0, v[136:137]
	s_mov_b32 m0, s50
	s_mov_b64 s[26:27], 0x40080
	v_lshl_add_u64 v[214:215], v[166:167], 0, s[26:27]
	global_load_lds_dwordx4 v[214:215], off
	s_mov_b32 m0, s51
	s_mov_b64 s[26:27], 0x60080
	v_lshl_add_u64 v[216:217], v[166:167], 0, s[26:27]
	global_load_lds_dwordx4 v[216:217], off
	s_waitcnt lgkmcnt(0)
	s_barrier
	s_setprio 1
	v_mfma_f32_16x16x32_bf16 v[124:127], v[154:157], v[138:141], v[124:127]
	v_mfma_f32_16x16x32_bf16 v[120:123], v[154:157], v[146:149], v[120:123]
	v_mfma_f32_16x16x32_bf16 v[116:119], v[162:165], v[138:141], v[116:119]
	v_mfma_f32_16x16x32_bf16 v[112:115], v[162:165], v[146:149], v[112:115]
	v_mfma_f32_16x16x32_bf16 v[108:111], v[180:183], v[138:141], v[108:111]
	v_mfma_f32_16x16x32_bf16 v[104:107], v[180:183], v[146:149], v[104:107]
	v_mfma_f32_16x16x32_bf16 v[100:103], v[188:191], v[138:141], v[100:103]
	v_mfma_f32_16x16x32_bf16 v[96:99], v[188:191], v[146:149], v[96:99]
	v_mfma_f32_16x16x32_bf16 v[124:127], v[158:161], v[142:145], v[124:127]
	v_mfma_f32_16x16x32_bf16 v[120:123], v[158:161], v[150:153], v[120:123]
	v_mfma_f32_16x16x32_bf16 v[116:119], v[172:175], v[142:145], v[116:119]
	v_mfma_f32_16x16x32_bf16 v[112:115], v[172:175], v[150:153], v[112:115]
	v_mfma_f32_16x16x32_bf16 v[108:111], v[184:187], v[142:145], v[108:111]
	v_mfma_f32_16x16x32_bf16 v[104:107], v[184:187], v[150:153], v[104:107]
	v_mfma_f32_16x16x32_bf16 v[100:103], v[192:195], v[142:145], v[100:103]
	v_mfma_f32_16x16x32_bf16 v[96:99], v[192:195], v[150:153], v[96:99]
	v_mfma_f32_16x16x32_bf16 v[92:95], v[154:157], v[196:199], v[92:95]
	v_mfma_f32_16x16x32_bf16 v[88:91], v[154:157], v[204:207], v[88:91]
	v_mfma_f32_16x16x32_bf16 v[84:87], v[162:165], v[196:199], v[84:87]
	v_mfma_f32_16x16x32_bf16 v[80:83], v[162:165], v[204:207], v[80:83]
	v_mfma_f32_16x16x32_bf16 v[76:79], v[180:183], v[196:199], v[76:79]
	v_mfma_f32_16x16x32_bf16 v[72:75], v[180:183], v[204:207], v[72:75]
	v_mfma_f32_16x16x32_bf16 v[68:71], v[188:191], v[196:199], v[68:71]
	v_mfma_f32_16x16x32_bf16 v[64:67], v[188:191], v[204:207], v[64:67]
	v_mfma_f32_16x16x32_bf16 v[92:95], v[158:161], v[200:203], v[92:95]
	v_mfma_f32_16x16x32_bf16 v[88:91], v[158:161], v[208:211], v[88:91]
	v_mfma_f32_16x16x32_bf16 v[84:87], v[172:175], v[200:203], v[84:87]
	v_mfma_f32_16x16x32_bf16 v[80:83], v[172:175], v[208:211], v[80:83]
	v_mfma_f32_16x16x32_bf16 v[76:79], v[184:187], v[200:203], v[76:79]
	v_mfma_f32_16x16x32_bf16 v[72:75], v[184:187], v[208:211], v[72:75]
	v_mfma_f32_16x16x32_bf16 v[68:71], v[192:195], v[200:203], v[68:71]
	v_mfma_f32_16x16x32_bf16 v[64:67], v[192:195], v[208:211], v[64:67]
	s_setprio 0
	s_barrier
	ds_read_b128 v[154:157], v129 offset:16384
	ds_read_b128 v[158:161], v129 offset:17408
	ds_read_b128 v[162:165], v129 offset:18432
	ds_read_b128 v[172:175], v129 offset:19456
	ds_read_b128 v[180:183], v129 offset:20480
	ds_read_b128 v[184:187], v129 offset:21504
	ds_read_b128 v[188:191], v129 offset:22528
	ds_read_b128 v[192:195], v129 offset:23552
	s_mov_b32 m0, s37
	s_mov_b64 s[26:27], 0x1600100
	v_lshl_add_u64 v[218:219], v[176:177], 0, s[26:27]
	global_load_lds_dwordx4 v[218:219], off
	s_mov_b32 m0, s38
	s_mov_b64 s[26:27], 0x1620100
	v_lshl_add_u64 v[214:215], v[176:177], 0, s[26:27]
	global_load_lds_dwordx4 v[214:215], off
	s_mov_b32 m0, s36
	s_mov_b64 s[26:27], 0x100
	v_lshl_add_u64 v[216:217], v[166:167], 0, s[26:27]
	global_load_lds_dwordx4 v[216:217], off
	s_mov_b32 m0, s39
	s_mov_b64 s[26:27], 0x20100
	v_lshl_add_u64 v[218:219], v[166:167], 0, s[26:27]
	global_load_lds_dwordx4 v[218:219], off
	s_mov_b32 m0, s40
	s_mov_b64 s[26:27], 0x1640100
	v_lshl_add_u64 v[214:215], v[176:177], 0, s[26:27]
	global_load_lds_dwordx4 v[214:215], off
	s_mov_b32 m0, s41
	s_mov_b64 s[26:27], 0x1660100
	v_lshl_add_u64 v[216:217], v[176:177], 0, s[26:27]
	global_load_lds_dwordx4 v[216:217], off
	s_waitcnt vmcnt(6)
	s_waitcnt lgkmcnt(0)
	s_barrier
; #define STAGE(P, BASE, br, kt) do { const char* _g = (const char*)((BASE) + (size_t)(br) * K + (size_t)(kt) * G_BK); \
;     _Pragma("unroll") for (int _i = 0; _i < 2; ++_i) { \
;       __builtin_amdgcn_global_load_lds((const unsigned*)(_g + (size_t)_i * 128 * K + sg_off), (unsigned*)((char*)(P) + wid * 1024 + _i * 8192), 16, 0, 0); } } while (0)
; #define LDA(dst, b, h) _Pragma("unroll") for (int m = 0; m < 4; ++m) _Pragma("unroll") for (int k = 0; k < 2; ++k) \
;     dst[m][k] = *reinterpret_cast<const bf16x8*>((const char*)shm + aoff + (((b) * 2 + (h)) * 16384 + m * 2048 + k * 1024))
; #define LDB(dst, b, h) _Pragma("unroll") for (int n = 0; n < 2; ++n) _Pragma("unroll") for (int k = 0; k < 2; ++k) \
;     dst[n][k] = *reinterpret_cast<const bf16x8*>((const char*)shm + boff + (((b) * 2 + (h)) * 16384 + n * 2048 + k * 1024))
; #define MMA(ai, bj, At, Bt_) do { __builtin_amdgcn_s_setprio(1); \
;     _Pragma("unroll") for (int m = 0; m < 4; ++m) _Pragma("unroll") for (int n = 0; n < 2; ++n) _Pragma("unroll") for (int k = 0; k < 2; ++k) \
;       acc[ai][bj][m][n] = mfma16(At[m][k], Bt_[n][k], acc[ai][bj][m][n]); \
;     __builtin_amdgcn_s_setprio(0); } while (0)
; #define WAIT_V(n) asm volatile("s_waitcnt vmcnt(" #n ")" ::: "memory")
; #define WAIT_L(n) asm volatile("s_waitcnt lgkmcnt(" #n ")" ::: "memory")
; #define BAR __builtin_amdgcn_s_barrier()
; #define SCHED __builtin_amdgcn_sched_barrier(0)
; template <class Epi>
; __device__ __forceinline__ void gemm_phase(const bfr* __restrict__ A, int lda, const bfr* __restrict__ Bt, int K,
;                                            int nM, int nN, const Epi& epi, bfr* shm, int wv, int nMfull, int ksplit) {
;     ...
;       BAR; WAIT_L(0); MMA(0, 1, At, B1); BAR;
;       LDA(At, 0, 1); STAGE(SA(0, 0), Ak, brow, t + 2);
;       BAR; WAIT_L(0); MMA(1, 0, At, B0); BAR; SCHED;
;       STAGE(SB(0, 1), Bk, bcol + G_HALF, t + 2);
;       WAIT_V(6); BAR; MMA(1, 1, At, B1); BAR;
;       LDB(B0, 1, 0); SCHED; LDA(At, 1, 0); STAGE(SA(0, 1), Ak, brow + G_HALF, t + 2);
;       WAIT_L(8); BAR; WAIT_L(0); MMA(0, 0, At, B0); BAR; SCHED;
;       LDB(B1, 1, 1); STAGE(SB(1, 0), Bk, bcol, t + 3);
;       BAR; WAIT_L(0); MMA(0, 1, At, B1); BAR;
;       LDA(At, 1, 1); STAGE(SA(1, 0), Ak, brow, t + 3);
;       BAR; WAIT_L(0); MMA(1, 0, At, B0); BAR; SCHED;
	s_setprio 1
	v_mfma_f32_16x16x32_bf16 v[60:63], v[154:157], v[138:141], v[60:63]
	v_mfma_f32_16x16x32_bf16 v[56:59], v[154:157], v[146:149], v[56:59]
	v_mfma_f32_16x16x32_bf16 v[52:55], v[162:165], v[138:141], v[52:55]
	v_mfma_f32_16x16x32_bf16 v[48:51], v[162:165], v[146:149], v[48:51]
	v_mfma_f32_16x16x32_bf16 v[44:47], v[180:183], v[138:141], v[44:47]
	v_mfma_f32_16x16x32_bf16 v[40:43], v[180:183], v[146:149], v[40:43]
	v_mfma_f32_16x16x32_bf16 v[36:39], v[188:191], v[138:141], v[36:39]
	v_mfma_f32_16x16x32_bf16 v[32:35], v[188:191], v[146:149], v[32:35]
	v_mfma_f32_16x16x32_bf16 v[60:63], v[158:161], v[142:145], v[60:63]
	v_mfma_f32_16x16x32_bf16 v[56:59], v[158:161], v[150:153], v[56:59]
	v_mfma_f32_16x16x32_bf16 v[52:55], v[172:175], v[142:145], v[52:55]
	v_mfma_f32_16x16x32_bf16 v[48:51], v[172:175], v[150:153], v[48:51]
	v_mfma_f32_16x16x32_bf16 v[44:47], v[184:187], v[142:145], v[44:47]
	v_mfma_f32_16x16x32_bf16 v[40:43], v[184:187], v[150:153], v[40:43]
	v_mfma_f32_16x16x32_bf16 v[36:39], v[192:195], v[142:145], v[36:39]
	v_mfma_f32_16x16x32_bf16 v[32:35], v[192:195], v[150:153], v[32:35]
	v_mfma_f32_16x16x32_bf16 v[28:31], v[154:157], v[196:199], v[28:31]
	v_mfma_f32_16x16x32_bf16 v[24:27], v[154:157], v[204:207], v[24:27]
	v_mfma_f32_16x16x32_bf16 v[20:23], v[162:165], v[196:199], v[20:23]
	v_mfma_f32_16x16x32_bf16 v[16:19], v[162:165], v[204:207], v[16:19]
	v_mfma_f32_16x16x32_bf16 v[12:15], v[180:183], v[196:199], v[12:15]
	v_mfma_f32_16x16x32_bf16 v[8:11], v[180:183], v[204:207], v[8:11]
	v_mfma_f32_16x16x32_bf16 v[4:7], v[188:191], v[196:199], v[4:7]
	v_mfma_f32_16x16x32_bf16 v[0:3], v[188:191], v[204:207], v[0:3]
	v_mfma_f32_16x16x32_bf16 v[28:31], v[158:161], v[200:203], v[28:31]
	v_mfma_f32_16x16x32_bf16 v[24:27], v[158:161], v[208:211], v[24:27]
	v_mfma_f32_16x16x32_bf16 v[20:23], v[172:175], v[200:203], v[20:23]
	v_mfma_f32_16x16x32_bf16 v[16:19], v[172:175], v[208:211], v[16:19]
	v_mfma_f32_16x16x32_bf16 v[12:15], v[184:187], v[200:203], v[12:15]
	v_mfma_f32_16x16x32_bf16 v[8:11], v[184:187], v[208:211], v[8:11]
	v_mfma_f32_16x16x32_bf16 v[4:7], v[192:195], v[200:203], v[4:7]
	v_mfma_f32_16x16x32_bf16 v[0:3], v[192:195], v[208:211], v[0:3]
	s_setprio 0
	s_barrier
	ds_read_b128 v[138:141], v169 offset:32768
	ds_read_b128 v[142:145], v169 offset:33792
	ds_read_b128 v[146:149], v169 offset:34816
	ds_read_b128 v[150:153], v169 offset:35840
	ds_read_b128 v[154:157], v129 offset:32768
	ds_read_b128 v[158:161], v129 offset:33792
	ds_read_b128 v[162:165], v129 offset:34816
	ds_read_b128 v[172:175], v129 offset:35840
	ds_read_b128 v[180:183], v129 offset:36864
	ds_read_b128 v[184:187], v129 offset:37888
	ds_read_b128 v[188:191], v129 offset:38912
	ds_read_b128 v[192:195], v129 offset:39936
	ds_read_b128 v[196:199], v169 offset:49152
	ds_read_b128 v[200:203], v169 offset:50176
	ds_read_b128 v[204:207], v169 offset:51200
	ds_read_b128 v[208:211], v169 offset:52224
	s_mov_b32 m0, s42
	s_mov_b64 s[26:27], 0x40100
	v_lshl_add_u64 v[218:219], v[166:167], 0, s[26:27]
	global_load_lds_dwordx4 v[218:219], off
	s_mov_b32 m0, s43
	s_mov_b64 s[26:27], 0x60100
	v_lshl_add_u64 v[214:215], v[166:167], 0, s[26:27]
	global_load_lds_dwordx4 v[214:215], off
	s_waitcnt lgkmcnt(0)
	s_barrier
	s_setprio 1
	v_mfma_f32_16x16x32_bf16 v[124:127], v[154:157], v[138:141], v[124:127]
	v_mfma_f32_16x16x32_bf16 v[120:123], v[154:157], v[146:149], v[120:123]
	v_mfma_f32_16x16x32_bf16 v[116:119], v[162:165], v[138:141], v[116:119]
	v_mfma_f32_16x16x32_bf16 v[112:115], v[162:165], v[146:149], v[112:115]
	v_mfma_f32_16x16x32_bf16 v[108:111], v[180:183], v[138:141], v[108:111]
	v_mfma_f32_16x16x32_bf16 v[104:107], v[180:183], v[146:149], v[104:107]
	v_mfma_f32_16x16x32_bf16 v[100:103], v[188:191], v[138:141], v[100:103]
	v_mfma_f32_16x16x32_bf16 v[96:99], v[188:191], v[146:149], v[96:99]
	v_mfma_f32_16x16x32_bf16 v[124:127], v[158:161], v[142:145], v[124:127]
	v_mfma_f32_16x16x32_bf16 v[120:123], v[158:161], v[150:153], v[120:123]
	v_mfma_f32_16x16x32_bf16 v[116:119], v[172:175], v[142:145], v[116:119]
	v_mfma_f32_16x16x32_bf16 v[112:115], v[172:175], v[150:153], v[112:115]
	v_mfma_f32_16x16x32_bf16 v[108:111], v[184:187], v[142:145], v[108:111]
	v_mfma_f32_16x16x32_bf16 v[104:107], v[184:187], v[150:153], v[104:107]
	v_mfma_f32_16x16x32_bf16 v[100:103], v[192:195], v[142:145], v[100:103]
	v_mfma_f32_16x16x32_bf16 v[96:99], v[192:195], v[150:153], v[96:99]
	v_mfma_f32_16x16x32_bf16 v[92:95], v[154:157], v[196:199], v[92:95]
	v_mfma_f32_16x16x32_bf16 v[88:91], v[154:157], v[204:207], v[88:91]
	v_mfma_f32_16x16x32_bf16 v[84:87], v[162:165], v[196:199], v[84:87]
	v_mfma_f32_16x16x32_bf16 v[80:83], v[162:165], v[204:207], v[80:83]
	v_mfma_f32_16x16x32_bf16 v[76:79], v[180:183], v[196:199], v[76:79]
	v_mfma_f32_16x16x32_bf16 v[72:75], v[180:183], v[204:207], v[72:75]
	v_mfma_f32_16x16x32_bf16 v[68:71], v[188:191], v[196:199], v[68:71]
	v_mfma_f32_16x16x32_bf16 v[64:67], v[188:191], v[204:207], v[64:67]
	v_mfma_f32_16x16x32_bf16 v[92:95], v[158:161], v[200:203], v[92:95]
	v_mfma_f32_16x16x32_bf16 v[88:91], v[158:161], v[208:211], v[88:91]
	v_mfma_f32_16x16x32_bf16 v[84:87], v[172:175], v[200:203], v[84:87]
	v_mfma_f32_16x16x32_bf16 v[80:83], v[172:175], v[208:211], v[80:83]
	v_mfma_f32_16x16x32_bf16 v[76:79], v[184:187], v[200:203], v[76:79]
	v_mfma_f32_16x16x32_bf16 v[72:75], v[184:187], v[208:211], v[72:75]
	v_mfma_f32_16x16x32_bf16 v[68:71], v[192:195], v[200:203], v[68:71]
	v_mfma_f32_16x16x32_bf16 v[64:67], v[192:195], v[208:211], v[64:67]
	s_setprio 0
	s_barrier
; #define STAGE(P, BASE, br, kt) do { const char* _g = (const char*)((BASE) + (size_t)(br) * K + (size_t)(kt) * G_BK); \
;     _Pragma("unroll") for (int _i = 0; _i < 2; ++_i) { \
;       __builtin_amdgcn_global_load_lds((const unsigned*)(_g + (size_t)_i * 128 * K + sg_off), (unsigned*)((char*)(P) + wid * 1024 + _i * 8192), 16, 0, 0); } } while (0)
; #define LDA(dst, b, h) _Pragma("unroll") for (int m = 0; m < 4; ++m) _Pragma("unroll") for (int k = 0; k < 2; ++k) \
;     dst[m][k] = *reinterpret_cast<const bf16x8*>((const char*)shm + aoff + (((b) * 2 + (h)) * 16384 + m * 2048 + k * 1024))
; #define MMA(ai, bj, At, Bt_) do { __builtin_amdgcn_s_setprio(1); \
;     _Pragma("unroll") for (int m = 0; m < 4; ++m) _Pragma("unroll") for (int n = 0; n < 2; ++n) _Pragma("unroll") for (int k = 0; k < 2; ++k) \
;       acc[ai][bj][m][n] = mfma16(At[m][k], Bt_[n][k], acc[ai][bj][m][n]); \
;     __builtin_amdgcn_s_setprio(0); } while (0)
; #define WAIT_V(n) asm volatile("s_waitcnt vmcnt(" #n ")" ::: "memory")
; #define WAIT_L(n) asm volatile("s_waitcnt lgkmcnt(" #n ")" ::: "memory")
; #define BAR __builtin_amdgcn_s_barrier()
; #define SCHED __builtin_amdgcn_sched_barrier(0)
; template <class Epi>
; __device__ __forceinline__ void gemm_phase(const bfr* __restrict__ A, int lda, const bfr* __restrict__ Bt, int K,
;                                            int nM, int nN, const Epi& epi, bfr* shm, int wv, int nMfull, int ksplit) {
;     ...
;       LDA(At, 1, 1); STAGE(SA(1, 0), Ak, brow, t + 3);
;       BAR; WAIT_L(0); MMA(1, 0, At, B0); BAR; SCHED;
;       STAGE(SB(1, 1), Bk, bcol + G_HALF, t + 3);
;       WAIT_V(6); BAR; MMA(1, 1, At, B1); BAR;
;     }
	ds_read_b128 v[154:157], v129 offset:49152
	ds_read_b128 v[158:161], v129 offset:50176
	ds_read_b128 v[162:165], v129 offset:51200
	ds_read_b128 v[172:175], v129 offset:52224
	ds_read_b128 v[180:183], v129 offset:53248
	ds_read_b128 v[184:187], v129 offset:54272
	ds_read_b128 v[188:191], v129 offset:55296
	ds_read_b128 v[192:195], v129 offset:56320
	s_mov_b32 m0, s44
	s_mov_b64 s[26:27], 0x1600180
	v_lshl_add_u64 v[216:217], v[176:177], 0, s[26:27]
	global_load_lds_dwordx4 v[216:217], off
	s_mov_b32 m0, s45
	s_mov_b64 s[26:27], 0x1620180
	v_lshl_add_u64 v[218:219], v[176:177], 0, s[26:27]
	global_load_lds_dwordx4 v[218:219], off
	s_mov_b32 m0, s46
	s_mov_b64 s[26:27], 0x180
	v_lshl_add_u64 v[214:215], v[166:167], 0, s[26:27]
	global_load_lds_dwordx4 v[214:215], off
	s_mov_b32 m0, s47
	s_mov_b64 s[26:27], 0x20180
	v_lshl_add_u64 v[216:217], v[166:167], 0, s[26:27]
	global_load_lds_dwordx4 v[216:217], off
	s_mov_b32 m0, s48
	s_mov_b64 s[26:27], 0x1640180
	v_lshl_add_u64 v[218:219], v[176:177], 0, s[26:27]
	global_load_lds_dwordx4 v[218:219], off
	s_mov_b32 m0, s49
	s_mov_b64 s[26:27], 0x1660180
	v_lshl_add_u64 v[214:215], v[176:177], 0, s[26:27]
	global_load_lds_dwordx4 v[214:215], off
	s_waitcnt vmcnt(6)
	s_waitcnt lgkmcnt(0)
	s_barrier
	s_setprio 1
	v_mfma_f32_16x16x32_bf16 v[60:63], v[154:157], v[138:141], v[60:63]
	v_mfma_f32_16x16x32_bf16 v[56:59], v[154:157], v[146:149], v[56:59]
	v_mfma_f32_16x16x32_bf16 v[52:55], v[162:165], v[138:141], v[52:55]
	v_mfma_f32_16x16x32_bf16 v[48:51], v[162:165], v[146:149], v[48:51]
	v_mfma_f32_16x16x32_bf16 v[44:47], v[180:183], v[138:141], v[44:47]
	v_mfma_f32_16x16x32_bf16 v[40:43], v[180:183], v[146:149], v[40:43]
	v_mfma_f32_16x16x32_bf16 v[36:39], v[188:191], v[138:141], v[36:39]
	v_mfma_f32_16x16x32_bf16 v[32:35], v[188:191], v[146:149], v[32:35]
	v_mfma_f32_16x16x32_bf16 v[60:63], v[158:161], v[142:145], v[60:63]
	v_mfma_f32_16x16x32_bf16 v[56:59], v[158:161], v[150:153], v[56:59]
	v_mfma_f32_16x16x32_bf16 v[52:55], v[172:175], v[142:145], v[52:55]
	v_mfma_f32_16x16x32_bf16 v[48:51], v[172:175], v[150:153], v[48:51]
	v_mfma_f32_16x16x32_bf16 v[44:47], v[184:187], v[142:145], v[44:47]
	v_mfma_f32_16x16x32_bf16 v[40:43], v[184:187], v[150:153], v[40:43]
	v_mfma_f32_16x16x32_bf16 v[36:39], v[192:195], v[142:145], v[36:39]
	v_mfma_f32_16x16x32_bf16 v[32:35], v[192:195], v[150:153], v[32:35]
	v_mfma_f32_16x16x32_bf16 v[28:31], v[154:157], v[196:199], v[28:31]
	v_mfma_f32_16x16x32_bf16 v[24:27], v[154:157], v[204:207], v[24:27]
	v_mfma_f32_16x16x32_bf16 v[20:23], v[162:165], v[196:199], v[20:23]
	v_mfma_f32_16x16x32_bf16 v[16:19], v[162:165], v[204:207], v[16:19]
	v_mfma_f32_16x16x32_bf16 v[12:15], v[180:183], v[196:199], v[12:15]
	v_mfma_f32_16x16x32_bf16 v[8:11], v[180:183], v[204:207], v[8:11]
	v_mfma_f32_16x16x32_bf16 v[4:7], v[188:191], v[196:199], v[4:7]
	v_mfma_f32_16x16x32_bf16 v[0:3], v[188:191], v[204:207], v[0:3]
	v_mfma_f32_16x16x32_bf16 v[28:31], v[158:161], v[200:203], v[28:31]
	v_mfma_f32_16x16x32_bf16 v[24:27], v[158:161], v[208:211], v[24:27]
	v_mfma_f32_16x16x32_bf16 v[20:23], v[172:175], v[200:203], v[20:23]
	v_mfma_f32_16x16x32_bf16 v[16:19], v[172:175], v[208:211], v[16:19]
	v_mfma_f32_16x16x32_bf16 v[12:15], v[184:187], v[200:203], v[12:15]
	v_mfma_f32_16x16x32_bf16 v[8:11], v[184:187], v[208:211], v[8:11]
	v_mfma_f32_16x16x32_bf16 v[4:7], v[192:195], v[200:203], v[4:7]
	v_mfma_f32_16x16x32_bf16 v[0:3], v[192:195], v[208:211], v[0:3]
	s_setprio 0
	s_add_i32 s24, s24, 2
	s_add_u32 s4, s4, 0x100
	s_addc_u32 s5, s5, 0
	s_add_u32 s22, s22, 0x100
	s_addc_u32 s23, s23, 0
	s_cmp_ge_i32 s24, s21
	s_barrier
	s_cbranch_scc0 .LBB0_879

; #define STAGE(P, BASE, br, kt) do { const char* _g = (const char*)((BASE) + (size_t)(br) * K + (size_t)(kt) * G_BK); \
;     _Pragma("unroll") for (int _i = 0; _i < 2; ++_i) { \
;       __builtin_amdgcn_global_load_lds((const unsigned*)(_g + (size_t)_i * 128 * K + sg_off), (unsigned*)((char*)(P) + wid * 1024 + _i * 8192), 16, 0, 0); } } while (0)
; #define LDA(dst, b, h) _Pragma("unroll") for (int m = 0; m < 4; ++m) _Pragma("unroll") for (int k = 0; k < 2; ++k) \
;     dst[m][k] = *reinterpret_cast<const bf16x8*>((const char*)shm + aoff + (((b) * 2 + (h)) * 16384 + m * 2048 + k * 1024))
; #define LDB(dst, b, h) _Pragma("unroll") for (int n = 0; n < 2; ++n) _Pragma("unroll") for (int k = 0; k < 2; ++k) \
;     dst[n][k] = *reinterpret_cast<const bf16x8*>((const char*)shm + boff + (((b) * 2 + (h)) * 16384 + n * 2048 + k * 1024))
; #define MMA(ai, bj, At, Bt_) do { __builtin_amdgcn_s_setprio(1); \
;     _Pragma("unroll") for (int m = 0; m < 4; ++m) _Pragma("unroll") for (int n = 0; n < 2; ++n) _Pragma("unroll") for (int k = 0; k < 2; ++k) \
;       acc[ai][bj][m][n] = mfma16(At[m][k], Bt_[n][k], acc[ai][bj][m][n]); \
;     __builtin_amdgcn_s_setprio(0); } while (0)
; #define WAIT_V(n) asm volatile("s_waitcnt vmcnt(" #n ")" ::: "memory")
; #define WAIT_L(n) asm volatile("s_waitcnt lgkmcnt(" #n ")" ::: "memory")
; #define BAR __builtin_amdgcn_s_barrier()
; #define SCHED __builtin_amdgcn_sched_barrier(0)
; template <class Epi>
; __device__ __forceinline__ void gemm_phase(const bfr* __restrict__ A, int lda, const bfr* __restrict__ Bt, int K,
;                                            int nM, int nN, const Epi& epi, bfr* shm, int wv, int nMfull, int ksplit) {
;     ...
;       LDB(B0, 0, 0); SCHED; LDA(At, 0, 0); STAGE(SA(1, 1), Ak, brow + G_HALF, t + 1);
;       WAIT_L(8); BAR; WAIT_L(0); MMA(0, 0, At, B0); BAR; SCHED;
;       LDB(B1, 0, 1); STAGE(SB(0, 0), Bk, bcol, t + 2);
;       BAR; WAIT_L(0); MMA(0, 1, At, B1); BAR;
;       LDA(At, 0, 1); STAGE(SA(0, 0), Ak, brow, t + 2);
;       BAR; WAIT_L(0); MMA(1, 0, At, B0); BAR; SCHED;
;       STAGE(SB(0, 1), Bk, bcol + G_HALF, t + 2);
;       WAIT_V(6); BAR; MMA(1, 1, At, B1); BAR;
.LBB0_935:
	ds_read_b128 v[138:141], v179
	ds_read_b128 v[142:145], v179 offset:1024
	ds_read_b128 v[146:149], v179 offset:2048
	ds_read_b128 v[150:153], v179 offset:3072
	ds_read_b128 v[154:157], v178
	ds_read_b128 v[158:161], v178 offset:1024
	ds_read_b128 v[162:165], v178 offset:2048
	ds_read_b128 v[166:169], v178 offset:3072
	ds_read_b128 v[170:173], v178 offset:4096
	ds_read_b128 v[174:177], v178 offset:5120
	ds_read_b128 v[184:187], v178 offset:6144
	ds_read_b128 v[188:191], v178 offset:7168
	ds_read_b128 v[192:195], v179 offset:16384
	ds_read_b128 v[196:199], v179 offset:17408
	ds_read_b128 v[200:203], v179 offset:18432
	ds_read_b128 v[204:207], v179 offset:19456
	v_lshl_add_u64 v[208:209], s[30:31], 0, v[136:137]
	v_lshl_add_u64 v[210:211], s[36:37], 0, v[136:137]
	s_mov_b32 m0, s50
	v_lshl_add_u64 v[214:215], v[208:209], 0, s[12:13]
	global_load_lds_dwordx4 v[214:215], off
	s_mov_b32 m0, s51
	v_lshl_add_u64 v[216:217], v[208:209], 0, s[14:15]
	global_load_lds_dwordx4 v[216:217], off
	s_waitcnt lgkmcnt(0)
	s_barrier
	s_setprio 1
	v_mfma_f32_16x16x32_bf16 v[124:127], v[154:157], v[138:141], v[124:127]
	v_mfma_f32_16x16x32_bf16 v[120:123], v[154:157], v[146:149], v[120:123]
	v_mfma_f32_16x16x32_bf16 v[116:119], v[162:165], v[138:141], v[116:119]
	v_mfma_f32_16x16x32_bf16 v[112:115], v[162:165], v[146:149], v[112:115]
	v_mfma_f32_16x16x32_bf16 v[108:111], v[170:173], v[138:141], v[108:111]
	v_mfma_f32_16x16x32_bf16 v[104:107], v[170:173], v[146:149], v[104:107]
	v_mfma_f32_16x16x32_bf16 v[100:103], v[184:187], v[138:141], v[100:103]
	v_mfma_f32_16x16x32_bf16 v[96:99], v[184:187], v[146:149], v[96:99]
	v_mfma_f32_16x16x32_bf16 v[124:127], v[158:161], v[142:145], v[124:127]
	v_mfma_f32_16x16x32_bf16 v[120:123], v[158:161], v[150:153], v[120:123]
	v_mfma_f32_16x16x32_bf16 v[116:119], v[166:169], v[142:145], v[116:119]
	v_mfma_f32_16x16x32_bf16 v[112:115], v[166:169], v[150:153], v[112:115]
	v_mfma_f32_16x16x32_bf16 v[108:111], v[174:177], v[142:145], v[108:111]
	v_mfma_f32_16x16x32_bf16 v[104:107], v[174:177], v[150:153], v[104:107]
	v_mfma_f32_16x16x32_bf16 v[100:103], v[188:191], v[142:145], v[100:103]
	v_mfma_f32_16x16x32_bf16 v[96:99], v[188:191], v[150:153], v[96:99]
	v_mfma_f32_16x16x32_bf16 v[92:95], v[154:157], v[192:195], v[92:95]
	v_mfma_f32_16x16x32_bf16 v[88:91], v[154:157], v[200:203], v[88:91]
	v_mfma_f32_16x16x32_bf16 v[84:87], v[162:165], v[192:195], v[84:87]
	v_mfma_f32_16x16x32_bf16 v[80:83], v[162:165], v[200:203], v[80:83]
	v_mfma_f32_16x16x32_bf16 v[76:79], v[170:173], v[192:195], v[76:79]
	v_mfma_f32_16x16x32_bf16 v[72:75], v[170:173], v[200:203], v[72:75]
	v_mfma_f32_16x16x32_bf16 v[68:71], v[184:187], v[192:195], v[68:71]
	v_mfma_f32_16x16x32_bf16 v[64:67], v[184:187], v[200:203], v[64:67]
	v_mfma_f32_16x16x32_bf16 v[92:95], v[158:161], v[196:199], v[92:95]
	v_mfma_f32_16x16x32_bf16 v[88:91], v[158:161], v[204:207], v[88:91]
	v_mfma_f32_16x16x32_bf16 v[84:87], v[166:169], v[196:199], v[84:87]
	v_mfma_f32_16x16x32_bf16 v[80:83], v[166:169], v[204:207], v[80:83]
	v_mfma_f32_16x16x32_bf16 v[76:79], v[174:177], v[196:199], v[76:79]
	v_mfma_f32_16x16x32_bf16 v[72:75], v[174:177], v[204:207], v[72:75]
	v_mfma_f32_16x16x32_bf16 v[68:71], v[188:191], v[196:199], v[68:71]
	v_mfma_f32_16x16x32_bf16 v[64:67], v[188:191], v[204:207], v[64:67]
	s_setprio 0
	s_barrier
	ds_read_b128 v[154:157], v178 offset:16384
	ds_read_b128 v[158:161], v178 offset:17408
	ds_read_b128 v[162:165], v178 offset:18432
	ds_read_b128 v[166:169], v178 offset:19456
	ds_read_b128 v[170:173], v178 offset:20480
	ds_read_b128 v[174:177], v178 offset:21504
	ds_read_b128 v[184:187], v178 offset:22528
	ds_read_b128 v[188:191], v178 offset:23552
	s_mov_b32 m0, s52
	s_mov_b64 s[40:41], 0xb00100
	v_lshl_add_u64 v[218:219], v[210:211], 0, s[40:41]
	global_load_lds_dwordx4 v[218:219], off
	s_mov_b32 m0, s53
	s_mov_b64 s[40:41], 0xb58100
	v_lshl_add_u64 v[214:215], v[210:211], 0, s[40:41]
	global_load_lds_dwordx4 v[214:215], off
	s_mov_b32 m0, s49
	s_mov_b64 s[40:41], 0x100
	v_lshl_add_u64 v[216:217], v[208:209], 0, s[40:41]
	global_load_lds_dwordx4 v[216:217], off
	s_mov_b32 m0, s54
	s_mov_b64 s[40:41], 0x58100
	v_lshl_add_u64 v[218:219], v[208:209], 0, s[40:41]
	global_load_lds_dwordx4 v[218:219], off
	s_mov_b32 m0, s55
	s_mov_b64 s[40:41], 0xbb0100
	v_lshl_add_u64 v[214:215], v[210:211], 0, s[40:41]
	global_load_lds_dwordx4 v[214:215], off
	s_mov_b32 m0, s56
	s_mov_b64 s[40:41], 0xc08100
	v_lshl_add_u64 v[216:217], v[210:211], 0, s[40:41]
	global_load_lds_dwordx4 v[216:217], off
	s_waitcnt vmcnt(6)
	s_waitcnt lgkmcnt(0)
	s_barrier
; #define STAGE(P, BASE, br, kt) do { const char* _g = (const char*)((BASE) + (size_t)(br) * K + (size_t)(kt) * G_BK); \
;     _Pragma("unroll") for (int _i = 0; _i < 2; ++_i) { \
;       __builtin_amdgcn_global_load_lds((const unsigned*)(_g + (size_t)_i * 128 * K + sg_off), (unsigned*)((char*)(P) + wid * 1024 + _i * 8192), 16, 0, 0); } } while (0)
; #define LDA(dst, b, h) _Pragma("unroll") for (int m = 0; m < 4; ++m) _Pragma("unroll") for (int k = 0; k < 2; ++k) \
;     dst[m][k] = *reinterpret_cast<const bf16x8*>((const char*)shm + aoff + (((b) * 2 + (h)) * 16384 + m * 2048 + k * 1024))
; #define LDB(dst, b, h) _Pragma("unroll") for (int n = 0; n < 2; ++n) _Pragma("unroll") for (int k = 0; k < 2; ++k) \
;     dst[n][k] = *reinterpret_cast<const bf16x8*>((const char*)shm + boff + (((b) * 2 + (h)) * 16384 + n * 2048 + k * 1024))
; #define MMA(ai, bj, At, Bt_) do { __builtin_amdgcn_s_setprio(1); \
;     _Pragma("unroll") for (int m = 0; m < 4; ++m) _Pragma("unroll") for (int n = 0; n < 2; ++n) _Pragma("unroll") for (int k = 0; k < 2; ++k) \
;       acc[ai][bj][m][n] = mfma16(At[m][k], Bt_[n][k], acc[ai][bj][m][n]); \
;     __builtin_amdgcn_s_setprio(0); } while (0)
; #define WAIT_V(n) asm volatile("s_waitcnt vmcnt(" #n ")" ::: "memory")
; #define WAIT_L(n) asm volatile("s_waitcnt lgkmcnt(" #n ")" ::: "memory")
; #define BAR __builtin_amdgcn_s_barrier()
; #define SCHED __builtin_amdgcn_sched_barrier(0)
; template <class Epi>
; __device__ __forceinline__ void gemm_phase(const bfr* __restrict__ A, int lda, const bfr* __restrict__ Bt, int K,
;                                            int nM, int nN, const Epi& epi, bfr* shm, int wv, int nMfull, int ksplit) {
;     ...
;       BAR; WAIT_L(0); MMA(0, 1, At, B1); BAR;
;       LDA(At, 0, 1); STAGE(SA(0, 0), Ak, brow, t + 2);
;       BAR; WAIT_L(0); MMA(1, 0, At, B0); BAR; SCHED;
;       STAGE(SB(0, 1), Bk, bcol + G_HALF, t + 2);
;       WAIT_V(6); BAR; MMA(1, 1, At, B1); BAR;
;       LDB(B0, 1, 0); SCHED; LDA(At, 1, 0); STAGE(SA(0, 1), Ak, brow + G_HALF, t + 2);
;       WAIT_L(8); BAR; WAIT_L(0); MMA(0, 0, At, B0); BAR; SCHED;
;       LDB(B1, 1, 1); STAGE(SB(1, 0), Bk, bcol, t + 3);
;       BAR; WAIT_L(0); MMA(0, 1, At, B1); BAR;
;       LDA(At, 1, 1); STAGE(SA(1, 0), Ak, brow, t + 3);
;       BAR; WAIT_L(0); MMA(1, 0, At, B0); BAR; SCHED;
	s_setprio 1
	v_mfma_f32_16x16x32_bf16 v[60:63], v[154:157], v[138:141], v[60:63]
	v_mfma_f32_16x16x32_bf16 v[56:59], v[154:157], v[146:149], v[56:59]
	v_mfma_f32_16x16x32_bf16 v[52:55], v[162:165], v[138:141], v[52:55]
	v_mfma_f32_16x16x32_bf16 v[48:51], v[162:165], v[146:149], v[48:51]
	v_mfma_f32_16x16x32_bf16 v[44:47], v[170:173], v[138:141], v[44:47]
	v_mfma_f32_16x16x32_bf16 v[40:43], v[170:173], v[146:149], v[40:43]
	v_mfma_f32_16x16x32_bf16 v[36:39], v[184:187], v[138:141], v[36:39]
	v_mfma_f32_16x16x32_bf16 v[32:35], v[184:187], v[146:149], v[32:35]
	v_mfma_f32_16x16x32_bf16 v[60:63], v[158:161], v[142:145], v[60:63]
	v_mfma_f32_16x16x32_bf16 v[56:59], v[158:161], v[150:153], v[56:59]
	v_mfma_f32_16x16x32_bf16 v[52:55], v[166:169], v[142:145], v[52:55]
	v_mfma_f32_16x16x32_bf16 v[48:51], v[166:169], v[150:153], v[48:51]
	v_mfma_f32_16x16x32_bf16 v[44:47], v[174:177], v[142:145], v[44:47]
	v_mfma_f32_16x16x32_bf16 v[40:43], v[174:177], v[150:153], v[40:43]
	v_mfma_f32_16x16x32_bf16 v[36:39], v[188:191], v[142:145], v[36:39]
	v_mfma_f32_16x16x32_bf16 v[32:35], v[188:191], v[150:153], v[32:35]
	v_mfma_f32_16x16x32_bf16 v[28:31], v[154:157], v[192:195], v[28:31]
	v_mfma_f32_16x16x32_bf16 v[24:27], v[154:157], v[200:203], v[24:27]
	v_mfma_f32_16x16x32_bf16 v[20:23], v[162:165], v[192:195], v[20:23]
	v_mfma_f32_16x16x32_bf16 v[16:19], v[162:165], v[200:203], v[16:19]
	v_mfma_f32_16x16x32_bf16 v[12:15], v[170:173], v[192:195], v[12:15]
	v_mfma_f32_16x16x32_bf16 v[8:11], v[170:173], v[200:203], v[8:11]
	v_mfma_f32_16x16x32_bf16 v[4:7], v[184:187], v[192:195], v[4:7]
	v_mfma_f32_16x16x32_bf16 v[0:3], v[184:187], v[200:203], v[0:3]
	v_mfma_f32_16x16x32_bf16 v[28:31], v[158:161], v[196:199], v[28:31]
	v_mfma_f32_16x16x32_bf16 v[24:27], v[158:161], v[204:207], v[24:27]
	v_mfma_f32_16x16x32_bf16 v[20:23], v[166:169], v[196:199], v[20:23]
	v_mfma_f32_16x16x32_bf16 v[16:19], v[166:169], v[204:207], v[16:19]
	v_mfma_f32_16x16x32_bf16 v[12:15], v[174:177], v[196:199], v[12:15]
	v_mfma_f32_16x16x32_bf16 v[8:11], v[174:177], v[204:207], v[8:11]
	v_mfma_f32_16x16x32_bf16 v[4:7], v[188:191], v[196:199], v[4:7]
	v_mfma_f32_16x16x32_bf16 v[0:3], v[188:191], v[204:207], v[0:3]
	s_setprio 0
	s_barrier
	ds_read_b128 v[138:141], v179 offset:32768
	ds_read_b128 v[142:145], v179 offset:33792
	ds_read_b128 v[146:149], v179 offset:34816
	ds_read_b128 v[150:153], v179 offset:35840
	ds_read_b128 v[154:157], v178 offset:32768
	ds_read_b128 v[158:161], v178 offset:33792
	ds_read_b128 v[162:165], v178 offset:34816
	ds_read_b128 v[166:169], v178 offset:35840
	ds_read_b128 v[170:173], v178 offset:36864
	ds_read_b128 v[174:177], v178 offset:37888
	ds_read_b128 v[184:187], v178 offset:38912
	ds_read_b128 v[188:191], v178 offset:39936
	ds_read_b128 v[192:195], v179 offset:49152
	ds_read_b128 v[196:199], v179 offset:50176
	ds_read_b128 v[200:203], v179 offset:51200
	ds_read_b128 v[204:207], v179 offset:52224
	s_mov_b32 m0, s57
	s_mov_b64 s[40:41], 0xb0100
	v_lshl_add_u64 v[218:219], v[208:209], 0, s[40:41]
	global_load_lds_dwordx4 v[218:219], off
	s_mov_b32 m0, s58
	s_mov_b64 s[40:41], 0x108100
	v_lshl_add_u64 v[214:215], v[208:209], 0, s[40:41]
	global_load_lds_dwordx4 v[214:215], off
	s_waitcnt lgkmcnt(0)
	s_barrier
	s_setprio 1
	v_mfma_f32_16x16x32_bf16 v[124:127], v[154:157], v[138:141], v[124:127]
	v_mfma_f32_16x16x32_bf16 v[120:123], v[154:157], v[146:149], v[120:123]
	v_mfma_f32_16x16x32_bf16 v[116:119], v[162:165], v[138:141], v[116:119]
	v_mfma_f32_16x16x32_bf16 v[112:115], v[162:165], v[146:149], v[112:115]
	v_mfma_f32_16x16x32_bf16 v[108:111], v[170:173], v[138:141], v[108:111]
	v_mfma_f32_16x16x32_bf16 v[104:107], v[170:173], v[146:149], v[104:107]
	v_mfma_f32_16x16x32_bf16 v[100:103], v[184:187], v[138:141], v[100:103]
	v_mfma_f32_16x16x32_bf16 v[96:99], v[184:187], v[146:149], v[96:99]
	v_mfma_f32_16x16x32_bf16 v[124:127], v[158:161], v[142:145], v[124:127]
	v_mfma_f32_16x16x32_bf16 v[120:123], v[158:161], v[150:153], v[120:123]
	v_mfma_f32_16x16x32_bf16 v[116:119], v[166:169], v[142:145], v[116:119]
	v_mfma_f32_16x16x32_bf16 v[112:115], v[166:169], v[150:153], v[112:115]
	v_mfma_f32_16x16x32_bf16 v[108:111], v[174:177], v[142:145], v[108:111]
	v_mfma_f32_16x16x32_bf16 v[104:107], v[174:177], v[150:153], v[104:107]
	v_mfma_f32_16x16x32_bf16 v[100:103], v[188:191], v[142:145], v[100:103]
	v_mfma_f32_16x16x32_bf16 v[96:99], v[188:191], v[150:153], v[96:99]
	v_mfma_f32_16x16x32_bf16 v[92:95], v[154:157], v[192:195], v[92:95]
	v_mfma_f32_16x16x32_bf16 v[88:91], v[154:157], v[200:203], v[88:91]
	v_mfma_f32_16x16x32_bf16 v[84:87], v[162:165], v[192:195], v[84:87]
	v_mfma_f32_16x16x32_bf16 v[80:83], v[162:165], v[200:203], v[80:83]
	v_mfma_f32_16x16x32_bf16 v[76:79], v[170:173], v[192:195], v[76:79]
	v_mfma_f32_16x16x32_bf16 v[72:75], v[170:173], v[200:203], v[72:75]
	v_mfma_f32_16x16x32_bf16 v[68:71], v[184:187], v[192:195], v[68:71]
	v_mfma_f32_16x16x32_bf16 v[64:67], v[184:187], v[200:203], v[64:67]
	v_mfma_f32_16x16x32_bf16 v[92:95], v[158:161], v[196:199], v[92:95]
	v_mfma_f32_16x16x32_bf16 v[88:91], v[158:161], v[204:207], v[88:91]
	v_mfma_f32_16x16x32_bf16 v[84:87], v[166:169], v[196:199], v[84:87]
	v_mfma_f32_16x16x32_bf16 v[80:83], v[166:169], v[204:207], v[80:83]
	v_mfma_f32_16x16x32_bf16 v[76:79], v[174:177], v[196:199], v[76:79]
	v_mfma_f32_16x16x32_bf16 v[72:75], v[174:177], v[204:207], v[72:75]
	v_mfma_f32_16x16x32_bf16 v[68:71], v[188:191], v[196:199], v[68:71]
	v_mfma_f32_16x16x32_bf16 v[64:67], v[188:191], v[204:207], v[64:67]
	s_setprio 0
	s_barrier
; #define STAGE(P, BASE, br, kt) do { const char* _g = (const char*)((BASE) + (size_t)(br) * K + (size_t)(kt) * G_BK); \
;     _Pragma("unroll") for (int _i = 0; _i < 2; ++_i) { \
;       __builtin_amdgcn_global_load_lds((const unsigned*)(_g + (size_t)_i * 128 * K + sg_off), (unsigned*)((char*)(P) + wid * 1024 + _i * 8192), 16, 0, 0); } } while (0)
; #define LDA(dst, b, h) _Pragma("unroll") for (int m = 0; m < 4; ++m) _Pragma("unroll") for (int k = 0; k < 2; ++k) \
;     dst[m][k] = *reinterpret_cast<const bf16x8*>((const char*)shm + aoff + (((b) * 2 + (h)) * 16384 + m * 2048 + k * 1024))
; #define LDB(dst, b, h) _Pragma("unroll") for (int n = 0; n < 2; ++n) _Pragma("unroll") for (int k = 0; k < 2; ++k) \
;     dst[n][k] = *reinterpret_cast<const bf16x8*>((const char*)shm + boff + (((b) * 2 + (h)) * 16384 + n * 2048 + k * 1024))
; #define WAIT_V(n) asm volatile("s_waitcnt vmcnt(" #n ")" ::: "memory")
; #define WAIT_L(n) asm volatile("s_waitcnt lgkmcnt(" #n ")" ::: "memory")
; #define BAR __builtin_amdgcn_s_barrier()
; #define SCHED __builtin_amdgcn_sched_barrier(0)
; template <class Epi>
; __device__ __forceinline__ void gemm_phase(const bfr* __restrict__ A, int lda, const bfr* __restrict__ Bt, int K,
;                                            int nM, int nN, const Epi& epi, bfr* shm, int wv, int nMfull, int ksplit) {
;     ...
;     for (int t = 0; t < nt - 2; t += 2) {
;       LDB(B0, 0, 0); SCHED; LDA(At, 0, 0); STAGE(SA(1, 1), Ak, brow + G_HALF, t + 1);
;       WAIT_L(8); BAR; WAIT_L(0); MMA(0, 0, At, B0); BAR; SCHED;
;       LDB(B1, 0, 1); STAGE(SB(0, 0), Bk, bcol, t + 2);
;       BAR; WAIT_L(0); MMA(0, 1, At, B1); BAR;
;       LDA(At, 0, 1); STAGE(SA(0, 0), Ak, brow, t + 2);
;       BAR; WAIT_L(0); MMA(1, 0, At, B0); BAR; SCHED;
;       STAGE(SB(0, 1), Bk, bcol + G_HALF, t + 2);
;       WAIT_V(6); BAR; MMA(1, 1, At, B1); BAR;
;       LDB(B0, 1, 0); SCHED; LDA(At, 1, 0); STAGE(SA(0, 1), Ak, brow + G_HALF, t + 2);
;       WAIT_L(8); BAR; WAIT_L(0); MMA(0, 0, At, B0); BAR; SCHED;
;       LDB(B1, 1, 1); STAGE(SB(1, 0), Bk, bcol, t + 3);
;       BAR; WAIT_L(0); MMA(0, 1, At, B1); BAR;
;       LDA(At, 1, 1); STAGE(SA(1, 0), Ak, brow, t + 3);
;       BAR; WAIT_L(0); MMA(1, 0, At, B0); BAR; SCHED;
;       STAGE(SB(1, 1), Bk, bcol + G_HALF, t + 3);
;       WAIT_V(6); BAR; MMA(1, 1, At, B1); BAR;
;     }
	ds_read_b128 v[154:157], v178 offset:49152
	ds_read_b128 v[158:161], v178 offset:50176
	ds_read_b128 v[162:165], v178 offset:51200
	ds_read_b128 v[166:169], v178 offset:52224
	ds_read_b128 v[170:173], v178 offset:53248
	ds_read_b128 v[174:177], v178 offset:54272
	ds_read_b128 v[184:187], v178 offset:55296
	ds_read_b128 v[188:191], v178 offset:56320
	s_mov_b32 m0, s59
	s_mov_b64 s[40:41], 0xb00180
	v_lshl_add_u64 v[216:217], v[210:211], 0, s[40:41]
	global_load_lds_dwordx4 v[216:217], off
	s_mov_b32 m0, s82
	s_mov_b64 s[40:41], 0xb58180
	v_lshl_add_u64 v[218:219], v[210:211], 0, s[40:41]
	global_load_lds_dwordx4 v[218:219], off
	s_mov_b32 m0, s83
	s_mov_b64 s[40:41], 0x180
	v_lshl_add_u64 v[214:215], v[208:209], 0, s[40:41]
	global_load_lds_dwordx4 v[214:215], off
	s_mov_b32 m0, s84
	s_mov_b64 s[40:41], 0x58180
	v_lshl_add_u64 v[216:217], v[208:209], 0, s[40:41]
	global_load_lds_dwordx4 v[216:217], off
	s_mov_b32 m0, s85
	s_mov_b64 s[40:41], 0xbb0180
	v_lshl_add_u64 v[218:219], v[210:211], 0, s[40:41]
	global_load_lds_dwordx4 v[218:219], off
	s_mov_b32 m0, s90
	s_mov_b64 s[40:41], 0xc08180
	v_lshl_add_u64 v[214:215], v[210:211], 0, s[40:41]
	global_load_lds_dwordx4 v[214:215], off
	s_waitcnt vmcnt(6)
	s_waitcnt lgkmcnt(0)
	s_barrier
	s_setprio 1
	v_mfma_f32_16x16x32_bf16 v[60:63], v[154:157], v[138:141], v[60:63]
	v_mfma_f32_16x16x32_bf16 v[56:59], v[154:157], v[146:149], v[56:59]
	v_mfma_f32_16x16x32_bf16 v[52:55], v[162:165], v[138:141], v[52:55]
	v_mfma_f32_16x16x32_bf16 v[48:51], v[162:165], v[146:149], v[48:51]
	v_mfma_f32_16x16x32_bf16 v[44:47], v[170:173], v[138:141], v[44:47]
	v_mfma_f32_16x16x32_bf16 v[40:43], v[170:173], v[146:149], v[40:43]
	v_mfma_f32_16x16x32_bf16 v[36:39], v[184:187], v[138:141], v[36:39]
	v_mfma_f32_16x16x32_bf16 v[32:35], v[184:187], v[146:149], v[32:35]
	v_mfma_f32_16x16x32_bf16 v[60:63], v[158:161], v[142:145], v[60:63]
	v_mfma_f32_16x16x32_bf16 v[56:59], v[158:161], v[150:153], v[56:59]
	v_mfma_f32_16x16x32_bf16 v[52:55], v[166:169], v[142:145], v[52:55]
	v_mfma_f32_16x16x32_bf16 v[48:51], v[166:169], v[150:153], v[48:51]
	v_mfma_f32_16x16x32_bf16 v[44:47], v[174:177], v[142:145], v[44:47]
	v_mfma_f32_16x16x32_bf16 v[40:43], v[174:177], v[150:153], v[40:43]
	v_mfma_f32_16x16x32_bf16 v[36:39], v[188:191], v[142:145], v[36:39]
	v_mfma_f32_16x16x32_bf16 v[32:35], v[188:191], v[150:153], v[32:35]
	v_mfma_f32_16x16x32_bf16 v[28:31], v[154:157], v[192:195], v[28:31]
	v_mfma_f32_16x16x32_bf16 v[24:27], v[154:157], v[200:203], v[24:27]
	v_mfma_f32_16x16x32_bf16 v[20:23], v[162:165], v[192:195], v[20:23]
	v_mfma_f32_16x16x32_bf16 v[16:19], v[162:165], v[200:203], v[16:19]
	v_mfma_f32_16x16x32_bf16 v[12:15], v[170:173], v[192:195], v[12:15]
	v_mfma_f32_16x16x32_bf16 v[8:11], v[170:173], v[200:203], v[8:11]
	v_mfma_f32_16x16x32_bf16 v[4:7], v[184:187], v[192:195], v[4:7]
	v_mfma_f32_16x16x32_bf16 v[0:3], v[184:187], v[200:203], v[0:3]
	v_mfma_f32_16x16x32_bf16 v[28:31], v[158:161], v[196:199], v[28:31]
	v_mfma_f32_16x16x32_bf16 v[24:27], v[158:161], v[204:207], v[24:27]
	v_mfma_f32_16x16x32_bf16 v[20:23], v[166:169], v[196:199], v[20:23]
	v_mfma_f32_16x16x32_bf16 v[16:19], v[166:169], v[204:207], v[16:19]
	v_mfma_f32_16x16x32_bf16 v[12:15], v[174:177], v[196:199], v[12:15]
	v_mfma_f32_16x16x32_bf16 v[8:11], v[174:177], v[204:207], v[8:11]
	v_mfma_f32_16x16x32_bf16 v[4:7], v[188:191], v[196:199], v[4:7]
	v_mfma_f32_16x16x32_bf16 v[0:3], v[188:191], v[204:207], v[0:3]
	s_setprio 0
	s_add_i32 s39, s39, 2
	s_add_u32 s36, s36, 0x100
	s_addc_u32 s37, s37, 0
	s_add_u32 s30, s30, 0x100
	s_addc_u32 s31, s31, 0
	s_cmp_ge_i32 s39, s35
	s_barrier
	s_cbranch_scc0 .LBB0_935

; #define STAGE(P, BASE, br, kt) do { const char* _g = (const char*)((BASE) + (size_t)(br) * K + (size_t)(kt) * G_BK); \
;     _Pragma("unroll") for (int _i = 0; _i < 2; ++_i) { \
;       __builtin_amdgcn_global_load_lds((const unsigned*)(_g + (size_t)_i * 128 * K + sg_off), (unsigned*)((char*)(P) + wid * 1024 + _i * 8192), 16, 0, 0); } } while (0)
; #define LDA(dst, b, h) _Pragma("unroll") for (int m = 0; m < 4; ++m) _Pragma("unroll") for (int k = 0; k < 2; ++k) \
;     dst[m][k] = *reinterpret_cast<const bf16x8*>((const char*)shm + aoff + (((b) * 2 + (h)) * 16384 + m * 2048 + k * 1024))
; #define LDB(dst, b, h) _Pragma("unroll") for (int n = 0; n < 2; ++n) _Pragma("unroll") for (int k = 0; k < 2; ++k) \
;     dst[n][k] = *reinterpret_cast<const bf16x8*>((const char*)shm + boff + (((b) * 2 + (h)) * 16384 + n * 2048 + k * 1024))
; #define MMA(ai, bj, At, Bt_) do { __builtin_amdgcn_s_setprio(1); \
;     _Pragma("unroll") for (int m = 0; m < 4; ++m) _Pragma("unroll") for (int n = 0; n < 2; ++n) _Pragma("unroll") for (int k = 0; k < 2; ++k) \
;       acc[ai][bj][m][n] = mfma16(At[m][k], Bt_[n][k], acc[ai][bj][m][n]); \
;     __builtin_amdgcn_s_setprio(0); } while (0)
; #define WAIT_V(n) asm volatile("s_waitcnt vmcnt(" #n ")" ::: "memory")
; #define WAIT_L(n) asm volatile("s_waitcnt lgkmcnt(" #n ")" ::: "memory")
; #define BAR __builtin_amdgcn_s_barrier()
; #define SCHED __builtin_amdgcn_sched_barrier(0)
; template <class Epi>
; __device__ __forceinline__ void gemm_phase(const bfr* __restrict__ A, int lda, const bfr* __restrict__ Bt, int K,
;                                            int nM, int nN, const Epi& epi, bfr* shm, int wv, int nMfull, int ksplit) {
;     ...
;       LDB(B0, 0, 0); SCHED; LDA(At, 0, 0); STAGE(SA(1, 1), Ak, brow + G_HALF, t + 1);
;       WAIT_L(8); BAR; WAIT_L(0); MMA(0, 0, At, B0); BAR; SCHED;
;       LDB(B1, 0, 1); STAGE(SB(0, 0), Bk, bcol, t + 2);
;       BAR; WAIT_L(0); MMA(0, 1, At, B1); BAR;
;       LDA(At, 0, 1); STAGE(SA(0, 0), Ak, brow, t + 2);
;       BAR; WAIT_L(0); MMA(1, 0, At, B0); BAR; SCHED;
;       STAGE(SB(0, 1), Bk, bcol + G_HALF, t + 2);
;       WAIT_V(6); BAR; MMA(1, 1, At, B1); BAR;
.LBB0_1086:
	ds_read_b128 v[148:151], v137
	ds_read_b128 v[152:155], v137 offset:1024
	ds_read_b128 v[162:165], v137 offset:2048
	ds_read_b128 v[166:169], v137 offset:3072
	ds_read_b128 v[170:173], v129
	ds_read_b128 v[174:177], v129 offset:1024
	ds_read_b128 v[178:181], v129 offset:2048
	ds_read_b128 v[182:185], v129 offset:3072
	ds_read_b128 v[186:189], v129 offset:4096
	ds_read_b128 v[190:193], v129 offset:5120
	ds_read_b128 v[194:197], v129 offset:6144
	ds_read_b128 v[198:201], v129 offset:7168
	ds_read_b128 v[202:205], v137 offset:16384
	ds_read_b128 v[206:209], v137 offset:17408
	ds_read_b128 v[210:213], v137 offset:18432
	ds_read_b128 v[214:217], v137 offset:19456
	v_lshl_add_u64 v[142:143], s[36:37], 0, v[140:141]
	v_lshl_add_u64 v[218:219], s[2:3], 0, v[140:141]
	s_mov_b32 m0, s95
	s_mov_b64 s[42:43], 0x40080
	v_lshl_add_u64 v[222:223], v[142:143], 0, s[42:43]
	global_load_lds_dwordx4 v[222:223], off
	s_mov_b32 m0, s96
	s_mov_b64 s[42:43], 0x60080
	v_lshl_add_u64 v[224:225], v[142:143], 0, s[42:43]
	global_load_lds_dwordx4 v[224:225], off
	s_waitcnt lgkmcnt(0)
	s_barrier
	s_setprio 1
	v_mfma_f32_16x16x32_bf16 v[124:127], v[170:173], v[148:151], v[124:127]
	v_mfma_f32_16x16x32_bf16 v[120:123], v[170:173], v[162:165], v[120:123]
	v_mfma_f32_16x16x32_bf16 v[116:119], v[178:181], v[148:151], v[116:119]
	v_mfma_f32_16x16x32_bf16 v[112:115], v[178:181], v[162:165], v[112:115]
	v_mfma_f32_16x16x32_bf16 v[108:111], v[186:189], v[148:151], v[108:111]
	v_mfma_f32_16x16x32_bf16 v[104:107], v[186:189], v[162:165], v[104:107]
	v_mfma_f32_16x16x32_bf16 v[100:103], v[194:197], v[148:151], v[100:103]
	v_mfma_f32_16x16x32_bf16 v[96:99], v[194:197], v[162:165], v[96:99]
	v_mfma_f32_16x16x32_bf16 v[124:127], v[174:177], v[152:155], v[124:127]
	v_mfma_f32_16x16x32_bf16 v[120:123], v[174:177], v[166:169], v[120:123]
	v_mfma_f32_16x16x32_bf16 v[116:119], v[182:185], v[152:155], v[116:119]
	v_mfma_f32_16x16x32_bf16 v[112:115], v[182:185], v[166:169], v[112:115]
	v_mfma_f32_16x16x32_bf16 v[108:111], v[190:193], v[152:155], v[108:111]
	v_mfma_f32_16x16x32_bf16 v[104:107], v[190:193], v[166:169], v[104:107]
	v_mfma_f32_16x16x32_bf16 v[100:103], v[198:201], v[152:155], v[100:103]
	v_mfma_f32_16x16x32_bf16 v[96:99], v[198:201], v[166:169], v[96:99]
	v_mfma_f32_16x16x32_bf16 v[92:95], v[170:173], v[202:205], v[92:95]
	v_mfma_f32_16x16x32_bf16 v[88:91], v[170:173], v[210:213], v[88:91]
	v_mfma_f32_16x16x32_bf16 v[84:87], v[178:181], v[202:205], v[84:87]
	v_mfma_f32_16x16x32_bf16 v[80:83], v[178:181], v[210:213], v[80:83]
	v_mfma_f32_16x16x32_bf16 v[76:79], v[186:189], v[202:205], v[76:79]
	v_mfma_f32_16x16x32_bf16 v[72:75], v[186:189], v[210:213], v[72:75]
	v_mfma_f32_16x16x32_bf16 v[68:71], v[194:197], v[202:205], v[68:71]
	v_mfma_f32_16x16x32_bf16 v[64:67], v[194:197], v[210:213], v[64:67]
	v_mfma_f32_16x16x32_bf16 v[92:95], v[174:177], v[206:209], v[92:95]
	v_mfma_f32_16x16x32_bf16 v[88:91], v[174:177], v[214:217], v[88:91]
	v_mfma_f32_16x16x32_bf16 v[84:87], v[182:185], v[206:209], v[84:87]
	v_mfma_f32_16x16x32_bf16 v[80:83], v[182:185], v[214:217], v[80:83]
	v_mfma_f32_16x16x32_bf16 v[76:79], v[190:193], v[206:209], v[76:79]
	v_mfma_f32_16x16x32_bf16 v[72:75], v[190:193], v[214:217], v[72:75]
	v_mfma_f32_16x16x32_bf16 v[68:71], v[198:201], v[206:209], v[68:71]
	v_mfma_f32_16x16x32_bf16 v[64:67], v[198:201], v[214:217], v[64:67]
	s_setprio 0
	s_barrier
	ds_read_b128 v[170:173], v129 offset:16384
	ds_read_b128 v[174:177], v129 offset:17408
	ds_read_b128 v[178:181], v129 offset:18432
	ds_read_b128 v[182:185], v129 offset:19456
	ds_read_b128 v[186:189], v129 offset:20480
	ds_read_b128 v[190:193], v129 offset:21504
	ds_read_b128 v[194:197], v129 offset:22528
	ds_read_b128 v[198:201], v129 offset:23552
	s_mov_b32 m0, s97
	v_lshl_add_u64 v[226:227], v[218:219], 0, s[8:9]
	global_load_lds_dwordx4 v[226:227], off
	s_mov_b32 m0, s92
	v_lshl_add_u64 v[222:223], v[218:219], 0, s[10:11]
	global_load_lds_dwordx4 v[222:223], off
	s_mov_b32 m0, s31
	v_lshl_add_u64 v[224:225], v[142:143], 0, s[8:9]
	global_load_lds_dwordx4 v[224:225], off
	s_mov_b32 m0, s94
	v_lshl_add_u64 v[226:227], v[142:143], 0, s[10:11]
	global_load_lds_dwordx4 v[226:227], off
	s_mov_b32 m0, s91
	v_lshl_add_u64 v[222:223], v[218:219], 0, s[12:13]
	global_load_lds_dwordx4 v[222:223], off
	s_mov_b32 m0, s93
	v_lshl_add_u64 v[224:225], v[218:219], 0, s[14:15]
	global_load_lds_dwordx4 v[224:225], off
	s_waitcnt vmcnt(6)
	s_waitcnt lgkmcnt(0)
	s_barrier
	s_setprio 1
	v_mfma_f32_16x16x32_bf16 v[60:63], v[170:173], v[148:151], v[60:63]
	v_mfma_f32_16x16x32_bf16 v[56:59], v[170:173], v[162:165], v[56:59]
	v_mfma_f32_16x16x32_bf16 v[52:55], v[178:181], v[148:151], v[52:55]
	v_mfma_f32_16x16x32_bf16 v[48:51], v[178:181], v[162:165], v[48:51]
	v_mfma_f32_16x16x32_bf16 v[44:47], v[186:189], v[148:151], v[44:47]
	v_mfma_f32_16x16x32_bf16 v[40:43], v[186:189], v[162:165], v[40:43]
	v_mfma_f32_16x16x32_bf16 v[36:39], v[194:197], v[148:151], v[36:39]
	v_mfma_f32_16x16x32_bf16 v[32:35], v[194:197], v[162:165], v[32:35]
	v_mfma_f32_16x16x32_bf16 v[60:63], v[174:177], v[152:155], v[60:63]
	v_mfma_f32_16x16x32_bf16 v[56:59], v[174:177], v[166:169], v[56:59]
	v_mfma_f32_16x16x32_bf16 v[52:55], v[182:185], v[152:155], v[52:55]
	v_mfma_f32_16x16x32_bf16 v[48:51], v[182:185], v[166:169], v[48:51]
	v_mfma_f32_16x16x32_bf16 v[44:47], v[190:193], v[152:155], v[44:47]
	v_mfma_f32_16x16x32_bf16 v[40:43], v[190:193], v[166:169], v[40:43]
	v_mfma_f32_16x16x32_bf16 v[36:39], v[198:201], v[152:155], v[36:39]
	v_mfma_f32_16x16x32_bf16 v[32:35], v[198:201], v[166:169], v[32:35]
	v_mfma_f32_16x16x32_bf16 v[28:31], v[170:173], v[202:205], v[28:31]
	v_mfma_f32_16x16x32_bf16 v[24:27], v[170:173], v[210:213], v[24:27]
	v_mfma_f32_16x16x32_bf16 v[20:23], v[178:181], v[202:205], v[20:23]
	v_mfma_f32_16x16x32_bf16 v[16:19], v[178:181], v[210:213], v[16:19]
	v_mfma_f32_16x16x32_bf16 v[12:15], v[186:189], v[202:205], v[12:15]
	v_mfma_f32_16x16x32_bf16 v[8:11], v[186:189], v[210:213], v[8:11]
	v_mfma_f32_16x16x32_bf16 v[4:7], v[194:197], v[202:205], v[4:7]
	v_mfma_f32_16x16x32_bf16 v[0:3], v[194:197], v[210:213], v[0:3]
	v_mfma_f32_16x16x32_bf16 v[28:31], v[174:177], v[206:209], v[28:31]
	v_mfma_f32_16x16x32_bf16 v[24:27], v[174:177], v[214:217], v[24:27]
	v_mfma_f32_16x16x32_bf16 v[20:23], v[182:185], v[206:209], v[20:23]
	v_mfma_f32_16x16x32_bf16 v[16:19], v[182:185], v[214:217], v[16:19]
	v_mfma_f32_16x16x32_bf16 v[12:15], v[190:193], v[206:209], v[12:15]
	v_mfma_f32_16x16x32_bf16 v[8:11], v[190:193], v[214:217], v[8:11]
	v_mfma_f32_16x16x32_bf16 v[4:7], v[198:201], v[206:209], v[4:7]
	v_mfma_f32_16x16x32_bf16 v[0:3], v[198:201], v[214:217], v[0:3]
	s_setprio 0
	s_barrier
; #define STAGE(P, BASE, br, kt) do { const char* _g = (const char*)((BASE) + (size_t)(br) * K + (size_t)(kt) * G_BK); \
;     _Pragma("unroll") for (int _i = 0; _i < 2; ++_i) { \
;       __builtin_amdgcn_global_load_lds((const unsigned*)(_g + (size_t)_i * 128 * K + sg_off), (unsigned*)((char*)(P) + wid * 1024 + _i * 8192), 16, 0, 0); } } while (0)
; #define LDA(dst, b, h) _Pragma("unroll") for (int m = 0; m < 4; ++m) _Pragma("unroll") for (int k = 0; k < 2; ++k) \
;     dst[m][k] = *reinterpret_cast<const bf16x8*>((const char*)shm + aoff + (((b) * 2 + (h)) * 16384 + m * 2048 + k * 1024))
; #define LDB(dst, b, h) _Pragma("unroll") for (int n = 0; n < 2; ++n) _Pragma("unroll") for (int k = 0; k < 2; ++k) \
;     dst[n][k] = *reinterpret_cast<const bf16x8*>((const char*)shm + boff + (((b) * 2 + (h)) * 16384 + n * 2048 + k * 1024))
; #define MMA(ai, bj, At, Bt_) do { __builtin_amdgcn_s_setprio(1); \
;     _Pragma("unroll") for (int m = 0; m < 4; ++m) _Pragma("unroll") for (int n = 0; n < 2; ++n) _Pragma("unroll") for (int k = 0; k < 2; ++k) \
;       acc[ai][bj][m][n] = mfma16(At[m][k], Bt_[n][k], acc[ai][bj][m][n]); \
;     __builtin_amdgcn_s_setprio(0); } while (0)
; #define WAIT_V(n) asm volatile("s_waitcnt vmcnt(" #n ")" ::: "memory")
; #define WAIT_L(n) asm volatile("s_waitcnt lgkmcnt(" #n ")" ::: "memory")
; #define BAR __builtin_amdgcn_s_barrier()
; #define SCHED __builtin_amdgcn_sched_barrier(0)
; template <class Epi>
; __device__ __forceinline__ void gemm_phase(const bfr* __restrict__ A, int lda, const bfr* __restrict__ Bt, int K,
;                                            int nM, int nN, const Epi& epi, bfr* shm, int wv, int nMfull, int ksplit) {
;     ...
;       LDB(B0, 1, 0); SCHED; LDA(At, 1, 0); STAGE(SA(0, 1), Ak, brow + G_HALF, t + 2);
;       WAIT_L(8); BAR; WAIT_L(0); MMA(0, 0, At, B0); BAR; SCHED;
;       LDB(B1, 1, 1); STAGE(SB(1, 0), Bk, bcol, t + 3);
;       BAR; WAIT_L(0); MMA(0, 1, At, B1); BAR;
;       LDA(At, 1, 1); STAGE(SA(1, 0), Ak, brow, t + 3);
;       BAR; WAIT_L(0); MMA(1, 0, At, B0); BAR; SCHED;
;       STAGE(SB(1, 1), Bk, bcol + G_HALF, t + 3);
;       WAIT_V(6); BAR; MMA(1, 1, At, B1); BAR;
;     }
	ds_read_b128 v[148:151], v137 offset:32768
	ds_read_b128 v[152:155], v137 offset:33792
	ds_read_b128 v[162:165], v137 offset:34816
	ds_read_b128 v[166:169], v137 offset:35840
	ds_read_b128 v[170:173], v129 offset:32768
	ds_read_b128 v[174:177], v129 offset:33792
	ds_read_b128 v[178:181], v129 offset:34816
	ds_read_b128 v[182:185], v129 offset:35840
	ds_read_b128 v[186:189], v129 offset:36864
	ds_read_b128 v[190:193], v129 offset:37888
	ds_read_b128 v[194:197], v129 offset:38912
	ds_read_b128 v[198:201], v129 offset:39936
	ds_read_b128 v[202:205], v137 offset:49152
	ds_read_b128 v[206:209], v137 offset:50176
	ds_read_b128 v[210:213], v137 offset:51200
	ds_read_b128 v[214:217], v137 offset:52224
	s_mov_b32 m0, s22
	v_lshl_add_u64 v[226:227], v[142:143], 0, s[12:13]
	global_load_lds_dwordx4 v[226:227], off
	s_mov_b32 m0, s23
	v_lshl_add_u64 v[222:223], v[142:143], 0, s[14:15]
	global_load_lds_dwordx4 v[222:223], off
	s_waitcnt lgkmcnt(0)
	s_barrier
	s_setprio 1
	v_mfma_f32_16x16x32_bf16 v[124:127], v[170:173], v[148:151], v[124:127]
	v_mfma_f32_16x16x32_bf16 v[120:123], v[170:173], v[162:165], v[120:123]
	v_mfma_f32_16x16x32_bf16 v[116:119], v[178:181], v[148:151], v[116:119]
	v_mfma_f32_16x16x32_bf16 v[112:115], v[178:181], v[162:165], v[112:115]
	v_mfma_f32_16x16x32_bf16 v[108:111], v[186:189], v[148:151], v[108:111]
	v_mfma_f32_16x16x32_bf16 v[104:107], v[186:189], v[162:165], v[104:107]
	v_mfma_f32_16x16x32_bf16 v[100:103], v[194:197], v[148:151], v[100:103]
	v_mfma_f32_16x16x32_bf16 v[96:99], v[194:197], v[162:165], v[96:99]
	v_mfma_f32_16x16x32_bf16 v[124:127], v[174:177], v[152:155], v[124:127]
	v_mfma_f32_16x16x32_bf16 v[120:123], v[174:177], v[166:169], v[120:123]
	v_mfma_f32_16x16x32_bf16 v[116:119], v[182:185], v[152:155], v[116:119]
	v_mfma_f32_16x16x32_bf16 v[112:115], v[182:185], v[166:169], v[112:115]
	v_mfma_f32_16x16x32_bf16 v[108:111], v[190:193], v[152:155], v[108:111]
	v_mfma_f32_16x16x32_bf16 v[104:107], v[190:193], v[166:169], v[104:107]
	v_mfma_f32_16x16x32_bf16 v[100:103], v[198:201], v[152:155], v[100:103]
	v_mfma_f32_16x16x32_bf16 v[96:99], v[198:201], v[166:169], v[96:99]
	v_mfma_f32_16x16x32_bf16 v[92:95], v[170:173], v[202:205], v[92:95]
	v_mfma_f32_16x16x32_bf16 v[88:91], v[170:173], v[210:213], v[88:91]
	v_mfma_f32_16x16x32_bf16 v[84:87], v[178:181], v[202:205], v[84:87]
	v_mfma_f32_16x16x32_bf16 v[80:83], v[178:181], v[210:213], v[80:83]
	v_mfma_f32_16x16x32_bf16 v[76:79], v[186:189], v[202:205], v[76:79]
	v_mfma_f32_16x16x32_bf16 v[72:75], v[186:189], v[210:213], v[72:75]
	v_mfma_f32_16x16x32_bf16 v[68:71], v[194:197], v[202:205], v[68:71]
	v_mfma_f32_16x16x32_bf16 v[64:67], v[194:197], v[210:213], v[64:67]
	v_mfma_f32_16x16x32_bf16 v[92:95], v[174:177], v[206:209], v[92:95]
	v_mfma_f32_16x16x32_bf16 v[88:91], v[174:177], v[214:217], v[88:91]
	v_mfma_f32_16x16x32_bf16 v[84:87], v[182:185], v[206:209], v[84:87]
	v_mfma_f32_16x16x32_bf16 v[80:83], v[182:185], v[214:217], v[80:83]
	v_mfma_f32_16x16x32_bf16 v[76:79], v[190:193], v[206:209], v[76:79]
	v_mfma_f32_16x16x32_bf16 v[72:75], v[190:193], v[214:217], v[72:75]
	v_mfma_f32_16x16x32_bf16 v[68:71], v[198:201], v[206:209], v[68:71]
	v_mfma_f32_16x16x32_bf16 v[64:67], v[198:201], v[214:217], v[64:67]
	s_setprio 0
	s_barrier
	ds_read_b128 v[170:173], v129 offset:49152
	ds_read_b128 v[174:177], v129 offset:50176
	ds_read_b128 v[178:181], v129 offset:51200
	ds_read_b128 v[182:185], v129 offset:52224
	ds_read_b128 v[186:189], v129 offset:53248
	ds_read_b128 v[190:193], v129 offset:54272
	ds_read_b128 v[194:197], v129 offset:55296
	ds_read_b128 v[198:201], v129 offset:56320
	s_mov_b32 m0, s24
	v_lshl_add_u64 v[224:225], v[218:219], 0, s[16:17]
	global_load_lds_dwordx4 v[224:225], off
	s_mov_b32 m0, s25
	v_lshl_add_u64 v[226:227], v[218:219], 0, s[18:19]
	global_load_lds_dwordx4 v[226:227], off
	s_mov_b32 m0, s28
	v_lshl_add_u64 v[222:223], v[142:143], 0, s[16:17]
	global_load_lds_dwordx4 v[222:223], off
	s_mov_b32 m0, s20
	v_lshl_add_u64 v[224:225], v[142:143], 0, s[18:19]
	global_load_lds_dwordx4 v[224:225], off
	s_mov_b32 m0, s21
	s_mov_b64 s[42:43], 0x40180
	v_lshl_add_u64 v[226:227], v[218:219], 0, s[42:43]
	global_load_lds_dwordx4 v[226:227], off
	s_mov_b32 m0, s29
	s_mov_b64 s[42:43], 0x60180
	v_lshl_add_u64 v[222:223], v[218:219], 0, s[42:43]
	global_load_lds_dwordx4 v[222:223], off
	s_waitcnt vmcnt(6)
	s_waitcnt lgkmcnt(0)
	s_barrier
	s_setprio 1
	v_mfma_f32_16x16x32_bf16 v[60:63], v[170:173], v[148:151], v[60:63]
	v_mfma_f32_16x16x32_bf16 v[56:59], v[170:173], v[162:165], v[56:59]
	v_mfma_f32_16x16x32_bf16 v[52:55], v[178:181], v[148:151], v[52:55]
	v_mfma_f32_16x16x32_bf16 v[48:51], v[178:181], v[162:165], v[48:51]
	v_mfma_f32_16x16x32_bf16 v[44:47], v[186:189], v[148:151], v[44:47]
	v_mfma_f32_16x16x32_bf16 v[40:43], v[186:189], v[162:165], v[40:43]
	v_mfma_f32_16x16x32_bf16 v[36:39], v[194:197], v[148:151], v[36:39]
	v_mfma_f32_16x16x32_bf16 v[32:35], v[194:197], v[162:165], v[32:35]
	v_mfma_f32_16x16x32_bf16 v[60:63], v[174:177], v[152:155], v[60:63]
	v_mfma_f32_16x16x32_bf16 v[56:59], v[174:177], v[166:169], v[56:59]
	v_mfma_f32_16x16x32_bf16 v[52:55], v[182:185], v[152:155], v[52:55]
	v_mfma_f32_16x16x32_bf16 v[48:51], v[182:185], v[166:169], v[48:51]
	v_mfma_f32_16x16x32_bf16 v[44:47], v[190:193], v[152:155], v[44:47]
	v_mfma_f32_16x16x32_bf16 v[40:43], v[190:193], v[166:169], v[40:43]
	v_mfma_f32_16x16x32_bf16 v[36:39], v[198:201], v[152:155], v[36:39]
	v_mfma_f32_16x16x32_bf16 v[32:35], v[198:201], v[166:169], v[32:35]
	v_mfma_f32_16x16x32_bf16 v[28:31], v[170:173], v[202:205], v[28:31]
	v_mfma_f32_16x16x32_bf16 v[24:27], v[170:173], v[210:213], v[24:27]
	v_mfma_f32_16x16x32_bf16 v[20:23], v[178:181], v[202:205], v[20:23]
	v_mfma_f32_16x16x32_bf16 v[16:19], v[178:181], v[210:213], v[16:19]
	v_mfma_f32_16x16x32_bf16 v[12:15], v[186:189], v[202:205], v[12:15]
	v_mfma_f32_16x16x32_bf16 v[8:11], v[186:189], v[210:213], v[8:11]
	v_mfma_f32_16x16x32_bf16 v[4:7], v[194:197], v[202:205], v[4:7]
	v_mfma_f32_16x16x32_bf16 v[0:3], v[194:197], v[210:213], v[0:3]
	v_mfma_f32_16x16x32_bf16 v[28:31], v[174:177], v[206:209], v[28:31]
	v_mfma_f32_16x16x32_bf16 v[24:27], v[174:177], v[214:217], v[24:27]
	v_mfma_f32_16x16x32_bf16 v[20:23], v[182:185], v[206:209], v[20:23]
	v_mfma_f32_16x16x32_bf16 v[16:19], v[182:185], v[214:217], v[16:19]
	v_mfma_f32_16x16x32_bf16 v[12:15], v[190:193], v[206:209], v[12:15]
	v_mfma_f32_16x16x32_bf16 v[8:11], v[190:193], v[214:217], v[8:11]
	v_mfma_f32_16x16x32_bf16 v[4:7], v[198:201], v[206:209], v[4:7]
	v_mfma_f32_16x16x32_bf16 v[0:3], v[198:201], v[214:217], v[0:3]
	s_setprio 0
	s_add_i32 s40, s40, 2
	s_add_u32 s2, s2, 0x100
	s_addc_u32 s3, s3, 0
	s_add_u32 s36, s36, 0x100
	s_addc_u32 s37, s37, 0
	s_cmp_ge_i32 s40, s39
	s_barrier
	s_cbranch_scc0 .LBB0_1086

; #define STAGE(P, BASE, br, kt) do { const char* _g = (const char*)((BASE) + (size_t)(br) * K + (size_t)(kt) * G_BK); \
;     _Pragma("unroll") for (int _i = 0; _i < 2; ++_i) { \
;       __builtin_amdgcn_global_load_lds((const unsigned*)(_g + (size_t)_i * 128 * K + sg_off), (unsigned*)((char*)(P) + wid * 1024 + _i * 8192), 16, 0, 0); } } while (0)
; #define LDA(dst, b, h) _Pragma("unroll") for (int m = 0; m < 4; ++m) _Pragma("unroll") for (int k = 0; k < 2; ++k) \
;     dst[m][k] = *reinterpret_cast<const bf16x8*>((const char*)shm + aoff + (((b) * 2 + (h)) * 16384 + m * 2048 + k * 1024))
; #define LDB(dst, b, h) _Pragma("unroll") for (int n = 0; n < 2; ++n) _Pragma("unroll") for (int k = 0; k < 2; ++k) \
;     dst[n][k] = *reinterpret_cast<const bf16x8*>((const char*)shm + boff + (((b) * 2 + (h)) * 16384 + n * 2048 + k * 1024))
; #define MMA(ai, bj, At, Bt_) do { __builtin_amdgcn_s_setprio(1); \
;     _Pragma("unroll") for (int m = 0; m < 4; ++m) _Pragma("unroll") for (int n = 0; n < 2; ++n) _Pragma("unroll") for (int k = 0; k < 2; ++k) \
;       acc[ai][bj][m][n] = mfma16(At[m][k], Bt_[n][k], acc[ai][bj][m][n]); \
;     __builtin_amdgcn_s_setprio(0); } while (0)
; #define WAIT_V(n) asm volatile("s_waitcnt vmcnt(" #n ")" ::: "memory")
; #define WAIT_L(n) asm volatile("s_waitcnt lgkmcnt(" #n ")" ::: "memory")
; #define BAR __builtin_amdgcn_s_barrier()
; #define SCHED __builtin_amdgcn_sched_barrier(0)
; template <class Epi>
; __device__ __forceinline__ void gemm_phase(const bfr* __restrict__ A, int lda, const bfr* __restrict__ Bt, int K,
;                                            int nM, int nN, const Epi& epi, bfr* shm, int wv, int nMfull, int ksplit) {
;     ...
;       LDB(B0, 0, 0); SCHED; LDA(At, 0, 0); STAGE(SA(1, 1), Ak, brow + G_HALF, t + 1);
;       WAIT_L(8); BAR; WAIT_L(0); MMA(0, 0, At, B0); BAR; SCHED;
;       LDB(B1, 0, 1); STAGE(SB(0, 0), Bk, bcol, t + 2);
;       BAR; WAIT_L(0); MMA(0, 1, At, B1); BAR;
;       LDA(At, 0, 1); STAGE(SA(0, 0), Ak, brow, t + 2);
;       BAR; WAIT_L(0); MMA(1, 0, At, B0); BAR; SCHED;
;       STAGE(SB(0, 1), Bk, bcol + G_HALF, t + 2);
;       WAIT_V(6); BAR; MMA(1, 1, At, B1); BAR;
.LBB0_1216:
	ds_read_b128 v[142:145], v169
	ds_read_b128 v[146:149], v169 offset:1024
	ds_read_b128 v[150:153], v169 offset:2048
	ds_read_b128 v[154:157], v169 offset:3072
	ds_read_b128 v[158:161], v168
	ds_read_b128 v[162:165], v168 offset:1024
	ds_read_b128 v[174:177], v168 offset:2048
	ds_read_b128 v[178:181], v168 offset:3072
	ds_read_b128 v[182:185], v168 offset:4096
	ds_read_b128 v[186:189], v168 offset:5120
	ds_read_b128 v[190:193], v168 offset:6144
	ds_read_b128 v[194:197], v168 offset:7168
	ds_read_b128 v[198:201], v169 offset:16384
	ds_read_b128 v[202:205], v169 offset:17408
	ds_read_b128 v[206:209], v169 offset:18432
	ds_read_b128 v[210:213], v169 offset:19456
	v_lshl_add_u64 v[166:167], s[44:45], 0, v[140:141]
	v_lshl_add_u64 v[214:215], s[42:43], 0, v[140:141]
	s_mov_b32 m0, s82
	s_mov_b64 s[46:47], 0x40080
	v_lshl_add_u64 v[218:219], v[166:167], 0, s[46:47]
	global_load_lds_dwordx4 v[218:219], off
	s_mov_b32 m0, s83
	s_mov_b64 s[46:47], 0x60080
	v_lshl_add_u64 v[220:221], v[166:167], 0, s[46:47]
	global_load_lds_dwordx4 v[220:221], off
	s_waitcnt lgkmcnt(0)
	s_barrier
	s_setprio 1
	v_mfma_f32_16x16x32_bf16 v[124:127], v[158:161], v[142:145], v[124:127]
	v_mfma_f32_16x16x32_bf16 v[120:123], v[158:161], v[150:153], v[120:123]
	v_mfma_f32_16x16x32_bf16 v[116:119], v[174:177], v[142:145], v[116:119]
	v_mfma_f32_16x16x32_bf16 v[112:115], v[174:177], v[150:153], v[112:115]
	v_mfma_f32_16x16x32_bf16 v[108:111], v[182:185], v[142:145], v[108:111]
	v_mfma_f32_16x16x32_bf16 v[104:107], v[182:185], v[150:153], v[104:107]
	v_mfma_f32_16x16x32_bf16 v[100:103], v[190:193], v[142:145], v[100:103]
	v_mfma_f32_16x16x32_bf16 v[96:99], v[190:193], v[150:153], v[96:99]
	v_mfma_f32_16x16x32_bf16 v[124:127], v[162:165], v[146:149], v[124:127]
	v_mfma_f32_16x16x32_bf16 v[120:123], v[162:165], v[154:157], v[120:123]
	v_mfma_f32_16x16x32_bf16 v[116:119], v[178:181], v[146:149], v[116:119]
	v_mfma_f32_16x16x32_bf16 v[112:115], v[178:181], v[154:157], v[112:115]
	v_mfma_f32_16x16x32_bf16 v[108:111], v[186:189], v[146:149], v[108:111]
	v_mfma_f32_16x16x32_bf16 v[104:107], v[186:189], v[154:157], v[104:107]
	v_mfma_f32_16x16x32_bf16 v[100:103], v[194:197], v[146:149], v[100:103]
	v_mfma_f32_16x16x32_bf16 v[96:99], v[194:197], v[154:157], v[96:99]
	v_mfma_f32_16x16x32_bf16 v[92:95], v[158:161], v[198:201], v[92:95]
	v_mfma_f32_16x16x32_bf16 v[88:91], v[158:161], v[206:209], v[88:91]
	v_mfma_f32_16x16x32_bf16 v[84:87], v[174:177], v[198:201], v[84:87]
	v_mfma_f32_16x16x32_bf16 v[80:83], v[174:177], v[206:209], v[80:83]
	v_mfma_f32_16x16x32_bf16 v[76:79], v[182:185], v[198:201], v[76:79]
	v_mfma_f32_16x16x32_bf16 v[72:75], v[182:185], v[206:209], v[72:75]
	v_mfma_f32_16x16x32_bf16 v[68:71], v[190:193], v[198:201], v[68:71]
	v_mfma_f32_16x16x32_bf16 v[64:67], v[190:193], v[206:209], v[64:67]
	v_mfma_f32_16x16x32_bf16 v[92:95], v[162:165], v[202:205], v[92:95]
	v_mfma_f32_16x16x32_bf16 v[88:91], v[162:165], v[210:213], v[88:91]
	v_mfma_f32_16x16x32_bf16 v[84:87], v[178:181], v[202:205], v[84:87]
	v_mfma_f32_16x16x32_bf16 v[80:83], v[178:181], v[210:213], v[80:83]
	v_mfma_f32_16x16x32_bf16 v[76:79], v[186:189], v[202:205], v[76:79]
	v_mfma_f32_16x16x32_bf16 v[72:75], v[186:189], v[210:213], v[72:75]
	v_mfma_f32_16x16x32_bf16 v[68:71], v[194:197], v[202:205], v[68:71]
	v_mfma_f32_16x16x32_bf16 v[64:67], v[194:197], v[210:213], v[64:67]
	s_setprio 0
	s_barrier
	ds_read_b128 v[158:161], v168 offset:16384
	ds_read_b128 v[162:165], v168 offset:17408
	ds_read_b128 v[174:177], v168 offset:18432
	ds_read_b128 v[178:181], v168 offset:19456
	ds_read_b128 v[182:185], v168 offset:20480
	ds_read_b128 v[186:189], v168 offset:21504
	ds_read_b128 v[190:193], v168 offset:22528
	ds_read_b128 v[194:197], v168 offset:23552
	s_mov_b32 m0, s84
	v_lshl_add_u64 v[222:223], v[214:215], 0, s[78:79]
	global_load_lds_dwordx4 v[222:223], off
	s_mov_b32 m0, s85
	v_lshl_add_u64 v[218:219], v[214:215], 0, s[80:81]
	global_load_lds_dwordx4 v[218:219], off
	s_mov_b32 m0, s71
	v_lshl_add_u64 v[220:221], v[166:167], 0, s[78:79]
	global_load_lds_dwordx4 v[220:221], off
	s_mov_b32 m0, s87
	v_lshl_add_u64 v[222:223], v[166:167], 0, s[80:81]
	global_load_lds_dwordx4 v[222:223], off
	s_mov_b32 m0, s90
	v_lshl_add_u64 v[218:219], v[214:215], 0, s[88:89]
	global_load_lds_dwordx4 v[218:219], off
	s_mov_b32 m0, s91
	v_lshl_add_u64 v[220:221], v[214:215], 0, s[34:35]
	global_load_lds_dwordx4 v[220:221], off
	s_waitcnt vmcnt(6)
	s_waitcnt lgkmcnt(0)
	s_barrier
	s_setprio 1
	v_mfma_f32_16x16x32_bf16 v[60:63], v[158:161], v[142:145], v[60:63]
	v_mfma_f32_16x16x32_bf16 v[56:59], v[158:161], v[150:153], v[56:59]
	v_mfma_f32_16x16x32_bf16 v[52:55], v[174:177], v[142:145], v[52:55]
	v_mfma_f32_16x16x32_bf16 v[48:51], v[174:177], v[150:153], v[48:51]
	v_mfma_f32_16x16x32_bf16 v[44:47], v[182:185], v[142:145], v[44:47]
	v_mfma_f32_16x16x32_bf16 v[40:43], v[182:185], v[150:153], v[40:43]
	v_mfma_f32_16x16x32_bf16 v[36:39], v[190:193], v[142:145], v[36:39]
	v_mfma_f32_16x16x32_bf16 v[32:35], v[190:193], v[150:153], v[32:35]
	v_mfma_f32_16x16x32_bf16 v[60:63], v[162:165], v[146:149], v[60:63]
	v_mfma_f32_16x16x32_bf16 v[56:59], v[162:165], v[154:157], v[56:59]
	v_mfma_f32_16x16x32_bf16 v[52:55], v[178:181], v[146:149], v[52:55]
	v_mfma_f32_16x16x32_bf16 v[48:51], v[178:181], v[154:157], v[48:51]
	v_mfma_f32_16x16x32_bf16 v[44:47], v[186:189], v[146:149], v[44:47]
	v_mfma_f32_16x16x32_bf16 v[40:43], v[186:189], v[154:157], v[40:43]
	v_mfma_f32_16x16x32_bf16 v[36:39], v[194:197], v[146:149], v[36:39]
	v_mfma_f32_16x16x32_bf16 v[32:35], v[194:197], v[154:157], v[32:35]
	v_mfma_f32_16x16x32_bf16 v[28:31], v[158:161], v[198:201], v[28:31]
	v_mfma_f32_16x16x32_bf16 v[24:27], v[158:161], v[206:209], v[24:27]
	v_mfma_f32_16x16x32_bf16 v[20:23], v[174:177], v[198:201], v[20:23]
	v_mfma_f32_16x16x32_bf16 v[16:19], v[174:177], v[206:209], v[16:19]
	v_mfma_f32_16x16x32_bf16 v[12:15], v[182:185], v[198:201], v[12:15]
	v_mfma_f32_16x16x32_bf16 v[8:11], v[182:185], v[206:209], v[8:11]
	v_mfma_f32_16x16x32_bf16 v[4:7], v[190:193], v[198:201], v[4:7]
	v_mfma_f32_16x16x32_bf16 v[0:3], v[190:193], v[206:209], v[0:3]
	v_mfma_f32_16x16x32_bf16 v[28:31], v[162:165], v[202:205], v[28:31]
	v_mfma_f32_16x16x32_bf16 v[24:27], v[162:165], v[210:213], v[24:27]
	v_mfma_f32_16x16x32_bf16 v[20:23], v[178:181], v[202:205], v[20:23]
	v_mfma_f32_16x16x32_bf16 v[16:19], v[178:181], v[210:213], v[16:19]
	v_mfma_f32_16x16x32_bf16 v[12:15], v[186:189], v[202:205], v[12:15]
	v_mfma_f32_16x16x32_bf16 v[8:11], v[186:189], v[210:213], v[8:11]
	v_mfma_f32_16x16x32_bf16 v[4:7], v[194:197], v[202:205], v[4:7]
	v_mfma_f32_16x16x32_bf16 v[0:3], v[194:197], v[210:213], v[0:3]
	s_setprio 0
	s_barrier
; #define STAGE(P, BASE, br, kt) do { const char* _g = (const char*)((BASE) + (size_t)(br) * K + (size_t)(kt) * G_BK); \
;     _Pragma("unroll") for (int _i = 0; _i < 2; ++_i) { \
;       __builtin_amdgcn_global_load_lds((const unsigned*)(_g + (size_t)_i * 128 * K + sg_off), (unsigned*)((char*)(P) + wid * 1024 + _i * 8192), 16, 0, 0); } } while (0)
; #define LDA(dst, b, h) _Pragma("unroll") for (int m = 0; m < 4; ++m) _Pragma("unroll") for (int k = 0; k < 2; ++k) \
;     dst[m][k] = *reinterpret_cast<const bf16x8*>((const char*)shm + aoff + (((b) * 2 + (h)) * 16384 + m * 2048 + k * 1024))
; #define LDB(dst, b, h) _Pragma("unroll") for (int n = 0; n < 2; ++n) _Pragma("unroll") for (int k = 0; k < 2; ++k) \
;     dst[n][k] = *reinterpret_cast<const bf16x8*>((const char*)shm + boff + (((b) * 2 + (h)) * 16384 + n * 2048 + k * 1024))
; #define MMA(ai, bj, At, Bt_) do { __builtin_amdgcn_s_setprio(1); \
;     _Pragma("unroll") for (int m = 0; m < 4; ++m) _Pragma("unroll") for (int n = 0; n < 2; ++n) _Pragma("unroll") for (int k = 0; k < 2; ++k) \
;       acc[ai][bj][m][n] = mfma16(At[m][k], Bt_[n][k], acc[ai][bj][m][n]); \
;     __builtin_amdgcn_s_setprio(0); } while (0)
; #define WAIT_V(n) asm volatile("s_waitcnt vmcnt(" #n ")" ::: "memory")
; #define WAIT_L(n) asm volatile("s_waitcnt lgkmcnt(" #n ")" ::: "memory")
; #define BAR __builtin_amdgcn_s_barrier()
; #define SCHED __builtin_amdgcn_sched_barrier(0)
; template <class Epi>
; __device__ __forceinline__ void gemm_phase(const bfr* __restrict__ A, int lda, const bfr* __restrict__ Bt, int K,
;                                            int nM, int nN, const Epi& epi, bfr* shm, int wv, int nMfull, int ksplit) {
;     ...
;       LDB(B0, 1, 0); SCHED; LDA(At, 1, 0); STAGE(SA(0, 1), Ak, brow + G_HALF, t + 2);
;       WAIT_L(8); BAR; WAIT_L(0); MMA(0, 0, At, B0); BAR; SCHED;
;       LDB(B1, 1, 1); STAGE(SB(1, 0), Bk, bcol, t + 3);
;       BAR; WAIT_L(0); MMA(0, 1, At, B1); BAR;
;       LDA(At, 1, 1); STAGE(SA(1, 0), Ak, brow, t + 3);
;       BAR; WAIT_L(0); MMA(1, 0, At, B0); BAR; SCHED;
;       STAGE(SB(1, 1), Bk, bcol + G_HALF, t + 3);
;       WAIT_V(6); BAR; MMA(1, 1, At, B1); BAR;
;     }
	ds_read_b128 v[142:145], v169 offset:32768
	ds_read_b128 v[146:149], v169 offset:33792
	ds_read_b128 v[150:153], v169 offset:34816
	ds_read_b128 v[154:157], v169 offset:35840
	ds_read_b128 v[158:161], v168 offset:32768
	ds_read_b128 v[162:165], v168 offset:33792
	ds_read_b128 v[174:177], v168 offset:34816
	ds_read_b128 v[178:181], v168 offset:35840
	ds_read_b128 v[182:185], v168 offset:36864
	ds_read_b128 v[186:189], v168 offset:37888
	ds_read_b128 v[190:193], v168 offset:38912
	ds_read_b128 v[194:197], v168 offset:39936
	ds_read_b128 v[198:201], v169 offset:49152
	ds_read_b128 v[202:205], v169 offset:50176
	ds_read_b128 v[206:209], v169 offset:51200
	ds_read_b128 v[210:213], v169 offset:52224
	s_mov_b32 m0, s92
	v_lshl_add_u64 v[222:223], v[166:167], 0, s[88:89]
	global_load_lds_dwordx4 v[222:223], off
	s_mov_b32 m0, s93
	v_lshl_add_u64 v[218:219], v[166:167], 0, s[34:35]
	global_load_lds_dwordx4 v[218:219], off
	s_waitcnt lgkmcnt(0)
	s_barrier
	s_setprio 1
	v_mfma_f32_16x16x32_bf16 v[124:127], v[158:161], v[142:145], v[124:127]
	v_mfma_f32_16x16x32_bf16 v[120:123], v[158:161], v[150:153], v[120:123]
	v_mfma_f32_16x16x32_bf16 v[116:119], v[174:177], v[142:145], v[116:119]
	v_mfma_f32_16x16x32_bf16 v[112:115], v[174:177], v[150:153], v[112:115]
	v_mfma_f32_16x16x32_bf16 v[108:111], v[182:185], v[142:145], v[108:111]
	v_mfma_f32_16x16x32_bf16 v[104:107], v[182:185], v[150:153], v[104:107]
	v_mfma_f32_16x16x32_bf16 v[100:103], v[190:193], v[142:145], v[100:103]
	v_mfma_f32_16x16x32_bf16 v[96:99], v[190:193], v[150:153], v[96:99]
	v_mfma_f32_16x16x32_bf16 v[124:127], v[162:165], v[146:149], v[124:127]
	v_mfma_f32_16x16x32_bf16 v[120:123], v[162:165], v[154:157], v[120:123]
	v_mfma_f32_16x16x32_bf16 v[116:119], v[178:181], v[146:149], v[116:119]
	v_mfma_f32_16x16x32_bf16 v[112:115], v[178:181], v[154:157], v[112:115]
	v_mfma_f32_16x16x32_bf16 v[108:111], v[186:189], v[146:149], v[108:111]
	v_mfma_f32_16x16x32_bf16 v[104:107], v[186:189], v[154:157], v[104:107]
	v_mfma_f32_16x16x32_bf16 v[100:103], v[194:197], v[146:149], v[100:103]
	v_mfma_f32_16x16x32_bf16 v[96:99], v[194:197], v[154:157], v[96:99]
	v_mfma_f32_16x16x32_bf16 v[92:95], v[158:161], v[198:201], v[92:95]
	v_mfma_f32_16x16x32_bf16 v[88:91], v[158:161], v[206:209], v[88:91]
	v_mfma_f32_16x16x32_bf16 v[84:87], v[174:177], v[198:201], v[84:87]
	v_mfma_f32_16x16x32_bf16 v[80:83], v[174:177], v[206:209], v[80:83]
	v_mfma_f32_16x16x32_bf16 v[76:79], v[182:185], v[198:201], v[76:79]
	v_mfma_f32_16x16x32_bf16 v[72:75], v[182:185], v[206:209], v[72:75]
	v_mfma_f32_16x16x32_bf16 v[68:71], v[190:193], v[198:201], v[68:71]
	v_mfma_f32_16x16x32_bf16 v[64:67], v[190:193], v[206:209], v[64:67]
	v_mfma_f32_16x16x32_bf16 v[92:95], v[162:165], v[202:205], v[92:95]
	v_mfma_f32_16x16x32_bf16 v[88:91], v[162:165], v[210:213], v[88:91]
	v_mfma_f32_16x16x32_bf16 v[84:87], v[178:181], v[202:205], v[84:87]
	v_mfma_f32_16x16x32_bf16 v[80:83], v[178:181], v[210:213], v[80:83]
	v_mfma_f32_16x16x32_bf16 v[76:79], v[186:189], v[202:205], v[76:79]
	v_mfma_f32_16x16x32_bf16 v[72:75], v[186:189], v[210:213], v[72:75]
	v_mfma_f32_16x16x32_bf16 v[68:71], v[194:197], v[202:205], v[68:71]
	v_mfma_f32_16x16x32_bf16 v[64:67], v[194:197], v[210:213], v[64:67]
	s_setprio 0
	s_barrier
	ds_read_b128 v[158:161], v168 offset:49152
	ds_read_b128 v[162:165], v168 offset:50176
	ds_read_b128 v[174:177], v168 offset:51200
	ds_read_b128 v[178:181], v168 offset:52224
	ds_read_b128 v[182:185], v168 offset:53248
	ds_read_b128 v[186:189], v168 offset:54272
	ds_read_b128 v[190:193], v168 offset:55296
	ds_read_b128 v[194:197], v168 offset:56320
	s_mov_b32 m0, s94
	v_lshl_add_u64 v[220:221], v[214:215], 0, s[20:21]
	global_load_lds_dwordx4 v[220:221], off
	s_mov_b32 m0, s95
	v_lshl_add_u64 v[222:223], v[214:215], 0, s[22:23]
	global_load_lds_dwordx4 v[222:223], off
	s_mov_b32 m0, s96
	v_lshl_add_u64 v[218:219], v[166:167], 0, s[20:21]
	global_load_lds_dwordx4 v[218:219], off
	s_mov_b32 m0, s97
	v_lshl_add_u64 v[220:221], v[166:167], 0, s[22:23]
	global_load_lds_dwordx4 v[220:221], off
	s_mov_b32 m0, s0
	s_mov_b64 s[46:47], 0x40180
	v_lshl_add_u64 v[222:223], v[214:215], 0, s[46:47]
	global_load_lds_dwordx4 v[222:223], off
	s_mov_b32 m0, s1
	s_mov_b64 s[46:47], 0x60180
	v_lshl_add_u64 v[218:219], v[214:215], 0, s[46:47]
	global_load_lds_dwordx4 v[218:219], off
	s_waitcnt vmcnt(6)
	s_waitcnt lgkmcnt(0)
	s_barrier
	s_setprio 1
	v_mfma_f32_16x16x32_bf16 v[60:63], v[158:161], v[142:145], v[60:63]
	v_mfma_f32_16x16x32_bf16 v[56:59], v[158:161], v[150:153], v[56:59]
	v_mfma_f32_16x16x32_bf16 v[52:55], v[174:177], v[142:145], v[52:55]
	v_mfma_f32_16x16x32_bf16 v[48:51], v[174:177], v[150:153], v[48:51]
	v_mfma_f32_16x16x32_bf16 v[44:47], v[182:185], v[142:145], v[44:47]
	v_mfma_f32_16x16x32_bf16 v[40:43], v[182:185], v[150:153], v[40:43]
	v_mfma_f32_16x16x32_bf16 v[36:39], v[190:193], v[142:145], v[36:39]
	v_mfma_f32_16x16x32_bf16 v[32:35], v[190:193], v[150:153], v[32:35]
	v_mfma_f32_16x16x32_bf16 v[60:63], v[162:165], v[146:149], v[60:63]
	v_mfma_f32_16x16x32_bf16 v[56:59], v[162:165], v[154:157], v[56:59]
	v_mfma_f32_16x16x32_bf16 v[52:55], v[178:181], v[146:149], v[52:55]
	v_mfma_f32_16x16x32_bf16 v[48:51], v[178:181], v[154:157], v[48:51]
	v_mfma_f32_16x16x32_bf16 v[44:47], v[186:189], v[146:149], v[44:47]
	v_mfma_f32_16x16x32_bf16 v[40:43], v[186:189], v[154:157], v[40:43]
	v_mfma_f32_16x16x32_bf16 v[36:39], v[194:197], v[146:149], v[36:39]
	v_mfma_f32_16x16x32_bf16 v[32:35], v[194:197], v[154:157], v[32:35]
	v_mfma_f32_16x16x32_bf16 v[28:31], v[158:161], v[198:201], v[28:31]
	v_mfma_f32_16x16x32_bf16 v[24:27], v[158:161], v[206:209], v[24:27]
	v_mfma_f32_16x16x32_bf16 v[20:23], v[174:177], v[198:201], v[20:23]
	v_mfma_f32_16x16x32_bf16 v[16:19], v[174:177], v[206:209], v[16:19]
	v_mfma_f32_16x16x32_bf16 v[12:15], v[182:185], v[198:201], v[12:15]
	v_mfma_f32_16x16x32_bf16 v[8:11], v[182:185], v[206:209], v[8:11]
	v_mfma_f32_16x16x32_bf16 v[4:7], v[190:193], v[198:201], v[4:7]
	v_mfma_f32_16x16x32_bf16 v[0:3], v[190:193], v[206:209], v[0:3]
	v_mfma_f32_16x16x32_bf16 v[28:31], v[162:165], v[202:205], v[28:31]
	v_mfma_f32_16x16x32_bf16 v[24:27], v[162:165], v[210:213], v[24:27]
	v_mfma_f32_16x16x32_bf16 v[20:23], v[178:181], v[202:205], v[20:23]
	v_mfma_f32_16x16x32_bf16 v[16:19], v[178:181], v[210:213], v[16:19]
	v_mfma_f32_16x16x32_bf16 v[12:15], v[186:189], v[202:205], v[12:15]
	v_mfma_f32_16x16x32_bf16 v[8:11], v[186:189], v[210:213], v[8:11]
	v_mfma_f32_16x16x32_bf16 v[4:7], v[194:197], v[202:205], v[4:7]
	v_mfma_f32_16x16x32_bf16 v[0:3], v[194:197], v[210:213], v[0:3]
	s_setprio 0
	s_add_i32 s39, s39, 2
	s_add_u32 s42, s42, 0x100
	s_addc_u32 s43, s43, 0
	s_add_u32 s44, s44, 0x100
	s_addc_u32 s45, s45, 0
	s_cmp_ge_i32 s39, s31
	s_barrier
	s_cbranch_scc0 .LBB0_1216

; #define STAGE(P, BASE, br, kt) do { const char* _g = (const char*)((BASE) + (size_t)(br) * K + (size_t)(kt) * G_BK); \
;     _Pragma("unroll") for (int _i = 0; _i < 2; ++_i) { \
;       __builtin_amdgcn_global_load_lds((const unsigned*)(_g + (size_t)_i * 128 * K + sg_off), (unsigned*)((char*)(P) + wid * 1024 + _i * 8192), 16, 0, 0); } } while (0)
; #define LDA(dst, b, h) _Pragma("unroll") for (int m = 0; m < 4; ++m) _Pragma("unroll") for (int k = 0; k < 2; ++k) \
;     dst[m][k] = *reinterpret_cast<const bf16x8*>((const char*)shm + aoff + (((b) * 2 + (h)) * 16384 + m * 2048 + k * 1024))
; #define LDB(dst, b, h) _Pragma("unroll") for (int n = 0; n < 2; ++n) _Pragma("unroll") for (int k = 0; k < 2; ++k) \
;     dst[n][k] = *reinterpret_cast<const bf16x8*>((const char*)shm + boff + (((b) * 2 + (h)) * 16384 + n * 2048 + k * 1024))
; #define MMA(ai, bj, At, Bt_) do { __builtin_amdgcn_s_setprio(1); \
;     _Pragma("unroll") for (int m = 0; m < 4; ++m) _Pragma("unroll") for (int n = 0; n < 2; ++n) _Pragma("unroll") for (int k = 0; k < 2; ++k) \
;       acc[ai][bj][m][n] = mfma16(At[m][k], Bt_[n][k], acc[ai][bj][m][n]); \
;     __builtin_amdgcn_s_setprio(0); } while (0)
; #define WAIT_L(n) asm volatile("s_waitcnt lgkmcnt(" #n ")" ::: "memory")
; #define BAR __builtin_amdgcn_s_barrier()
; #define SCHED __builtin_amdgcn_sched_barrier(0)
; template <class Epi>
; __device__ __forceinline__ void gemm_phase(const bfr* __restrict__ A, int lda, const bfr* __restrict__ Bt, int K,
;                                            int nM, int nN, const Epi& epi, bfr* shm, int wv, int nMfull, int ksplit) {
;     ...
;       LDB(B0, 0, 0); SCHED; LDA(At, 0, 0); STAGE(SA(1, 1), Ak, brow + G_HALF, t + 1);
;       WAIT_L(8); BAR; WAIT_L(0); MMA(0, 0, At, B0); BAR; SCHED;
;       LDB(B1, 0, 1); STAGE(SB(0, 0), Bk, bcol, t + 2);
;       BAR; WAIT_L(0); MMA(0, 1, At, B1); BAR;
;       LDA(At, 0, 1); STAGE(SA(0, 0), Ak, brow, t + 2);
;       BAR; WAIT_L(0); MMA(1, 0, At, B0); BAR; SCHED;
;       STAGE(SB(0, 1), Bk, bcol + G_HALF, t + 2);
.LBB0_1327:
	ds_read_b128 v[136:139], v143
	ds_read_b128 v[148:151], v143 offset:1024
	ds_read_b128 v[152:155], v143 offset:2048
	ds_read_b128 v[156:159], v143 offset:3072
	ds_read_b128 v[160:163], v142
	ds_read_b128 v[164:167], v142 offset:1024
	ds_read_b128 v[168:171], v142 offset:2048
	ds_read_b128 v[172:175], v142 offset:3072
	ds_read_b128 v[176:179], v142 offset:4096
	ds_read_b128 v[180:183], v142 offset:5120
	ds_read_b128 v[184:187], v142 offset:6144
	ds_read_b128 v[188:191], v142 offset:7168
	ds_read_b128 v[192:195], v143 offset:16384
	ds_read_b128 v[196:199], v143 offset:17408
	ds_read_b128 v[200:203], v143 offset:18432
	ds_read_b128 v[204:207], v143 offset:19456
	v_lshl_add_u64 v[140:141], s[52:53], 0, v[134:135]
	v_lshl_add_u64 v[208:209], s[50:51], 0, v[134:135]
	s_mov_b32 m0, s90
	s_mov_b64 s[54:55], 0x40080
	v_lshl_add_u64 v[212:213], v[140:141], 0, s[54:55]
	global_load_lds_dwordx4 v[212:213], off
	s_mov_b32 m0, s91
	s_mov_b64 s[54:55], 0x60080
	v_lshl_add_u64 v[214:215], v[140:141], 0, s[54:55]
	global_load_lds_dwordx4 v[214:215], off
	s_waitcnt lgkmcnt(0)
	s_barrier
	s_setprio 1
	v_mfma_f32_16x16x32_bf16 v[124:127], v[160:163], v[136:139], v[124:127]
	v_mfma_f32_16x16x32_bf16 v[120:123], v[160:163], v[152:155], v[120:123]
	v_mfma_f32_16x16x32_bf16 v[116:119], v[168:171], v[136:139], v[116:119]
	v_mfma_f32_16x16x32_bf16 v[112:115], v[168:171], v[152:155], v[112:115]
	v_mfma_f32_16x16x32_bf16 v[108:111], v[176:179], v[136:139], v[108:111]
	v_mfma_f32_16x16x32_bf16 v[104:107], v[176:179], v[152:155], v[104:107]
	v_mfma_f32_16x16x32_bf16 v[100:103], v[184:187], v[136:139], v[100:103]
	v_mfma_f32_16x16x32_bf16 v[96:99], v[184:187], v[152:155], v[96:99]
	v_mfma_f32_16x16x32_bf16 v[124:127], v[164:167], v[148:151], v[124:127]
	v_mfma_f32_16x16x32_bf16 v[120:123], v[164:167], v[156:159], v[120:123]
	v_mfma_f32_16x16x32_bf16 v[116:119], v[172:175], v[148:151], v[116:119]
	v_mfma_f32_16x16x32_bf16 v[112:115], v[172:175], v[156:159], v[112:115]
	v_mfma_f32_16x16x32_bf16 v[108:111], v[180:183], v[148:151], v[108:111]
	v_mfma_f32_16x16x32_bf16 v[104:107], v[180:183], v[156:159], v[104:107]
	v_mfma_f32_16x16x32_bf16 v[100:103], v[188:191], v[148:151], v[100:103]
	v_mfma_f32_16x16x32_bf16 v[96:99], v[188:191], v[156:159], v[96:99]
	v_mfma_f32_16x16x32_bf16 v[92:95], v[160:163], v[192:195], v[92:95]
	v_mfma_f32_16x16x32_bf16 v[88:91], v[160:163], v[200:203], v[88:91]
	v_mfma_f32_16x16x32_bf16 v[84:87], v[168:171], v[192:195], v[84:87]
	v_mfma_f32_16x16x32_bf16 v[80:83], v[168:171], v[200:203], v[80:83]
	v_mfma_f32_16x16x32_bf16 v[76:79], v[176:179], v[192:195], v[76:79]
	v_mfma_f32_16x16x32_bf16 v[72:75], v[176:179], v[200:203], v[72:75]
	v_mfma_f32_16x16x32_bf16 v[68:71], v[184:187], v[192:195], v[68:71]
	v_mfma_f32_16x16x32_bf16 v[64:67], v[184:187], v[200:203], v[64:67]
	v_mfma_f32_16x16x32_bf16 v[92:95], v[164:167], v[196:199], v[92:95]
	v_mfma_f32_16x16x32_bf16 v[88:91], v[164:167], v[204:207], v[88:91]
	v_mfma_f32_16x16x32_bf16 v[84:87], v[172:175], v[196:199], v[84:87]
	v_mfma_f32_16x16x32_bf16 v[80:83], v[172:175], v[204:207], v[80:83]
	v_mfma_f32_16x16x32_bf16 v[76:79], v[180:183], v[196:199], v[76:79]
	v_mfma_f32_16x16x32_bf16 v[72:75], v[180:183], v[204:207], v[72:75]
	v_mfma_f32_16x16x32_bf16 v[68:71], v[188:191], v[196:199], v[68:71]
	v_mfma_f32_16x16x32_bf16 v[64:67], v[188:191], v[204:207], v[64:67]
	s_setprio 0
	s_barrier
	ds_read_b128 v[160:163], v142 offset:16384
	ds_read_b128 v[164:167], v142 offset:17408
	ds_read_b128 v[168:171], v142 offset:18432
	ds_read_b128 v[172:175], v142 offset:19456
	ds_read_b128 v[176:179], v142 offset:20480
	ds_read_b128 v[180:183], v142 offset:21504
	ds_read_b128 v[184:187], v142 offset:22528
	ds_read_b128 v[188:191], v142 offset:23552
	s_mov_b32 m0, s7
	s_mov_b64 s[54:55], 0x2100100
	v_lshl_add_u64 v[216:217], v[208:209], 0, s[54:55]
	global_load_lds_dwordx4 v[216:217], off
	s_mov_b32 m0, s78
	s_mov_b64 s[54:55], 0x2120100
	v_lshl_add_u64 v[212:213], v[208:209], 0, s[54:55]
	global_load_lds_dwordx4 v[212:213], off
	s_mov_b32 m0, s6
	s_mov_b64 s[54:55], 0x100
	v_lshl_add_u64 v[214:215], v[140:141], 0, s[54:55]
	global_load_lds_dwordx4 v[214:215], off
	s_mov_b32 m0, s79
	v_lshl_add_u64 v[216:217], v[140:141], 0, s[16:17]
	global_load_lds_dwordx4 v[216:217], off
	s_mov_b32 m0, s80
	v_lshl_add_u64 v[212:213], v[208:209], 0, s[18:19]
	global_load_lds_dwordx4 v[212:213], off
	s_mov_b32 m0, s81
	v_lshl_add_u64 v[214:215], v[208:209], 0, s[20:21]
	global_load_lds_dwordx4 v[214:215], off
	s_waitcnt vmcnt(6)
	s_waitcnt lgkmcnt(0)
	s_barrier
; #define STAGE(P, BASE, br, kt) do { const char* _g = (const char*)((BASE) + (size_t)(br) * K + (size_t)(kt) * G_BK); \
;     _Pragma("unroll") for (int _i = 0; _i < 2; ++_i) { \
;       __builtin_amdgcn_global_load_lds((const unsigned*)(_g + (size_t)_i * 128 * K + sg_off), (unsigned*)((char*)(P) + wid * 1024 + _i * 8192), 16, 0, 0); } } while (0)
; #define LDA(dst, b, h) _Pragma("unroll") for (int m = 0; m < 4; ++m) _Pragma("unroll") for (int k = 0; k < 2; ++k) \
;     dst[m][k] = *reinterpret_cast<const bf16x8*>((const char*)shm + aoff + (((b) * 2 + (h)) * 16384 + m * 2048 + k * 1024))
; #define LDB(dst, b, h) _Pragma("unroll") for (int n = 0; n < 2; ++n) _Pragma("unroll") for (int k = 0; k < 2; ++k) \
;     dst[n][k] = *reinterpret_cast<const bf16x8*>((const char*)shm + boff + (((b) * 2 + (h)) * 16384 + n * 2048 + k * 1024))
; #define MMA(ai, bj, At, Bt_) do { __builtin_amdgcn_s_setprio(1); \
;     _Pragma("unroll") for (int m = 0; m < 4; ++m) _Pragma("unroll") for (int n = 0; n < 2; ++n) _Pragma("unroll") for (int k = 0; k < 2; ++k) \
;       acc[ai][bj][m][n] = mfma16(At[m][k], Bt_[n][k], acc[ai][bj][m][n]); \
;     __builtin_amdgcn_s_setprio(0); } while (0)
; #define WAIT_V(n) asm volatile("s_waitcnt vmcnt(" #n ")" ::: "memory")
; #define WAIT_L(n) asm volatile("s_waitcnt lgkmcnt(" #n ")" ::: "memory")
; #define BAR __builtin_amdgcn_s_barrier()
; #define SCHED __builtin_amdgcn_sched_barrier(0)
; template <class Epi>
; __device__ __forceinline__ void gemm_phase(const bfr* __restrict__ A, int lda, const bfr* __restrict__ Bt, int K,
;                                            int nM, int nN, const Epi& epi, bfr* shm, int wv, int nMfull, int ksplit) {
;     ...
;       WAIT_V(6); BAR; MMA(1, 1, At, B1); BAR;
;       LDB(B0, 1, 0); SCHED; LDA(At, 1, 0); STAGE(SA(0, 1), Ak, brow + G_HALF, t + 2);
;       WAIT_L(8); BAR; WAIT_L(0); MMA(0, 0, At, B0); BAR; SCHED;
;       LDB(B1, 1, 1); STAGE(SB(1, 0), Bk, bcol, t + 3);
;       BAR; WAIT_L(0); MMA(0, 1, At, B1); BAR;
;       LDA(At, 1, 1); STAGE(SA(1, 0), Ak, brow, t + 3);
;       BAR; WAIT_L(0); MMA(1, 0, At, B0); BAR; SCHED;
	s_setprio 1
	v_mfma_f32_16x16x32_bf16 v[60:63], v[160:163], v[136:139], v[60:63]
	v_mfma_f32_16x16x32_bf16 v[56:59], v[160:163], v[152:155], v[56:59]
	v_mfma_f32_16x16x32_bf16 v[52:55], v[168:171], v[136:139], v[52:55]
	v_mfma_f32_16x16x32_bf16 v[48:51], v[168:171], v[152:155], v[48:51]
	v_mfma_f32_16x16x32_bf16 v[44:47], v[176:179], v[136:139], v[44:47]
	v_mfma_f32_16x16x32_bf16 v[40:43], v[176:179], v[152:155], v[40:43]
	v_mfma_f32_16x16x32_bf16 v[36:39], v[184:187], v[136:139], v[36:39]
	v_mfma_f32_16x16x32_bf16 v[32:35], v[184:187], v[152:155], v[32:35]
	v_mfma_f32_16x16x32_bf16 v[60:63], v[164:167], v[148:151], v[60:63]
	v_mfma_f32_16x16x32_bf16 v[56:59], v[164:167], v[156:159], v[56:59]
	v_mfma_f32_16x16x32_bf16 v[52:55], v[172:175], v[148:151], v[52:55]
	v_mfma_f32_16x16x32_bf16 v[48:51], v[172:175], v[156:159], v[48:51]
	v_mfma_f32_16x16x32_bf16 v[44:47], v[180:183], v[148:151], v[44:47]
	v_mfma_f32_16x16x32_bf16 v[40:43], v[180:183], v[156:159], v[40:43]
	v_mfma_f32_16x16x32_bf16 v[36:39], v[188:191], v[148:151], v[36:39]
	v_mfma_f32_16x16x32_bf16 v[32:35], v[188:191], v[156:159], v[32:35]
	v_mfma_f32_16x16x32_bf16 v[28:31], v[160:163], v[192:195], v[28:31]
	v_mfma_f32_16x16x32_bf16 v[24:27], v[160:163], v[200:203], v[24:27]
	v_mfma_f32_16x16x32_bf16 v[20:23], v[168:171], v[192:195], v[20:23]
	v_mfma_f32_16x16x32_bf16 v[16:19], v[168:171], v[200:203], v[16:19]
	v_mfma_f32_16x16x32_bf16 v[12:15], v[176:179], v[192:195], v[12:15]
	v_mfma_f32_16x16x32_bf16 v[8:11], v[176:179], v[200:203], v[8:11]
	v_mfma_f32_16x16x32_bf16 v[4:7], v[184:187], v[192:195], v[4:7]
	v_mfma_f32_16x16x32_bf16 v[0:3], v[184:187], v[200:203], v[0:3]
	v_mfma_f32_16x16x32_bf16 v[28:31], v[164:167], v[196:199], v[28:31]
	v_mfma_f32_16x16x32_bf16 v[24:27], v[164:167], v[204:207], v[24:27]
	v_mfma_f32_16x16x32_bf16 v[20:23], v[172:175], v[196:199], v[20:23]
	v_mfma_f32_16x16x32_bf16 v[16:19], v[172:175], v[204:207], v[16:19]
	v_mfma_f32_16x16x32_bf16 v[12:15], v[180:183], v[196:199], v[12:15]
	v_mfma_f32_16x16x32_bf16 v[8:11], v[180:183], v[204:207], v[8:11]
	v_mfma_f32_16x16x32_bf16 v[4:7], v[188:191], v[196:199], v[4:7]
	v_mfma_f32_16x16x32_bf16 v[0:3], v[188:191], v[204:207], v[0:3]
	s_setprio 0
	s_barrier
	ds_read_b128 v[136:139], v143 offset:32768
	ds_read_b128 v[148:151], v143 offset:33792
	ds_read_b128 v[152:155], v143 offset:34816
	ds_read_b128 v[156:159], v143 offset:35840
	ds_read_b128 v[160:163], v142 offset:32768
	ds_read_b128 v[164:167], v142 offset:33792
	ds_read_b128 v[168:171], v142 offset:34816
	ds_read_b128 v[172:175], v142 offset:35840
	ds_read_b128 v[176:179], v142 offset:36864
	ds_read_b128 v[180:183], v142 offset:37888
	ds_read_b128 v[184:187], v142 offset:38912
	ds_read_b128 v[188:191], v142 offset:39936
	ds_read_b128 v[192:195], v143 offset:49152
	ds_read_b128 v[196:199], v143 offset:50176
	ds_read_b128 v[200:203], v143 offset:51200
	ds_read_b128 v[204:207], v143 offset:52224
	s_mov_b32 m0, s82
	v_lshl_add_u64 v[216:217], v[140:141], 0, s[22:23]
	global_load_lds_dwordx4 v[216:217], off
	s_mov_b32 m0, s83
	v_lshl_add_u64 v[212:213], v[140:141], 0, s[24:25]
	global_load_lds_dwordx4 v[212:213], off
	s_waitcnt lgkmcnt(0)
	s_barrier
	s_setprio 1
	v_mfma_f32_16x16x32_bf16 v[124:127], v[160:163], v[136:139], v[124:127]
	v_mfma_f32_16x16x32_bf16 v[120:123], v[160:163], v[152:155], v[120:123]
	v_mfma_f32_16x16x32_bf16 v[116:119], v[168:171], v[136:139], v[116:119]
	v_mfma_f32_16x16x32_bf16 v[112:115], v[168:171], v[152:155], v[112:115]
	v_mfma_f32_16x16x32_bf16 v[108:111], v[176:179], v[136:139], v[108:111]
	v_mfma_f32_16x16x32_bf16 v[104:107], v[176:179], v[152:155], v[104:107]
	v_mfma_f32_16x16x32_bf16 v[100:103], v[184:187], v[136:139], v[100:103]
	v_mfma_f32_16x16x32_bf16 v[96:99], v[184:187], v[152:155], v[96:99]
	v_mfma_f32_16x16x32_bf16 v[124:127], v[164:167], v[148:151], v[124:127]
	v_mfma_f32_16x16x32_bf16 v[120:123], v[164:167], v[156:159], v[120:123]
	v_mfma_f32_16x16x32_bf16 v[116:119], v[172:175], v[148:151], v[116:119]
	v_mfma_f32_16x16x32_bf16 v[112:115], v[172:175], v[156:159], v[112:115]
	v_mfma_f32_16x16x32_bf16 v[108:111], v[180:183], v[148:151], v[108:111]
	v_mfma_f32_16x16x32_bf16 v[104:107], v[180:183], v[156:159], v[104:107]
	v_mfma_f32_16x16x32_bf16 v[100:103], v[188:191], v[148:151], v[100:103]
	v_mfma_f32_16x16x32_bf16 v[96:99], v[188:191], v[156:159], v[96:99]
	v_mfma_f32_16x16x32_bf16 v[92:95], v[160:163], v[192:195], v[92:95]
	v_mfma_f32_16x16x32_bf16 v[88:91], v[160:163], v[200:203], v[88:91]
	v_mfma_f32_16x16x32_bf16 v[84:87], v[168:171], v[192:195], v[84:87]
	v_mfma_f32_16x16x32_bf16 v[80:83], v[168:171], v[200:203], v[80:83]
	v_mfma_f32_16x16x32_bf16 v[76:79], v[176:179], v[192:195], v[76:79]
	v_mfma_f32_16x16x32_bf16 v[72:75], v[176:179], v[200:203], v[72:75]
	v_mfma_f32_16x16x32_bf16 v[68:71], v[184:187], v[192:195], v[68:71]
	v_mfma_f32_16x16x32_bf16 v[64:67], v[184:187], v[200:203], v[64:67]
	v_mfma_f32_16x16x32_bf16 v[92:95], v[164:167], v[196:199], v[92:95]
	v_mfma_f32_16x16x32_bf16 v[88:91], v[164:167], v[204:207], v[88:91]
	v_mfma_f32_16x16x32_bf16 v[84:87], v[172:175], v[196:199], v[84:87]
	v_mfma_f32_16x16x32_bf16 v[80:83], v[172:175], v[204:207], v[80:83]
	v_mfma_f32_16x16x32_bf16 v[76:79], v[180:183], v[196:199], v[76:79]
	v_mfma_f32_16x16x32_bf16 v[72:75], v[180:183], v[204:207], v[72:75]
	v_mfma_f32_16x16x32_bf16 v[68:71], v[188:191], v[196:199], v[68:71]
	v_mfma_f32_16x16x32_bf16 v[64:67], v[188:191], v[204:207], v[64:67]
	s_setprio 0
	s_barrier
; #define STAGE(P, BASE, br, kt) do { const char* _g = (const char*)((BASE) + (size_t)(br) * K + (size_t)(kt) * G_BK); \
;     _Pragma("unroll") for (int _i = 0; _i < 2; ++_i) { \
;       __builtin_amdgcn_global_load_lds((const unsigned*)(_g + (size_t)_i * 128 * K + sg_off), (unsigned*)((char*)(P) + wid * 1024 + _i * 8192), 16, 0, 0); } } while (0)
; #define LDA(dst, b, h) _Pragma("unroll") for (int m = 0; m < 4; ++m) _Pragma("unroll") for (int k = 0; k < 2; ++k) \
;     dst[m][k] = *reinterpret_cast<const bf16x8*>((const char*)shm + aoff + (((b) * 2 + (h)) * 16384 + m * 2048 + k * 1024))
; #define MMA(ai, bj, At, Bt_) do { __builtin_amdgcn_s_setprio(1); \
;     _Pragma("unroll") for (int m = 0; m < 4; ++m) _Pragma("unroll") for (int n = 0; n < 2; ++n) _Pragma("unroll") for (int k = 0; k < 2; ++k) \
;       acc[ai][bj][m][n] = mfma16(At[m][k], Bt_[n][k], acc[ai][bj][m][n]); \
;     __builtin_amdgcn_s_setprio(0); } while (0)
; #define WAIT_V(n) asm volatile("s_waitcnt vmcnt(" #n ")" ::: "memory")
; #define WAIT_L(n) asm volatile("s_waitcnt lgkmcnt(" #n ")" ::: "memory")
; #define BAR __builtin_amdgcn_s_barrier()
; #define SCHED __builtin_amdgcn_sched_barrier(0)
; template <class Epi>
; __device__ __forceinline__ void gemm_phase(const bfr* __restrict__ A, int lda, const bfr* __restrict__ Bt, int K,
;                                            int nM, int nN, const Epi& epi, bfr* shm, int wv, int nMfull, int ksplit) {
;     ...
;       LDA(At, 1, 1); STAGE(SA(1, 0), Ak, brow, t + 3);
;       BAR; WAIT_L(0); MMA(1, 0, At, B0); BAR; SCHED;
;       STAGE(SB(1, 1), Bk, bcol + G_HALF, t + 3);
;       WAIT_V(6); BAR; MMA(1, 1, At, B1); BAR;
;     }
	ds_read_b128 v[160:163], v142 offset:49152
	ds_read_b128 v[164:167], v142 offset:50176
	ds_read_b128 v[168:171], v142 offset:51200
	ds_read_b128 v[172:175], v142 offset:52224
	ds_read_b128 v[176:179], v142 offset:53248
	ds_read_b128 v[180:183], v142 offset:54272
	ds_read_b128 v[184:187], v142 offset:55296
	ds_read_b128 v[188:191], v142 offset:56320
	s_mov_b32 m0, s84
	v_lshl_add_u64 v[214:215], v[208:209], 0, s[26:27]
	global_load_lds_dwordx4 v[214:215], off
	s_mov_b32 m0, s85
	v_lshl_add_u64 v[216:217], v[208:209], 0, s[28:29]
	global_load_lds_dwordx4 v[216:217], off
	s_mov_b32 m0, s86
	v_lshl_add_u64 v[212:213], v[140:141], 0, s[30:31]
	global_load_lds_dwordx4 v[212:213], off
	s_mov_b32 m0, s87
	v_lshl_add_u64 v[214:215], v[140:141], 0, s[34:35]
	global_load_lds_dwordx4 v[214:215], off
	s_mov_b32 m0, s88
	v_lshl_add_u64 v[216:217], v[208:209], 0, s[36:37]
	global_load_lds_dwordx4 v[216:217], off
	s_mov_b32 m0, s89
	v_lshl_add_u64 v[212:213], v[208:209], 0, s[38:39]
	global_load_lds_dwordx4 v[212:213], off
	s_waitcnt vmcnt(6)
	s_waitcnt lgkmcnt(0)
	s_barrier
	s_setprio 1
	v_mfma_f32_16x16x32_bf16 v[60:63], v[160:163], v[136:139], v[60:63]
	v_mfma_f32_16x16x32_bf16 v[56:59], v[160:163], v[152:155], v[56:59]
	v_mfma_f32_16x16x32_bf16 v[52:55], v[168:171], v[136:139], v[52:55]
	v_mfma_f32_16x16x32_bf16 v[48:51], v[168:171], v[152:155], v[48:51]
	v_mfma_f32_16x16x32_bf16 v[44:47], v[176:179], v[136:139], v[44:47]
	v_mfma_f32_16x16x32_bf16 v[40:43], v[176:179], v[152:155], v[40:43]
	v_mfma_f32_16x16x32_bf16 v[36:39], v[184:187], v[136:139], v[36:39]
	v_mfma_f32_16x16x32_bf16 v[32:35], v[184:187], v[152:155], v[32:35]
	v_mfma_f32_16x16x32_bf16 v[60:63], v[164:167], v[148:151], v[60:63]
	v_mfma_f32_16x16x32_bf16 v[56:59], v[164:167], v[156:159], v[56:59]
	v_mfma_f32_16x16x32_bf16 v[52:55], v[172:175], v[148:151], v[52:55]
	v_mfma_f32_16x16x32_bf16 v[48:51], v[172:175], v[156:159], v[48:51]
	v_mfma_f32_16x16x32_bf16 v[44:47], v[180:183], v[148:151], v[44:47]
	v_mfma_f32_16x16x32_bf16 v[40:43], v[180:183], v[156:159], v[40:43]
	v_mfma_f32_16x16x32_bf16 v[36:39], v[188:191], v[148:151], v[36:39]
	v_mfma_f32_16x16x32_bf16 v[32:35], v[188:191], v[156:159], v[32:35]
	v_mfma_f32_16x16x32_bf16 v[28:31], v[160:163], v[192:195], v[28:31]
	v_mfma_f32_16x16x32_bf16 v[24:27], v[160:163], v[200:203], v[24:27]
	v_mfma_f32_16x16x32_bf16 v[20:23], v[168:171], v[192:195], v[20:23]
	v_mfma_f32_16x16x32_bf16 v[16:19], v[168:171], v[200:203], v[16:19]
	v_mfma_f32_16x16x32_bf16 v[12:15], v[176:179], v[192:195], v[12:15]
	v_mfma_f32_16x16x32_bf16 v[8:11], v[176:179], v[200:203], v[8:11]
	v_mfma_f32_16x16x32_bf16 v[4:7], v[184:187], v[192:195], v[4:7]
	v_mfma_f32_16x16x32_bf16 v[0:3], v[184:187], v[200:203], v[0:3]
	v_mfma_f32_16x16x32_bf16 v[28:31], v[164:167], v[196:199], v[28:31]
	v_mfma_f32_16x16x32_bf16 v[24:27], v[164:167], v[204:207], v[24:27]
	v_mfma_f32_16x16x32_bf16 v[20:23], v[172:175], v[196:199], v[20:23]
	v_mfma_f32_16x16x32_bf16 v[16:19], v[172:175], v[204:207], v[16:19]
	v_mfma_f32_16x16x32_bf16 v[12:15], v[180:183], v[196:199], v[12:15]
	v_mfma_f32_16x16x32_bf16 v[8:11], v[180:183], v[204:207], v[8:11]
	v_mfma_f32_16x16x32_bf16 v[4:7], v[188:191], v[196:199], v[4:7]
	v_mfma_f32_16x16x32_bf16 v[0:3], v[188:191], v[204:207], v[0:3]
	s_setprio 0
	s_add_i32 s1, s1, 2
	s_add_u32 s50, s50, 0x100
	s_addc_u32 s51, s51, 0
	s_add_u32 s52, s52, 0x100
	s_addc_u32 s53, s53, 0
	s_cmp_ge_i32 s1, s0
	s_barrier
	s_cbranch_scc0 .LBB0_1327

; #define STAGE(P, BASE, br, kt) do { const char* _g = (const char*)((BASE) + (size_t)(br) * K + (size_t)(kt) * G_BK); \
;     _Pragma("unroll") for (int _i = 0; _i < 2; ++_i) { \
;       __builtin_amdgcn_global_load_lds((const unsigned*)(_g + (size_t)_i * 128 * K + sg_off), (unsigned*)((char*)(P) + wid * 1024 + _i * 8192), 16, 0, 0); } } while (0)
; #define LDA(dst, b, h) _Pragma("unroll") for (int m = 0; m < 4; ++m) _Pragma("unroll") for (int k = 0; k < 2; ++k) \
;     dst[m][k] = *reinterpret_cast<const bf16x8*>((const char*)shm + aoff + (((b) * 2 + (h)) * 16384 + m * 2048 + k * 1024))
; #define LDB(dst, b, h) _Pragma("unroll") for (int n = 0; n < 2; ++n) _Pragma("unroll") for (int k = 0; k < 2; ++k) \
;     dst[n][k] = *reinterpret_cast<const bf16x8*>((const char*)shm + boff + (((b) * 2 + (h)) * 16384 + n * 2048 + k * 1024))
; #define MMA(ai, bj, At, Bt_) do { __builtin_amdgcn_s_setprio(1); \
;     _Pragma("unroll") for (int m = 0; m < 4; ++m) _Pragma("unroll") for (int n = 0; n < 2; ++n) _Pragma("unroll") for (int k = 0; k < 2; ++k) \
;       acc[ai][bj][m][n] = mfma16(At[m][k], Bt_[n][k], acc[ai][bj][m][n]); \
;     __builtin_amdgcn_s_setprio(0); } while (0)
; #define WAIT_V(n) asm volatile("s_waitcnt vmcnt(" #n ")" ::: "memory")
; #define WAIT_L(n) asm volatile("s_waitcnt lgkmcnt(" #n ")" ::: "memory")
; #define BAR __builtin_amdgcn_s_barrier()
; #define SCHED __builtin_amdgcn_sched_barrier(0)
; template <class Epi>
; __device__ __forceinline__ void gemm_phase(const bfr* __restrict__ A, int lda, const bfr* __restrict__ Bt, int K,
;                                            int nM, int nN, const Epi& epi, bfr* shm, int wv, int nMfull, int ksplit) {
;     ...
;       LDB(B0, 0, 0); SCHED; LDA(At, 0, 0); STAGE(SA(1, 1), Ak, brow + G_HALF, t + 1);
;       WAIT_L(8); BAR; WAIT_L(0); MMA(0, 0, At, B0); BAR; SCHED;
;       LDB(B1, 0, 1); STAGE(SB(0, 0), Bk, bcol, t + 2);
;       BAR; WAIT_L(0); MMA(0, 1, At, B1); BAR;
;       LDA(At, 0, 1); STAGE(SA(0, 0), Ak, brow, t + 2);
;       BAR; WAIT_L(0); MMA(1, 0, At, B0); BAR; SCHED;
;       STAGE(SB(0, 1), Bk, bcol + G_HALF, t + 2);
;       WAIT_V(6); BAR; MMA(1, 1, At, B1); BAR;
.LBB0_1368:
	ds_read_b128 v[136:139], v143
	ds_read_b128 v[148:151], v143 offset:1024
	ds_read_b128 v[152:155], v143 offset:2048
	ds_read_b128 v[156:159], v143 offset:3072
	ds_read_b128 v[160:163], v142
	ds_read_b128 v[164:167], v142 offset:1024
	ds_read_b128 v[168:171], v142 offset:2048
	ds_read_b128 v[172:175], v142 offset:3072
	ds_read_b128 v[176:179], v142 offset:4096
	ds_read_b128 v[180:183], v142 offset:5120
	ds_read_b128 v[184:187], v142 offset:6144
	ds_read_b128 v[188:191], v142 offset:7168
	ds_read_b128 v[192:195], v143 offset:16384
	ds_read_b128 v[196:199], v143 offset:17408
	ds_read_b128 v[200:203], v143 offset:18432
	ds_read_b128 v[204:207], v143 offset:19456
	v_lshl_add_u64 v[140:141], s[64:65], 0, v[134:135]
	v_lshl_add_u64 v[208:209], s[60:61], 0, v[134:135]
	s_mov_b32 m0, s47
	v_lshl_add_u64 v[212:213], v[140:141], 0, s[12:13]
	global_load_lds_dwordx4 v[212:213], off
	s_mov_b32 m0, s71
	v_lshl_add_u64 v[214:215], v[140:141], 0, s[14:15]
	global_load_lds_dwordx4 v[214:215], off
	s_waitcnt lgkmcnt(0)
	s_barrier
	s_setprio 1
	v_mfma_f32_16x16x32_bf16 v[124:127], v[160:163], v[136:139], v[124:127]
	v_mfma_f32_16x16x32_bf16 v[120:123], v[160:163], v[152:155], v[120:123]
	v_mfma_f32_16x16x32_bf16 v[116:119], v[168:171], v[136:139], v[116:119]
	v_mfma_f32_16x16x32_bf16 v[112:115], v[168:171], v[152:155], v[112:115]
	v_mfma_f32_16x16x32_bf16 v[108:111], v[176:179], v[136:139], v[108:111]
	v_mfma_f32_16x16x32_bf16 v[104:107], v[176:179], v[152:155], v[104:107]
	v_mfma_f32_16x16x32_bf16 v[100:103], v[184:187], v[136:139], v[100:103]
	v_mfma_f32_16x16x32_bf16 v[96:99], v[184:187], v[152:155], v[96:99]
	v_mfma_f32_16x16x32_bf16 v[124:127], v[164:167], v[148:151], v[124:127]
	v_mfma_f32_16x16x32_bf16 v[120:123], v[164:167], v[156:159], v[120:123]
	v_mfma_f32_16x16x32_bf16 v[116:119], v[172:175], v[148:151], v[116:119]
	v_mfma_f32_16x16x32_bf16 v[112:115], v[172:175], v[156:159], v[112:115]
	v_mfma_f32_16x16x32_bf16 v[108:111], v[180:183], v[148:151], v[108:111]
	v_mfma_f32_16x16x32_bf16 v[104:107], v[180:183], v[156:159], v[104:107]
	v_mfma_f32_16x16x32_bf16 v[100:103], v[188:191], v[148:151], v[100:103]
	v_mfma_f32_16x16x32_bf16 v[96:99], v[188:191], v[156:159], v[96:99]
	v_mfma_f32_16x16x32_bf16 v[92:95], v[160:163], v[192:195], v[92:95]
	v_mfma_f32_16x16x32_bf16 v[88:91], v[160:163], v[200:203], v[88:91]
	v_mfma_f32_16x16x32_bf16 v[84:87], v[168:171], v[192:195], v[84:87]
	v_mfma_f32_16x16x32_bf16 v[80:83], v[168:171], v[200:203], v[80:83]
	v_mfma_f32_16x16x32_bf16 v[76:79], v[176:179], v[192:195], v[76:79]
	v_mfma_f32_16x16x32_bf16 v[72:75], v[176:179], v[200:203], v[72:75]
	v_mfma_f32_16x16x32_bf16 v[68:71], v[184:187], v[192:195], v[68:71]
	v_mfma_f32_16x16x32_bf16 v[64:67], v[184:187], v[200:203], v[64:67]
	v_mfma_f32_16x16x32_bf16 v[92:95], v[164:167], v[196:199], v[92:95]
	v_mfma_f32_16x16x32_bf16 v[88:91], v[164:167], v[204:207], v[88:91]
	v_mfma_f32_16x16x32_bf16 v[84:87], v[172:175], v[196:199], v[84:87]
	v_mfma_f32_16x16x32_bf16 v[80:83], v[172:175], v[204:207], v[80:83]
	v_mfma_f32_16x16x32_bf16 v[76:79], v[180:183], v[196:199], v[76:79]
	v_mfma_f32_16x16x32_bf16 v[72:75], v[180:183], v[204:207], v[72:75]
	v_mfma_f32_16x16x32_bf16 v[68:71], v[188:191], v[196:199], v[68:71]
	v_mfma_f32_16x16x32_bf16 v[64:67], v[188:191], v[204:207], v[64:67]
	s_setprio 0
	s_barrier
	ds_read_b128 v[160:163], v142 offset:16384
	ds_read_b128 v[164:167], v142 offset:17408
	ds_read_b128 v[168:171], v142 offset:18432
	ds_read_b128 v[172:175], v142 offset:19456
	ds_read_b128 v[176:179], v142 offset:20480
	ds_read_b128 v[180:183], v142 offset:21504
	ds_read_b128 v[184:187], v142 offset:22528
	ds_read_b128 v[188:191], v142 offset:23552
	s_mov_b32 m0, s72
	s_mov_b64 s[96:97], 0x1080100
	v_lshl_add_u64 v[216:217], v[208:209], 0, s[96:97]
	global_load_lds_dwordx4 v[216:217], off
	s_mov_b32 m0, s73
	v_lshl_add_u64 v[212:213], v[208:209], 0, s[18:19]
	global_load_lds_dwordx4 v[212:213], off
	s_mov_b32 m0, s48
	v_lshl_add_u64 v[214:215], v[140:141], 0, s[24:25]
	global_load_lds_dwordx4 v[214:215], off
	s_mov_b32 m0, s74
	v_lshl_add_u64 v[216:217], v[140:141], 0, s[26:27]
	global_load_lds_dwordx4 v[216:217], off
	s_mov_b32 m0, s75
	v_lshl_add_u64 v[212:213], v[208:209], 0, s[28:29]
	global_load_lds_dwordx4 v[212:213], off
	s_mov_b32 m0, s62
	v_lshl_add_u64 v[214:215], v[208:209], 0, s[30:31]
	global_load_lds_dwordx4 v[214:215], off
	s_waitcnt vmcnt(6)
	s_waitcnt lgkmcnt(0)
	s_barrier
	s_setprio 1
	v_mfma_f32_16x16x32_bf16 v[60:63], v[160:163], v[136:139], v[60:63]
	v_mfma_f32_16x16x32_bf16 v[56:59], v[160:163], v[152:155], v[56:59]
	v_mfma_f32_16x16x32_bf16 v[52:55], v[168:171], v[136:139], v[52:55]
	v_mfma_f32_16x16x32_bf16 v[48:51], v[168:171], v[152:155], v[48:51]
	v_mfma_f32_16x16x32_bf16 v[44:47], v[176:179], v[136:139], v[44:47]
	v_mfma_f32_16x16x32_bf16 v[40:43], v[176:179], v[152:155], v[40:43]
	v_mfma_f32_16x16x32_bf16 v[36:39], v[184:187], v[136:139], v[36:39]
	v_mfma_f32_16x16x32_bf16 v[32:35], v[184:187], v[152:155], v[32:35]
	v_mfma_f32_16x16x32_bf16 v[60:63], v[164:167], v[148:151], v[60:63]
	v_mfma_f32_16x16x32_bf16 v[56:59], v[164:167], v[156:159], v[56:59]
	v_mfma_f32_16x16x32_bf16 v[52:55], v[172:175], v[148:151], v[52:55]
	v_mfma_f32_16x16x32_bf16 v[48:51], v[172:175], v[156:159], v[48:51]
	v_mfma_f32_16x16x32_bf16 v[44:47], v[180:183], v[148:151], v[44:47]
	v_mfma_f32_16x16x32_bf16 v[40:43], v[180:183], v[156:159], v[40:43]
	v_mfma_f32_16x16x32_bf16 v[36:39], v[188:191], v[148:151], v[36:39]
	v_mfma_f32_16x16x32_bf16 v[32:35], v[188:191], v[156:159], v[32:35]
	v_mfma_f32_16x16x32_bf16 v[28:31], v[160:163], v[192:195], v[28:31]
	v_mfma_f32_16x16x32_bf16 v[24:27], v[160:163], v[200:203], v[24:27]
	v_mfma_f32_16x16x32_bf16 v[20:23], v[168:171], v[192:195], v[20:23]
	v_mfma_f32_16x16x32_bf16 v[16:19], v[168:171], v[200:203], v[16:19]
	v_mfma_f32_16x16x32_bf16 v[12:15], v[176:179], v[192:195], v[12:15]
	v_mfma_f32_16x16x32_bf16 v[8:11], v[176:179], v[200:203], v[8:11]
	v_mfma_f32_16x16x32_bf16 v[4:7], v[184:187], v[192:195], v[4:7]
	v_mfma_f32_16x16x32_bf16 v[0:3], v[184:187], v[200:203], v[0:3]
	v_mfma_f32_16x16x32_bf16 v[28:31], v[164:167], v[196:199], v[28:31]
	v_mfma_f32_16x16x32_bf16 v[24:27], v[164:167], v[204:207], v[24:27]
	v_mfma_f32_16x16x32_bf16 v[20:23], v[172:175], v[196:199], v[20:23]
	v_mfma_f32_16x16x32_bf16 v[16:19], v[172:175], v[204:207], v[16:19]
	v_mfma_f32_16x16x32_bf16 v[12:15], v[180:183], v[196:199], v[12:15]
	v_mfma_f32_16x16x32_bf16 v[8:11], v[180:183], v[204:207], v[8:11]
	v_mfma_f32_16x16x32_bf16 v[4:7], v[188:191], v[196:199], v[4:7]
	v_mfma_f32_16x16x32_bf16 v[0:3], v[188:191], v[204:207], v[0:3]
	s_setprio 0
	s_barrier
; #define STAGE(P, BASE, br, kt) do { const char* _g = (const char*)((BASE) + (size_t)(br) * K + (size_t)(kt) * G_BK); \
;     _Pragma("unroll") for (int _i = 0; _i < 2; ++_i) { \
;       __builtin_amdgcn_global_load_lds((const unsigned*)(_g + (size_t)_i * 128 * K + sg_off), (unsigned*)((char*)(P) + wid * 1024 + _i * 8192), 16, 0, 0); } } while (0)
; #define LDA(dst, b, h) _Pragma("unroll") for (int m = 0; m < 4; ++m) _Pragma("unroll") for (int k = 0; k < 2; ++k) \
;     dst[m][k] = *reinterpret_cast<const bf16x8*>((const char*)shm + aoff + (((b) * 2 + (h)) * 16384 + m * 2048 + k * 1024))
; #define LDB(dst, b, h) _Pragma("unroll") for (int n = 0; n < 2; ++n) _Pragma("unroll") for (int k = 0; k < 2; ++k) \
;     dst[n][k] = *reinterpret_cast<const bf16x8*>((const char*)shm + boff + (((b) * 2 + (h)) * 16384 + n * 2048 + k * 1024))
; #define MMA(ai, bj, At, Bt_) do { __builtin_amdgcn_s_setprio(1); \
;     _Pragma("unroll") for (int m = 0; m < 4; ++m) _Pragma("unroll") for (int n = 0; n < 2; ++n) _Pragma("unroll") for (int k = 0; k < 2; ++k) \
;       acc[ai][bj][m][n] = mfma16(At[m][k], Bt_[n][k], acc[ai][bj][m][n]); \
;     __builtin_amdgcn_s_setprio(0); } while (0)
; #define WAIT_V(n) asm volatile("s_waitcnt vmcnt(" #n ")" ::: "memory")
; #define WAIT_L(n) asm volatile("s_waitcnt lgkmcnt(" #n ")" ::: "memory")
; #define BAR __builtin_amdgcn_s_barrier()
; #define SCHED __builtin_amdgcn_sched_barrier(0)
; template <class Epi>
; __device__ __forceinline__ void gemm_phase(const bfr* __restrict__ A, int lda, const bfr* __restrict__ Bt, int K,
;                                            int nM, int nN, const Epi& epi, bfr* shm, int wv, int nMfull, int ksplit) {
;     ...
;       LDB(B0, 1, 0); SCHED; LDA(At, 1, 0); STAGE(SA(0, 1), Ak, brow + G_HALF, t + 2);
;       WAIT_L(8); BAR; WAIT_L(0); MMA(0, 0, At, B0); BAR; SCHED;
;       LDB(B1, 1, 1); STAGE(SB(1, 0), Bk, bcol, t + 3);
;       BAR; WAIT_L(0); MMA(0, 1, At, B1); BAR;
;       LDA(At, 1, 1); STAGE(SA(1, 0), Ak, brow, t + 3);
;       BAR; WAIT_L(0); MMA(1, 0, At, B0); BAR; SCHED;
;       STAGE(SB(1, 1), Bk, bcol + G_HALF, t + 3);
;       WAIT_V(6); BAR; MMA(1, 1, At, B1); BAR;
;     }
	ds_read_b128 v[136:139], v143 offset:32768
	ds_read_b128 v[148:151], v143 offset:33792
	ds_read_b128 v[152:155], v143 offset:34816
	ds_read_b128 v[156:159], v143 offset:35840
	ds_read_b128 v[160:163], v142 offset:32768
	ds_read_b128 v[164:167], v142 offset:33792
	ds_read_b128 v[168:171], v142 offset:34816
	ds_read_b128 v[172:175], v142 offset:35840
	ds_read_b128 v[176:179], v142 offset:36864
	ds_read_b128 v[180:183], v142 offset:37888
	ds_read_b128 v[184:187], v142 offset:38912
	ds_read_b128 v[188:191], v142 offset:39936
	ds_read_b128 v[192:195], v143 offset:49152
	ds_read_b128 v[196:199], v143 offset:50176
	ds_read_b128 v[200:203], v143 offset:51200
	ds_read_b128 v[204:207], v143 offset:52224
	s_mov_b32 m0, s63
	v_lshl_add_u64 v[216:217], v[140:141], 0, s[8:9]
	global_load_lds_dwordx4 v[216:217], off
	s_mov_b32 m0, s66
	v_lshl_add_u64 v[212:213], v[140:141], 0, s[10:11]
	global_load_lds_dwordx4 v[212:213], off
	s_waitcnt lgkmcnt(0)
	s_barrier
	s_setprio 1
	v_mfma_f32_16x16x32_bf16 v[124:127], v[160:163], v[136:139], v[124:127]
	v_mfma_f32_16x16x32_bf16 v[120:123], v[160:163], v[152:155], v[120:123]
	v_mfma_f32_16x16x32_bf16 v[116:119], v[168:171], v[136:139], v[116:119]
	v_mfma_f32_16x16x32_bf16 v[112:115], v[168:171], v[152:155], v[112:115]
	v_mfma_f32_16x16x32_bf16 v[108:111], v[176:179], v[136:139], v[108:111]
	v_mfma_f32_16x16x32_bf16 v[104:107], v[176:179], v[152:155], v[104:107]
	v_mfma_f32_16x16x32_bf16 v[100:103], v[184:187], v[136:139], v[100:103]
	v_mfma_f32_16x16x32_bf16 v[96:99], v[184:187], v[152:155], v[96:99]
	v_mfma_f32_16x16x32_bf16 v[124:127], v[164:167], v[148:151], v[124:127]
	v_mfma_f32_16x16x32_bf16 v[120:123], v[164:167], v[156:159], v[120:123]
	v_mfma_f32_16x16x32_bf16 v[116:119], v[172:175], v[148:151], v[116:119]
	v_mfma_f32_16x16x32_bf16 v[112:115], v[172:175], v[156:159], v[112:115]
	v_mfma_f32_16x16x32_bf16 v[108:111], v[180:183], v[148:151], v[108:111]
	v_mfma_f32_16x16x32_bf16 v[104:107], v[180:183], v[156:159], v[104:107]
	v_mfma_f32_16x16x32_bf16 v[100:103], v[188:191], v[148:151], v[100:103]
	v_mfma_f32_16x16x32_bf16 v[96:99], v[188:191], v[156:159], v[96:99]
	v_mfma_f32_16x16x32_bf16 v[92:95], v[160:163], v[192:195], v[92:95]
	v_mfma_f32_16x16x32_bf16 v[88:91], v[160:163], v[200:203], v[88:91]
	v_mfma_f32_16x16x32_bf16 v[84:87], v[168:171], v[192:195], v[84:87]
	v_mfma_f32_16x16x32_bf16 v[80:83], v[168:171], v[200:203], v[80:83]
	v_mfma_f32_16x16x32_bf16 v[76:79], v[176:179], v[192:195], v[76:79]
	v_mfma_f32_16x16x32_bf16 v[72:75], v[176:179], v[200:203], v[72:75]
	v_mfma_f32_16x16x32_bf16 v[68:71], v[184:187], v[192:195], v[68:71]
	v_mfma_f32_16x16x32_bf16 v[64:67], v[184:187], v[200:203], v[64:67]
	v_mfma_f32_16x16x32_bf16 v[92:95], v[164:167], v[196:199], v[92:95]
	v_mfma_f32_16x16x32_bf16 v[88:91], v[164:167], v[204:207], v[88:91]
	v_mfma_f32_16x16x32_bf16 v[84:87], v[172:175], v[196:199], v[84:87]
	v_mfma_f32_16x16x32_bf16 v[80:83], v[172:175], v[204:207], v[80:83]
	v_mfma_f32_16x16x32_bf16 v[76:79], v[180:183], v[196:199], v[76:79]
	v_mfma_f32_16x16x32_bf16 v[72:75], v[180:183], v[204:207], v[72:75]
	v_mfma_f32_16x16x32_bf16 v[68:71], v[188:191], v[196:199], v[68:71]
	v_mfma_f32_16x16x32_bf16 v[64:67], v[188:191], v[204:207], v[64:67]
	s_setprio 0
	s_barrier
	ds_read_b128 v[160:163], v142 offset:49152
	ds_read_b128 v[164:167], v142 offset:50176
	ds_read_b128 v[168:171], v142 offset:51200
	ds_read_b128 v[172:175], v142 offset:52224
	ds_read_b128 v[176:179], v142 offset:53248
	ds_read_b128 v[180:183], v142 offset:54272
	ds_read_b128 v[184:187], v142 offset:55296
	ds_read_b128 v[188:191], v142 offset:56320
	s_mov_b32 m0, s67
	v_lshl_add_u64 v[214:215], v[208:209], 0, s[34:35]
	global_load_lds_dwordx4 v[214:215], off
	s_mov_b32 m0, s4
	v_lshl_add_u64 v[216:217], v[208:209], 0, s[36:37]
	global_load_lds_dwordx4 v[216:217], off
	s_mov_b32 m0, s5
	v_lshl_add_u64 v[212:213], v[140:141], 0, s[38:39]
	global_load_lds_dwordx4 v[212:213], off
	s_mov_b32 m0, s6
	v_lshl_add_u64 v[214:215], v[140:141], 0, s[40:41]
	global_load_lds_dwordx4 v[214:215], off
	s_mov_b32 m0, s7
	v_lshl_add_u64 v[216:217], v[208:209], 0, s[42:43]
	global_load_lds_dwordx4 v[216:217], off
	s_mov_b32 m0, s46
	v_lshl_add_u64 v[212:213], v[208:209], 0, s[44:45]
	global_load_lds_dwordx4 v[212:213], off
	s_waitcnt vmcnt(6)
	s_waitcnt lgkmcnt(0)
	s_barrier
	s_setprio 1
	v_mfma_f32_16x16x32_bf16 v[60:63], v[160:163], v[136:139], v[60:63]
	v_mfma_f32_16x16x32_bf16 v[56:59], v[160:163], v[152:155], v[56:59]
	v_mfma_f32_16x16x32_bf16 v[52:55], v[168:171], v[136:139], v[52:55]
	v_mfma_f32_16x16x32_bf16 v[48:51], v[168:171], v[152:155], v[48:51]
	v_mfma_f32_16x16x32_bf16 v[44:47], v[176:179], v[136:139], v[44:47]
	v_mfma_f32_16x16x32_bf16 v[40:43], v[176:179], v[152:155], v[40:43]
	v_mfma_f32_16x16x32_bf16 v[36:39], v[184:187], v[136:139], v[36:39]
	v_mfma_f32_16x16x32_bf16 v[32:35], v[184:187], v[152:155], v[32:35]
	v_mfma_f32_16x16x32_bf16 v[60:63], v[164:167], v[148:151], v[60:63]
	v_mfma_f32_16x16x32_bf16 v[56:59], v[164:167], v[156:159], v[56:59]
	v_mfma_f32_16x16x32_bf16 v[52:55], v[172:175], v[148:151], v[52:55]
	v_mfma_f32_16x16x32_bf16 v[48:51], v[172:175], v[156:159], v[48:51]
	v_mfma_f32_16x16x32_bf16 v[44:47], v[180:183], v[148:151], v[44:47]
	v_mfma_f32_16x16x32_bf16 v[40:43], v[180:183], v[156:159], v[40:43]
	v_mfma_f32_16x16x32_bf16 v[36:39], v[188:191], v[148:151], v[36:39]
	v_mfma_f32_16x16x32_bf16 v[32:35], v[188:191], v[156:159], v[32:35]
	v_mfma_f32_16x16x32_bf16 v[28:31], v[160:163], v[192:195], v[28:31]
	v_mfma_f32_16x16x32_bf16 v[24:27], v[160:163], v[200:203], v[24:27]
	v_mfma_f32_16x16x32_bf16 v[20:23], v[168:171], v[192:195], v[20:23]
	v_mfma_f32_16x16x32_bf16 v[16:19], v[168:171], v[200:203], v[16:19]
	v_mfma_f32_16x16x32_bf16 v[12:15], v[176:179], v[192:195], v[12:15]
	v_mfma_f32_16x16x32_bf16 v[8:11], v[176:179], v[200:203], v[8:11]
	v_mfma_f32_16x16x32_bf16 v[4:7], v[184:187], v[192:195], v[4:7]
	v_mfma_f32_16x16x32_bf16 v[0:3], v[184:187], v[200:203], v[0:3]
	v_mfma_f32_16x16x32_bf16 v[28:31], v[164:167], v[196:199], v[28:31]
	v_mfma_f32_16x16x32_bf16 v[24:27], v[164:167], v[204:207], v[24:27]
	v_mfma_f32_16x16x32_bf16 v[20:23], v[172:175], v[196:199], v[20:23]
	v_mfma_f32_16x16x32_bf16 v[16:19], v[172:175], v[204:207], v[16:19]
	v_mfma_f32_16x16x32_bf16 v[12:15], v[180:183], v[196:199], v[12:15]
	v_mfma_f32_16x16x32_bf16 v[8:11], v[180:183], v[204:207], v[8:11]
	v_mfma_f32_16x16x32_bf16 v[4:7], v[188:191], v[196:199], v[4:7]
	v_mfma_f32_16x16x32_bf16 v[0:3], v[188:191], v[204:207], v[0:3]
	s_setprio 0
	s_add_i32 s59, s59, 2
	s_add_u32 s60, s60, 0x100
	s_addc_u32 s61, s61, 0
	s_add_u32 s64, s64, 0x100
	s_addc_u32 s65, s65, 0
	s_cmp_ge_i32 s59, s57
	s_barrier
	s_cbranch_scc0 .LBB0_1368
